# GEMM K-loops: M0 for each LDS-DMA piece set by s_add_i32 from a wave-base SGPR instead of v_readfirstlane + s_mov (16 VALU->SGPR round trips per iteration removed)
# speedup vs baseline: 1.0075x; 1.0075x over previous
.LBB0_33:
	s_or_b64 exec, exec, s[52:53]
	v_mov_b32_e32 v3, v1
	v_lshl_add_u64 v[12:13], s[0:1], 0, v[2:3]
	s_waitcnt vmcnt(8)
	v_lshl_add_u64 v[16:17], s[14:15], 0, v[2:3]
	v_lshl_add_u64 v[20:21], s[16:17], 0, v[2:3]
	v_lshl_add_u64 v[130:131], s[72:73], 0, v[2:3]
	v_and_b32_e32 v146, 15, v142
	v_bfe_u32 v145, v142, 4, 2
	v_lshlrev_b32_e32 v3, 2, v142
	v_add_u32_e32 v156, 0x18000, v147
	v_lshl_add_u64 v[10:11], s[0:1], 0, v[0:1]
	v_lshl_add_u64 v[14:15], s[14:15], 0, v[0:1]
	v_lshl_add_u64 v[18:19], s[16:17], 0, v[0:1]
	v_lshl_add_u64 v[132:133], s[72:73], 0, v[0:1]
	v_lshlrev_b32_e32 v0, 6, v146
	v_lshlrev_b32_e32 v2, 4, v145
	v_and_b32_e32 v3, 32, v3
	s_mov_b64 s[14:15], 0x80
	v_readfirstlane_b32 s0, v156
	v_add_u32_e32 v157, 0x1a000, v147
	v_bitop3_b32 v22, v2, v3, v0 bitop3:0x36
	v_lshl_add_u64 v[2:3], v[10:11], 0, s[14:15]
	s_mov_b32 m0, s0
	v_readfirstlane_b32 s0, v157
	v_add_u32_e32 v158, 0x8000, v147
	s_waitcnt vmcnt(4)
	s_barrier
	global_load_lds_dwordx4 v[2:3], off
	v_lshl_add_u64 v[2:3], v[12:13], 0, s[14:15]
	s_mov_b32 m0, s0
	v_readfirstlane_b32 s0, v158
	v_add_u32_e32 v159, 0xa000, v147
	global_load_lds_dwordx4 v[2:3], off
	v_lshl_add_u64 v[2:3], v[14:15], 0, s[14:15]
	s_mov_b32 m0, s0
	v_readfirstlane_b32 s0, v159
	v_add_u32_e32 v160, 0x1c000, v147
	global_load_lds_dwordx4 v[2:3], off
	v_lshl_add_u64 v[2:3], v[16:17], 0, s[14:15]
	s_mov_b32 m0, s0
	v_readfirstlane_b32 s0, v160
	v_add_u32_e32 v161, 0x1e000, v147
	global_load_lds_dwordx4 v[2:3], off
	v_lshl_add_u64 v[2:3], v[18:19], 0, s[14:15]
	s_mov_b32 m0, s0
	v_readfirstlane_b32 s0, v161
	global_load_lds_dwordx4 v[2:3], off
	v_lshl_add_u64 v[2:3], v[20:21], 0, s[14:15]
	s_mov_b32 m0, s0
	s_sub_i32 s1, s56, s63
	global_load_lds_dwordx4 v[2:3], off
	s_sub_i32 s1, s1, s62
	v_lshlrev_b32_e32 v0, 15, v4
	s_sext_i32_i16 s1, s1
	v_and_b32_e32 v0, 0xffff0000, v0
	s_lshl_b32 s0, s57, 10
	s_lshl_b32 s1, s1, 8
	v_lshl_add_u32 v0, v5, 12, v0
	v_and_b32_e32 v2, 1, v4
	s_add_i32 s0, s0, s1
	v_lshl_or_b32 v0, v2, 6, v0
	v_lshlrev_b32_e32 v2, 15, v6
	s_ashr_i32 s1, s0, 31
	v_and_b32_e32 v2, 0xffff0000, v2
	s_lshl_b64 s[0:1], s[0:1], 12
	v_lshl_add_u32 v2, v8, 12, v2
	v_and_b32_e32 v3, 1, v6
	s_add_u32 s0, s6, s0
	v_lshl_or_b32 v2, v3, 6, v2
	v_lshl_add_u32 v0, v7, 1, v0
	s_addc_u32 s1, s7, s1
	v_lshl_add_u32 v2, v9, 1, v2
	v_mov_b32_e32 v3, v1
	v_lshl_add_u64 v[134:135], s[0:1], 0, v[0:1]
	v_lshl_add_u64 v[136:137], s[0:1], 0, v[2:3]
	s_add_u32 s0, s88, s12
	v_bfe_u32 v144, v142, 6, 2
	s_waitcnt vmcnt(6)
	s_addc_u32 s1, s89, s13
	v_lshlrev_b32_e32 v23, 13, v143
	v_lshl_or_b32 v24, v144, 12, v212
	v_lshl_add_u64 v[140:141], s[0:1], 0, v[2:3]
	v_mov_b32_e32 v2, 0
	v_lshl_add_u64 v[138:139], s[0:1], 0, v[0:1]
	s_mov_b32 s0, -2
	s_mov_b64 s[12:13], 0
	v_add_u32_e32 v151, v24, v22
	v_add_u32_e32 v0, v23, v22
	v_mov_b32_e32 v3, v2
	v_mov_b32_e32 v4, v2
	v_mov_b32_e32 v5, v2
	v_mov_b32_e32 v6, v2
	v_mov_b32_e32 v7, v2
	v_mov_b32_e32 v8, v2
	v_mov_b32_e32 v9, v2
	v_mov_b32_e32 v10, v2
	v_mov_b32_e32 v11, v2
	v_mov_b32_e32 v12, v2
	v_mov_b32_e32 v13, v2
	v_mov_b32_e32 v14, v2
	v_mov_b32_e32 v15, v2
	v_mov_b32_e32 v16, v2
	v_mov_b32_e32 v17, v2
	v_mov_b32_e32 v18, v2
	v_mov_b32_e32 v19, v2
	v_mov_b32_e32 v20, v2
	v_mov_b32_e32 v21, v2
	v_mov_b32_e32 v22, v2
	v_mov_b32_e32 v23, v2
	v_mov_b32_e32 v24, v2
	v_mov_b32_e32 v25, v2
	v_mov_b32_e32 v26, v2
	v_mov_b32_e32 v27, v2
	v_mov_b32_e32 v28, v2
	v_mov_b32_e32 v29, v2
	v_mov_b32_e32 v30, v2
	v_mov_b32_e32 v31, v2
	v_mov_b32_e32 v32, v2
	v_mov_b32_e32 v33, v2
	v_mov_b32_e32 v34, v2
	v_mov_b32_e32 v35, v2
	v_mov_b32_e32 v36, v2
	v_mov_b32_e32 v37, v2
	v_mov_b32_e32 v38, v2
	v_mov_b32_e32 v39, v2
	v_mov_b32_e32 v40, v2
	v_mov_b32_e32 v41, v2
	v_mov_b32_e32 v42, v2
	v_mov_b32_e32 v43, v2
	v_mov_b32_e32 v44, v2
	v_mov_b32_e32 v45, v2
	v_mov_b32_e32 v46, v2
	v_mov_b32_e32 v47, v2
	v_mov_b32_e32 v48, v2
	v_mov_b32_e32 v49, v2
	v_mov_b32_e32 v50, v2
	v_mov_b32_e32 v51, v2
	v_mov_b32_e32 v52, v2
	v_mov_b32_e32 v53, v2
	v_mov_b32_e32 v54, v2
	v_mov_b32_e32 v55, v2
	v_mov_b32_e32 v56, v2
	v_mov_b32_e32 v57, v2
	v_mov_b32_e32 v58, v2
	v_mov_b32_e32 v59, v2
	v_mov_b32_e32 v60, v2
	v_mov_b32_e32 v61, v2
	v_mov_b32_e32 v62, v2
	v_mov_b32_e32 v63, v2
	v_mov_b32_e32 v64, v2
	v_mov_b32_e32 v65, v2
	v_mov_b32_e32 v70, v2
	v_mov_b32_e32 v71, v2
	v_mov_b32_e32 v72, v2
	v_mov_b32_e32 v73, v2
	v_mov_b32_e32 v86, v2
	v_mov_b32_e32 v87, v2
	v_mov_b32_e32 v88, v2
	v_mov_b32_e32 v89, v2
	v_mov_b32_e32 v90, v2
	v_mov_b32_e32 v91, v2
	v_mov_b32_e32 v92, v2
	v_mov_b32_e32 v93, v2
	v_mov_b32_e32 v94, v2
	v_mov_b32_e32 v95, v2
	v_mov_b32_e32 v96, v2
	v_mov_b32_e32 v97, v2
	v_mov_b32_e32 v98, v2
	v_mov_b32_e32 v99, v2
	v_mov_b32_e32 v100, v2
	v_mov_b32_e32 v101, v2
	v_mov_b32_e32 v102, v2
	v_mov_b32_e32 v103, v2
	v_mov_b32_e32 v104, v2
	v_mov_b32_e32 v105, v2
	v_mov_b32_e32 v106, v2
	v_mov_b32_e32 v107, v2
	v_mov_b32_e32 v108, v2
	v_mov_b32_e32 v109, v2
	v_mov_b32_e32 v110, v2
	v_mov_b32_e32 v111, v2
	v_mov_b32_e32 v112, v2
	v_mov_b32_e32 v113, v2
	v_mov_b32_e32 v114, v2
	v_mov_b32_e32 v115, v2
	v_mov_b32_e32 v116, v2
	v_mov_b32_e32 v117, v2
	v_mov_b32_e32 v118, v2
	v_mov_b32_e32 v119, v2
	v_mov_b32_e32 v120, v2
	v_mov_b32_e32 v121, v2
	v_mov_b32_e32 v122, v2
	v_mov_b32_e32 v123, v2
	v_mov_b32_e32 v124, v2
	v_mov_b32_e32 v125, v2
	v_mov_b32_e32 v126, v2
	v_mov_b32_e32 v127, v2
	v_mov_b32_e32 v128, v2
	v_mov_b32_e32 v129, v2
	v_mov_b32_e32 v66, v2
	v_mov_b32_e32 v67, v2
	v_mov_b32_e32 v68, v2
	v_mov_b32_e32 v69, v2
	v_mov_b32_e32 v74, v2
	v_mov_b32_e32 v75, v2
	v_mov_b32_e32 v76, v2
	v_mov_b32_e32 v77, v2
	v_mov_b32_e32 v78, v2
	v_mov_b32_e32 v79, v2
	v_mov_b32_e32 v80, v2
	v_mov_b32_e32 v81, v2
	v_mov_b32_e32 v82, v2
	v_mov_b32_e32 v83, v2
	v_mov_b32_e32 v84, v2
	v_mov_b32_e32 v85, v2
	s_barrier
	v_readfirstlane_b32 s1, v147
	s_nop 1
.LBB0_34:
	ds_read_b128 v[164:167], v151
	ds_read_b128 v[168:171], v151 offset:1024
	ds_read_b128 v[172:175], v151 offset:2048
	ds_read_b128 v[176:179], v151 offset:3072
	v_add_u32_e32 v162, 0xc000, v147
	v_lshl_add_u64 v[204:205], v[138:139], 0, s[12:13]
	v_lshl_add_u64 v[210:211], v[204:205], 0, s[60:61]
	s_add_i32 m0, s1, 0xc000
	v_add_u32_e32 v163, 0xe000, v147
	ds_read_b128 v[180:183], v0
	ds_read_b128 v[184:187], v0 offset:1024
	ds_read_b128 v[188:191], v0 offset:2048
	ds_read_b128 v[192:195], v0 offset:3072
	ds_read_b128 v[196:199], v0 offset:4096
	ds_read_b128 v[200:203], v0 offset:5120
	ds_read_b128 v[222:225], v0 offset:6144
	ds_read_b128 v[232:235], v0 offset:7168
	global_load_lds_dwordx4 v[210:211], off
	v_lshl_add_u64 v[210:211], v[140:141], 0, s[12:13]
	v_lshl_add_u64 v[216:217], v[210:211], 0, s[60:61]
	s_add_i32 m0, s1, 0xe000
	s_nop 0
	global_load_lds_dwordx4 v[216:217], off
	s_waitcnt lgkmcnt(8)
	s_barrier
	s_waitcnt lgkmcnt(0)
	s_setprio 1
	s_waitcnt lgkmcnt(0)
	v_mfma_f32_16x16x32_bf16 v[126:129], v[164:167], v[180:183], v[126:129]
	v_mfma_f32_16x16x32_bf16 v[122:125], v[172:175], v[180:183], v[122:125]
	v_mfma_f32_16x16x32_bf16 v[118:121], v[164:167], v[188:191], v[118:121]
	v_mfma_f32_16x16x32_bf16 v[114:117], v[172:175], v[188:191], v[114:117]
	v_mfma_f32_16x16x32_bf16 v[110:113], v[164:167], v[196:199], v[110:113]
	v_mfma_f32_16x16x32_bf16 v[106:109], v[172:175], v[196:199], v[106:109]
	v_mfma_f32_16x16x32_bf16 v[102:105], v[164:167], v[222:225], v[102:105]
	v_mfma_f32_16x16x32_bf16 v[98:101], v[172:175], v[222:225], v[98:101]
	v_mfma_f32_16x16x32_bf16 v[126:129], v[168:171], v[184:187], v[126:129]
	v_mfma_f32_16x16x32_bf16 v[122:125], v[176:179], v[184:187], v[122:125]
	v_mfma_f32_16x16x32_bf16 v[118:121], v[168:171], v[192:195], v[118:121]
	v_mfma_f32_16x16x32_bf16 v[114:117], v[176:179], v[192:195], v[114:117]
	v_mfma_f32_16x16x32_bf16 v[110:113], v[168:171], v[200:203], v[110:113]
	v_mfma_f32_16x16x32_bf16 v[106:109], v[176:179], v[200:203], v[106:109]
	v_mfma_f32_16x16x32_bf16 v[102:105], v[168:171], v[232:235], v[102:105]
	v_mfma_f32_16x16x32_bf16 v[98:101], v[176:179], v[232:235], v[98:101]
	s_setprio 0
	s_barrier
	v_lshl_add_u64 v[216:217], v[134:135], 0, s[12:13]
	v_lshl_add_u64 v[218:219], v[216:217], 0, s[74:75]
	s_add_i32 m0, s1, 0x10000
	ds_read_b128 v[236:239], v151 offset:16384
	ds_read_b128 v[240:243], v151 offset:17408
	ds_read_b128 v[244:247], v151 offset:18432
	ds_read_b128 v[248:251], v151 offset:19456
	global_load_lds_dwordx4 v[218:219], off
	v_lshl_add_u64 v[218:219], v[136:137], 0, s[12:13]
	v_lshl_add_u64 v[228:229], v[218:219], 0, s[74:75]
	s_add_i32 m0, s1, 0x12000
	s_nop 0
	global_load_lds_dwordx4 v[228:229], off
	s_barrier
	s_waitcnt lgkmcnt(0)
	s_setprio 1
	s_waitcnt lgkmcnt(0)
	v_mfma_f32_16x16x32_bf16 v[94:97], v[236:239], v[180:183], v[94:97]
	v_mfma_f32_16x16x32_bf16 v[90:93], v[244:247], v[180:183], v[90:93]
	v_mfma_f32_16x16x32_bf16 v[86:89], v[236:239], v[188:191], v[86:89]
	v_mfma_f32_16x16x32_bf16 v[70:73], v[244:247], v[188:191], v[70:73]
	v_mfma_f32_16x16x32_bf16 v[62:65], v[236:239], v[196:199], v[62:65]
	v_mfma_f32_16x16x32_bf16 v[58:61], v[244:247], v[196:199], v[58:61]
	v_mfma_f32_16x16x32_bf16 v[54:57], v[236:239], v[222:225], v[54:57]
	v_mfma_f32_16x16x32_bf16 v[50:53], v[244:247], v[222:225], v[50:53]
	v_mfma_f32_16x16x32_bf16 v[94:97], v[240:243], v[184:187], v[94:97]
	v_mfma_f32_16x16x32_bf16 v[90:93], v[248:251], v[184:187], v[90:93]
	v_mfma_f32_16x16x32_bf16 v[86:89], v[240:243], v[192:195], v[86:89]
	v_mfma_f32_16x16x32_bf16 v[70:73], v[248:251], v[192:195], v[70:73]
	v_mfma_f32_16x16x32_bf16 v[62:65], v[240:243], v[200:203], v[62:65]
	v_mfma_f32_16x16x32_bf16 v[58:61], v[248:251], v[200:203], v[58:61]
	v_mfma_f32_16x16x32_bf16 v[54:57], v[240:243], v[232:235], v[54:57]
	v_mfma_f32_16x16x32_bf16 v[50:53], v[248:251], v[232:235], v[50:53]
	s_setprio 0
	v_lshl_add_u64 v[228:229], v[204:205], 0, s[74:75]
	s_mov_b32 m0, s1
	s_barrier
	ds_read_b128 v[180:183], v0 offset:16384
	ds_read_b128 v[184:187], v0 offset:17408
	ds_read_b128 v[188:191], v0 offset:18432
	ds_read_b128 v[192:195], v0 offset:19456
	ds_read_b128 v[196:199], v0 offset:20480
	ds_read_b128 v[200:203], v0 offset:21504
	ds_read_b128 v[222:225], v0 offset:22528
	ds_read_b128 v[232:235], v0 offset:23552
	global_load_lds_dwordx4 v[228:229], off
	v_lshl_add_u64 v[228:229], v[210:211], 0, s[74:75]
	s_add_i32 m0, s1, 0x2000
	s_nop 0
	global_load_lds_dwordx4 v[228:229], off
	s_barrier
	s_waitcnt lgkmcnt(0)
	s_setprio 1
	s_waitcnt lgkmcnt(0)
	v_mfma_f32_16x16x32_bf16 v[46:49], v[164:167], v[180:183], v[46:49]
	v_mfma_f32_16x16x32_bf16 v[42:45], v[172:175], v[180:183], v[42:45]
	v_mfma_f32_16x16x32_bf16 v[38:41], v[164:167], v[188:191], v[38:41]
	v_mfma_f32_16x16x32_bf16 v[34:37], v[172:175], v[188:191], v[34:37]
	v_mfma_f32_16x16x32_bf16 v[30:33], v[164:167], v[196:199], v[30:33]
	v_mfma_f32_16x16x32_bf16 v[26:29], v[172:175], v[196:199], v[26:29]
	v_mfma_f32_16x16x32_bf16 v[22:25], v[164:167], v[222:225], v[22:25]
	v_mfma_f32_16x16x32_bf16 v[18:21], v[172:175], v[222:225], v[18:21]
	v_mfma_f32_16x16x32_bf16 v[46:49], v[168:171], v[184:187], v[46:49]
	v_mfma_f32_16x16x32_bf16 v[42:45], v[176:179], v[184:187], v[42:45]
	v_mfma_f32_16x16x32_bf16 v[38:41], v[168:171], v[192:195], v[38:41]
	v_mfma_f32_16x16x32_bf16 v[34:37], v[176:179], v[192:195], v[34:37]
	v_mfma_f32_16x16x32_bf16 v[30:33], v[168:171], v[200:203], v[30:33]
	v_mfma_f32_16x16x32_bf16 v[26:29], v[176:179], v[200:203], v[26:29]
	v_mfma_f32_16x16x32_bf16 v[22:25], v[168:171], v[232:235], v[22:25]
	v_mfma_f32_16x16x32_bf16 v[18:21], v[176:179], v[232:235], v[18:21]
	s_setprio 0
	s_barrier
	v_lshl_add_u64 v[164:165], v[216:217], 0, s[18:19]
	s_add_i32 m0, s1, 0x14000
	global_load_lds_dwordx4 v[164:165], off
	v_lshl_add_u64 v[164:165], v[218:219], 0, s[18:19]
	s_add_i32 m0, s1, 0x16000
	s_nop 0
	global_load_lds_dwordx4 v[164:165], off
	s_waitcnt vmcnt(6)
	s_barrier
	s_setprio 1
	v_mfma_f32_16x16x32_bf16 v[14:17], v[236:239], v[180:183], v[14:17]
	v_mfma_f32_16x16x32_bf16 v[10:13], v[244:247], v[180:183], v[10:13]
	v_mfma_f32_16x16x32_bf16 v[6:9], v[236:239], v[188:191], v[6:9]
	v_mfma_f32_16x16x32_bf16 v[2:5], v[244:247], v[188:191], v[2:5]
	v_mfma_f32_16x16x32_bf16 v[66:69], v[236:239], v[196:199], v[66:69]
	v_mfma_f32_16x16x32_bf16 v[74:77], v[244:247], v[196:199], v[74:77]
	v_mfma_f32_16x16x32_bf16 v[78:81], v[236:239], v[222:225], v[78:81]
	v_mfma_f32_16x16x32_bf16 v[82:85], v[244:247], v[222:225], v[82:85]
	v_mfma_f32_16x16x32_bf16 v[14:17], v[240:243], v[184:187], v[14:17]
	v_mfma_f32_16x16x32_bf16 v[10:13], v[248:251], v[184:187], v[10:13]
	v_mfma_f32_16x16x32_bf16 v[6:9], v[240:243], v[192:195], v[6:9]
	v_mfma_f32_16x16x32_bf16 v[2:5], v[248:251], v[192:195], v[2:5]
	v_mfma_f32_16x16x32_bf16 v[66:69], v[240:243], v[200:203], v[66:69]
	v_mfma_f32_16x16x32_bf16 v[74:77], v[248:251], v[200:203], v[74:77]
	v_mfma_f32_16x16x32_bf16 v[78:81], v[240:243], v[232:235], v[78:81]
	v_mfma_f32_16x16x32_bf16 v[82:85], v[248:251], v[232:235], v[82:85]
	s_setprio 0
	s_barrier
	ds_read_b128 v[164:167], v151 offset:32768
	ds_read_b128 v[168:171], v151 offset:33792
	ds_read_b128 v[172:175], v151 offset:34816
	ds_read_b128 v[176:179], v151 offset:35840
	v_lshl_add_u64 v[228:229], v[204:205], 0, s[18:19]
	s_add_i32 m0, s1, 0x4000
	ds_read_b128 v[180:183], v0 offset:32768
	ds_read_b128 v[184:187], v0 offset:33792
	ds_read_b128 v[188:191], v0 offset:34816
	ds_read_b128 v[192:195], v0 offset:35840
	ds_read_b128 v[196:199], v0 offset:36864
	ds_read_b128 v[200:203], v0 offset:37888
	ds_read_b128 v[222:225], v0 offset:38912
	ds_read_b128 v[232:235], v0 offset:39936
	global_load_lds_dwordx4 v[228:229], off
	v_lshl_add_u64 v[228:229], v[210:211], 0, s[18:19]
	s_add_i32 m0, s1, 0x6000
	s_nop 0
	global_load_lds_dwordx4 v[228:229], off
	s_waitcnt lgkmcnt(8)
	s_barrier
	s_waitcnt lgkmcnt(0)
	s_setprio 1
	s_waitcnt lgkmcnt(0)
	v_mfma_f32_16x16x32_bf16 v[126:129], v[164:167], v[180:183], v[126:129]
	v_mfma_f32_16x16x32_bf16 v[122:125], v[172:175], v[180:183], v[122:125]
	v_mfma_f32_16x16x32_bf16 v[118:121], v[164:167], v[188:191], v[118:121]
	v_mfma_f32_16x16x32_bf16 v[114:117], v[172:175], v[188:191], v[114:117]
	v_mfma_f32_16x16x32_bf16 v[110:113], v[164:167], v[196:199], v[110:113]
	v_mfma_f32_16x16x32_bf16 v[106:109], v[172:175], v[196:199], v[106:109]
	v_mfma_f32_16x16x32_bf16 v[102:105], v[164:167], v[222:225], v[102:105]
	v_mfma_f32_16x16x32_bf16 v[98:101], v[172:175], v[222:225], v[98:101]
	v_mfma_f32_16x16x32_bf16 v[126:129], v[168:171], v[184:187], v[126:129]
	v_mfma_f32_16x16x32_bf16 v[122:125], v[176:179], v[184:187], v[122:125]
	v_mfma_f32_16x16x32_bf16 v[118:121], v[168:171], v[192:195], v[118:121]
	v_mfma_f32_16x16x32_bf16 v[114:117], v[176:179], v[192:195], v[114:117]
	v_mfma_f32_16x16x32_bf16 v[110:113], v[168:171], v[200:203], v[110:113]
	v_mfma_f32_16x16x32_bf16 v[106:109], v[176:179], v[200:203], v[106:109]
	v_mfma_f32_16x16x32_bf16 v[102:105], v[168:171], v[232:235], v[102:105]
	v_mfma_f32_16x16x32_bf16 v[98:101], v[176:179], v[232:235], v[98:101]
	s_setprio 0
	s_barrier
	v_lshl_add_u64 v[228:229], v[216:217], 0, s[28:29]
	s_add_i32 m0, s1, 0x18000
	ds_read_b128 v[236:239], v151 offset:49152
	ds_read_b128 v[240:243], v151 offset:50176
	ds_read_b128 v[244:247], v151 offset:51200
	ds_read_b128 v[248:251], v151 offset:52224
	global_load_lds_dwordx4 v[228:229], off
	v_lshl_add_u64 v[228:229], v[218:219], 0, s[28:29]
	s_add_i32 m0, s1, 0x1a000
	s_nop 0
	global_load_lds_dwordx4 v[228:229], off
	s_barrier
	s_waitcnt lgkmcnt(0)
	s_setprio 1
	s_waitcnt lgkmcnt(0)
	v_mfma_f32_16x16x32_bf16 v[94:97], v[236:239], v[180:183], v[94:97]
	v_mfma_f32_16x16x32_bf16 v[90:93], v[244:247], v[180:183], v[90:93]
	v_mfma_f32_16x16x32_bf16 v[86:89], v[236:239], v[188:191], v[86:89]
	v_mfma_f32_16x16x32_bf16 v[70:73], v[244:247], v[188:191], v[70:73]
	v_mfma_f32_16x16x32_bf16 v[62:65], v[236:239], v[196:199], v[62:65]
	v_mfma_f32_16x16x32_bf16 v[58:61], v[244:247], v[196:199], v[58:61]
	v_mfma_f32_16x16x32_bf16 v[54:57], v[236:239], v[222:225], v[54:57]
	v_mfma_f32_16x16x32_bf16 v[50:53], v[244:247], v[222:225], v[50:53]
	v_mfma_f32_16x16x32_bf16 v[94:97], v[240:243], v[184:187], v[94:97]
	v_mfma_f32_16x16x32_bf16 v[90:93], v[248:251], v[184:187], v[90:93]
	v_mfma_f32_16x16x32_bf16 v[86:89], v[240:243], v[192:195], v[86:89]
	v_mfma_f32_16x16x32_bf16 v[70:73], v[248:251], v[192:195], v[70:73]
	v_mfma_f32_16x16x32_bf16 v[62:65], v[240:243], v[200:203], v[62:65]
	v_mfma_f32_16x16x32_bf16 v[58:61], v[248:251], v[200:203], v[58:61]
	v_mfma_f32_16x16x32_bf16 v[54:57], v[240:243], v[232:235], v[54:57]
	v_mfma_f32_16x16x32_bf16 v[50:53], v[248:251], v[232:235], v[50:53]
	s_setprio 0
	v_lshl_add_u64 v[204:205], v[204:205], 0, s[28:29]
	s_add_i32 m0, s1, 0x8000
	s_barrier
	ds_read_b128 v[180:183], v0 offset:49152
	ds_read_b128 v[184:187], v0 offset:50176
	ds_read_b128 v[188:191], v0 offset:51200
	ds_read_b128 v[192:195], v0 offset:52224
	ds_read_b128 v[196:199], v0 offset:53248
	ds_read_b128 v[200:203], v0 offset:54272
	ds_read_b128 v[222:225], v0 offset:55296
	ds_read_b128 v[232:235], v0 offset:56320
	global_load_lds_dwordx4 v[204:205], off
	v_lshl_add_u64 v[204:205], v[210:211], 0, s[28:29]
	s_add_i32 m0, s1, 0xa000
	s_nop 0
	global_load_lds_dwordx4 v[204:205], off
	s_barrier
	s_waitcnt lgkmcnt(0)
	s_setprio 1
	s_waitcnt lgkmcnt(0)
	v_mfma_f32_16x16x32_bf16 v[46:49], v[164:167], v[180:183], v[46:49]
	v_mfma_f32_16x16x32_bf16 v[42:45], v[172:175], v[180:183], v[42:45]
	v_mfma_f32_16x16x32_bf16 v[38:41], v[164:167], v[188:191], v[38:41]
	v_mfma_f32_16x16x32_bf16 v[34:37], v[172:175], v[188:191], v[34:37]
	v_mfma_f32_16x16x32_bf16 v[30:33], v[164:167], v[196:199], v[30:33]
	v_mfma_f32_16x16x32_bf16 v[26:29], v[172:175], v[196:199], v[26:29]
	v_mfma_f32_16x16x32_bf16 v[22:25], v[164:167], v[222:225], v[22:25]
	v_mfma_f32_16x16x32_bf16 v[18:21], v[172:175], v[222:225], v[18:21]
	v_mfma_f32_16x16x32_bf16 v[46:49], v[168:171], v[184:187], v[46:49]
	v_mfma_f32_16x16x32_bf16 v[42:45], v[176:179], v[184:187], v[42:45]
	v_mfma_f32_16x16x32_bf16 v[38:41], v[168:171], v[192:195], v[38:41]
	v_mfma_f32_16x16x32_bf16 v[34:37], v[176:179], v[192:195], v[34:37]
	v_mfma_f32_16x16x32_bf16 v[30:33], v[168:171], v[200:203], v[30:33]
	v_mfma_f32_16x16x32_bf16 v[26:29], v[176:179], v[200:203], v[26:29]
	v_mfma_f32_16x16x32_bf16 v[22:25], v[168:171], v[232:235], v[22:25]
	v_mfma_f32_16x16x32_bf16 v[18:21], v[176:179], v[232:235], v[18:21]
	s_setprio 0
	s_barrier
	v_lshl_add_u64 v[164:165], v[216:217], 0, s[30:31]
	s_add_i32 m0, s1, 0x1c000
	global_load_lds_dwordx4 v[164:165], off
	v_lshl_add_u64 v[164:165], v[218:219], 0, s[30:31]
	s_add_i32 m0, s1, 0x1e000
	s_nop 0
	global_load_lds_dwordx4 v[164:165], off
	s_waitcnt vmcnt(6)
	s_barrier
	s_setprio 1
	v_mfma_f32_16x16x32_bf16 v[14:17], v[236:239], v[180:183], v[14:17]
	v_mfma_f32_16x16x32_bf16 v[10:13], v[244:247], v[180:183], v[10:13]
	v_mfma_f32_16x16x32_bf16 v[6:9], v[236:239], v[188:191], v[6:9]
	v_mfma_f32_16x16x32_bf16 v[2:5], v[244:247], v[188:191], v[2:5]
	v_mfma_f32_16x16x32_bf16 v[66:69], v[236:239], v[196:199], v[66:69]
	v_mfma_f32_16x16x32_bf16 v[74:77], v[244:247], v[196:199], v[74:77]
	v_mfma_f32_16x16x32_bf16 v[78:81], v[236:239], v[222:225], v[78:81]
	v_mfma_f32_16x16x32_bf16 v[82:85], v[244:247], v[222:225], v[82:85]
	v_mfma_f32_16x16x32_bf16 v[14:17], v[240:243], v[184:187], v[14:17]
	v_mfma_f32_16x16x32_bf16 v[10:13], v[248:251], v[184:187], v[10:13]
	v_mfma_f32_16x16x32_bf16 v[6:9], v[240:243], v[192:195], v[6:9]
	v_mfma_f32_16x16x32_bf16 v[2:5], v[248:251], v[192:195], v[2:5]
	v_mfma_f32_16x16x32_bf16 v[66:69], v[240:243], v[200:203], v[66:69]
	v_mfma_f32_16x16x32_bf16 v[74:77], v[248:251], v[200:203], v[74:77]
	v_mfma_f32_16x16x32_bf16 v[78:81], v[240:243], v[232:235], v[78:81]
	v_mfma_f32_16x16x32_bf16 v[82:85], v[248:251], v[232:235], v[82:85]
	s_setprio 0
	s_add_i32 s0, s0, 2
	s_add_u32 s12, s12, 0x100
	s_addc_u32 s13, s13, 0
	s_cmp_lt_u32 s0, 28
	s_barrier
	s_cbranch_scc1 .LBB0_34
	s_add_i32 s1, s1, 0x1e000
	s_mov_b64 s[12:13], 0xf80
	v_readfirstlane_b32 s0, v162
	v_lshl_add_u64 v[132:133], v[132:133], 0, s[12:13]
	s_mov_b32 m0, s0
	v_readfirstlane_b32 s0, v163
	ds_read_b128 v[134:137], v151
	ds_read_b128 v[138:141], v151 offset:1024
	ds_read_b128 v[152:155], v151 offset:2048
	ds_read_b128 v[156:159], v151 offset:3072
	ds_read_b128 v[164:167], v0
	ds_read_b128 v[168:171], v0 offset:1024
	ds_read_b128 v[172:175], v0 offset:2048
	ds_read_b128 v[176:179], v0 offset:3072
	ds_read_b128 v[180:183], v0 offset:4096
	ds_read_b128 v[184:187], v0 offset:5120
	ds_read_b128 v[188:191], v0 offset:6144
	ds_read_b128 v[192:195], v0 offset:7168
	global_load_lds_dwordx4 v[132:133], off
	v_lshl_add_u64 v[130:131], v[130:131], 0, s[12:13]
	s_mov_b32 m0, s0
	s_nop 0
	global_load_lds_dwordx4 v[130:131], off
	s_barrier
	s_waitcnt lgkmcnt(0)
	s_setprio 1
	s_waitcnt lgkmcnt(0)
	v_mfma_f32_16x16x32_bf16 v[122:125], v[152:155], v[164:167], v[122:125]
	v_mfma_f32_16x16x32_bf16 v[118:121], v[134:137], v[172:175], v[118:121]
	v_mfma_f32_16x16x32_bf16 v[114:117], v[152:155], v[172:175], v[114:117]
	v_mfma_f32_16x16x32_bf16 v[102:105], v[134:137], v[188:191], v[102:105]
	v_mfma_f32_16x16x32_bf16 v[98:101], v[152:155], v[188:191], v[98:101]
	v_mfma_f32_16x16x32_bf16 v[126:129], v[134:137], v[164:167], v[126:129]
	v_mfma_f32_16x16x32_bf16 v[122:125], v[156:159], v[168:171], v[122:125]
	v_mfma_f32_16x16x32_bf16 v[118:121], v[138:141], v[176:179], v[118:121]
	v_mfma_f32_16x16x32_bf16 v[114:117], v[156:159], v[176:179], v[114:117]
	v_mfma_f32_16x16x32_bf16 v[110:113], v[134:137], v[180:183], v[110:113]
	v_mfma_f32_16x16x32_bf16 v[106:109], v[152:155], v[180:183], v[106:109]
	v_mfma_f32_16x16x32_bf16 v[102:105], v[138:141], v[192:195], v[102:105]
	v_mfma_f32_16x16x32_bf16 v[98:101], v[156:159], v[192:195], v[98:101]
	v_mfma_f32_16x16x32_bf16 v[126:129], v[138:141], v[168:171], v[126:129]
	v_mfma_f32_16x16x32_bf16 v[130:133], v[138:141], v[184:187], v[110:113]
	v_mfma_f32_16x16x32_bf16 v[160:163], v[156:159], v[184:187], v[106:109]
	s_setprio 0
	s_barrier
	ds_read_b128 v[106:109], v151 offset:16384
	ds_read_b128 v[110:113], v151 offset:17408
	ds_read_b128 v[196:199], v151 offset:18432
	ds_read_b128 v[200:203], v151 offset:19456
	s_barrier
	s_waitcnt lgkmcnt(0)
	s_setprio 1
	s_waitcnt lgkmcnt(3)
	v_mfma_f32_16x16x32_bf16 v[86:89], v[106:109], v[172:175], v[86:89]
	s_waitcnt lgkmcnt(1)
	v_mfma_f32_16x16x32_bf16 v[70:73], v[196:199], v[172:175], v[70:73]
	v_mfma_f32_16x16x32_bf16 v[62:65], v[106:109], v[180:183], v[62:65]
	v_mfma_f32_16x16x32_bf16 v[58:61], v[196:199], v[180:183], v[58:61]
	v_mfma_f32_16x16x32_bf16 v[54:57], v[106:109], v[188:191], v[54:57]
	v_mfma_f32_16x16x32_bf16 v[50:53], v[196:199], v[188:191], v[50:53]
	v_mfma_f32_16x16x32_bf16 v[94:97], v[106:109], v[164:167], v[94:97]
	v_mfma_f32_16x16x32_bf16 v[90:93], v[196:199], v[164:167], v[90:93]
	v_mfma_f32_16x16x32_bf16 v[86:89], v[110:113], v[176:179], v[86:89]
	s_waitcnt lgkmcnt(0)
	v_mfma_f32_16x16x32_bf16 v[70:73], v[200:203], v[176:179], v[70:73]
	v_mfma_f32_16x16x32_bf16 v[62:65], v[110:113], v[184:187], v[62:65]
	v_mfma_f32_16x16x32_bf16 v[58:61], v[200:203], v[184:187], v[58:61]
	v_mfma_f32_16x16x32_bf16 v[54:57], v[110:113], v[192:195], v[54:57]
	v_mfma_f32_16x16x32_bf16 v[50:53], v[200:203], v[192:195], v[50:53]
	v_mfma_f32_16x16x32_bf16 v[222:225], v[110:113], v[168:171], v[94:97]
	v_mfma_f32_16x16x32_bf16 v[164:167], v[200:203], v[168:171], v[90:93]
	s_setprio 0
	s_barrier
	s_nop 0
	ds_read_b128 v[90:93], v0 offset:16384
	ds_read_b128 v[94:97], v0 offset:17408
	ds_read_b128 v[168:171], v0 offset:18432
	ds_read_b128 v[172:175], v0 offset:19456
	ds_read_b128 v[176:179], v0 offset:20480
	ds_read_b128 v[180:183], v0 offset:21504
	ds_read_b128 v[184:187], v0 offset:22528
	ds_read_b128 v[188:191], v0 offset:23552
	s_waitcnt vmcnt(4)
	s_barrier
	s_waitcnt lgkmcnt(0)
	s_setprio 1
	s_waitcnt lgkmcnt(7)
	v_mfma_f32_16x16x32_bf16 v[46:49], v[134:137], v[90:93], v[46:49]
	v_mfma_f32_16x16x32_bf16 v[42:45], v[152:155], v[90:93], v[42:45]
	s_waitcnt lgkmcnt(5)
	v_mfma_f32_16x16x32_bf16 v[38:41], v[134:137], v[168:171], v[38:41]
	v_mfma_f32_16x16x32_bf16 v[34:37], v[152:155], v[168:171], v[34:37]
	s_waitcnt lgkmcnt(3)
	v_mfma_f32_16x16x32_bf16 v[30:33], v[134:137], v[176:179], v[30:33]
	v_mfma_f32_16x16x32_bf16 v[26:29], v[152:155], v[176:179], v[26:29]
	s_waitcnt lgkmcnt(1)
	v_mfma_f32_16x16x32_bf16 v[22:25], v[134:137], v[184:187], v[22:25]
	v_mfma_f32_16x16x32_bf16 v[18:21], v[152:155], v[184:187], v[18:21]
	v_mfma_f32_16x16x32_bf16 v[46:49], v[138:141], v[94:97], v[46:49]
	v_mfma_f32_16x16x32_bf16 v[42:45], v[156:159], v[94:97], v[42:45]
	v_mfma_f32_16x16x32_bf16 v[38:41], v[138:141], v[172:175], v[38:41]
	v_mfma_f32_16x16x32_bf16 v[34:37], v[156:159], v[172:175], v[34:37]
	v_mfma_f32_16x16x32_bf16 v[30:33], v[138:141], v[180:183], v[30:33]
	v_mfma_f32_16x16x32_bf16 v[26:29], v[156:159], v[180:183], v[26:29]
	s_waitcnt lgkmcnt(0)
	v_mfma_f32_16x16x32_bf16 v[22:25], v[138:141], v[188:191], v[22:25]
	v_mfma_f32_16x16x32_bf16 v[18:21], v[156:159], v[188:191], v[18:21]
	s_setprio 0
	s_setprio 1
	v_mfma_f32_16x16x32_bf16 v[10:13], v[196:199], v[90:93], v[10:13]
	v_mfma_f32_16x16x32_bf16 v[152:155], v[200:203], v[94:97], v[10:13]
	v_mfma_f32_16x16x32_bf16 v[10:13], v[106:109], v[176:179], v[66:69]
	v_mfma_f32_16x16x32_bf16 v[156:159], v[110:113], v[180:183], v[10:13]
	v_mfma_f32_16x16x32_bf16 v[10:13], v[196:199], v[176:179], v[74:77]
	v_mfma_f32_16x16x32_bf16 v[6:9], v[106:109], v[168:171], v[6:9]
	v_mfma_f32_16x16x32_bf16 v[2:5], v[196:199], v[168:171], v[2:5]
	v_mfma_f32_16x16x32_bf16 v[168:171], v[200:203], v[180:183], v[10:13]
	v_mfma_f32_16x16x32_bf16 v[10:13], v[106:109], v[184:187], v[78:81]
	v_mfma_f32_16x16x32_bf16 v[14:17], v[106:109], v[90:93], v[14:17]
	v_mfma_f32_16x16x32_bf16 v[6:9], v[110:113], v[172:175], v[6:9]
	v_mfma_f32_16x16x32_bf16 v[2:5], v[200:203], v[172:175], v[2:5]
	v_mfma_f32_16x16x32_bf16 v[172:175], v[110:113], v[188:191], v[10:13]
	v_mfma_f32_16x16x32_bf16 v[10:13], v[196:199], v[184:187], v[82:85]
	v_mfma_f32_16x16x32_bf16 v[134:137], v[110:113], v[94:97], v[14:17]
	v_mfma_f32_16x16x32_bf16 v[176:179], v[200:203], v[188:191], v[10:13]
	s_setprio 0
	s_barrier
	s_nop 3
	ds_read_b128 v[10:13], v151 offset:32768
	ds_read_b128 v[14:17], v151 offset:33792
	ds_read_b128 v[180:183], v151 offset:34816
	ds_read_b128 v[184:187], v151 offset:35840
	ds_read_b128 v[66:69], v0 offset:32768
	ds_read_b128 v[82:85], v0 offset:33792
	ds_read_b128 v[188:191], v0 offset:34816
	ds_read_b128 v[192:195], v0 offset:35840
	ds_read_b128 v[196:199], v0 offset:36864
	ds_read_b128 v[200:203], v0 offset:37888
	ds_read_b128 v[232:235], v0 offset:38912
	ds_read_b128 v[236:239], v0 offset:39936
	s_waitcnt vmcnt(2)
	s_barrier
	s_waitcnt lgkmcnt(0)
	s_setprio 1
	s_waitcnt lgkmcnt(7)
	v_mfma_f32_16x16x32_bf16 v[74:77], v[10:13], v[66:69], v[126:129]
	s_waitcnt lgkmcnt(6)
	v_mfma_f32_16x16x32_bf16 v[138:141], v[14:17], v[82:85], v[74:77]
	v_mfma_f32_16x16x32_bf16 v[74:77], v[180:183], v[66:69], v[122:125]
	v_mfma_f32_16x16x32_bf16 v[122:125], v[184:187], v[82:85], v[74:77]
	s_waitcnt lgkmcnt(5)
	v_mfma_f32_16x16x32_bf16 v[74:77], v[10:13], v[188:191], v[118:121]
	s_waitcnt lgkmcnt(4)
	v_mfma_f32_16x16x32_bf16 v[110:113], v[14:17], v[192:195], v[74:77]
	v_mfma_f32_16x16x32_bf16 v[74:77], v[180:183], v[188:191], v[114:117]
	v_mfma_f32_16x16x32_bf16 v[106:109], v[184:187], v[192:195], v[74:77]
	s_waitcnt lgkmcnt(3)
	v_mfma_f32_16x16x32_bf16 v[74:77], v[10:13], v[196:199], v[130:133]
	s_waitcnt lgkmcnt(2)
	v_mfma_f32_16x16x32_bf16 v[94:97], v[14:17], v[200:203], v[74:77]
	v_mfma_f32_16x16x32_bf16 v[74:77], v[180:183], v[196:199], v[160:163]
	v_mfma_f32_16x16x32_bf16 v[90:93], v[184:187], v[200:203], v[74:77]
	s_waitcnt lgkmcnt(1)
	v_mfma_f32_16x16x32_bf16 v[74:77], v[10:13], v[232:235], v[102:105]
	s_waitcnt lgkmcnt(0)
	v_mfma_f32_16x16x32_bf16 v[78:81], v[14:17], v[236:239], v[74:77]
	v_mfma_f32_16x16x32_bf16 v[74:77], v[180:183], v[232:235], v[98:101]
	v_mfma_f32_16x16x32_bf16 v[74:77], v[184:187], v[236:239], v[74:77]
	s_setprio 0
	s_barrier
	ds_read_b128 v[126:129], v151 offset:49152
	ds_read_b128 v[130:133], v151 offset:50176
	ds_read_b128 v[160:163], v151 offset:51200
	ds_read_b128 v[148:151], v151 offset:52224
	s_waitcnt vmcnt(0)
	s_barrier
	s_waitcnt lgkmcnt(0)
	s_setprio 1
	s_waitcnt lgkmcnt(3)
	v_mfma_f32_16x16x32_bf16 v[98:101], v[126:129], v[66:69], v[222:225]
	s_waitcnt lgkmcnt(1)
	v_mfma_f32_16x16x32_bf16 v[66:69], v[160:163], v[66:69], v[164:167]
	s_waitcnt lgkmcnt(0)
	v_mfma_f32_16x16x32_bf16 v[114:117], v[148:151], v[82:85], v[66:69]
	v_mfma_f32_16x16x32_bf16 v[66:69], v[126:129], v[188:191], v[86:89]
	v_mfma_f32_16x16x32_bf16 v[102:105], v[130:133], v[192:195], v[66:69]
	v_mfma_f32_16x16x32_bf16 v[66:69], v[160:163], v[188:191], v[70:73]
	v_mfma_f32_16x16x32_bf16 v[62:65], v[126:129], v[196:199], v[62:65]
	v_mfma_f32_16x16x32_bf16 v[58:61], v[160:163], v[196:199], v[58:61]
	v_mfma_f32_16x16x32_bf16 v[54:57], v[126:129], v[232:235], v[54:57]
	v_mfma_f32_16x16x32_bf16 v[50:53], v[160:163], v[232:235], v[50:53]
	v_mfma_f32_16x16x32_bf16 v[118:121], v[130:133], v[82:85], v[98:101]
	v_mfma_f32_16x16x32_bf16 v[98:101], v[148:151], v[192:195], v[66:69]
	v_mfma_f32_16x16x32_bf16 v[86:89], v[130:133], v[200:203], v[62:65]
	v_mfma_f32_16x16x32_bf16 v[82:85], v[148:151], v[200:203], v[58:61]
	v_mfma_f32_16x16x32_bf16 v[70:73], v[130:133], v[236:239], v[54:57]
	v_mfma_f32_16x16x32_bf16 v[66:69], v[148:151], v[236:239], v[50:53]
	s_setprio 0
	s_barrier
	s_nop 0
	ds_read_b128 v[50:53], v0 offset:49152
	ds_read_b128 v[164:167], v0 offset:50176
	ds_read_b128 v[188:191], v0 offset:51200
	ds_read_b128 v[192:195], v0 offset:52224
	ds_read_b128 v[196:199], v0 offset:53248
	ds_read_b128 v[200:203], v0 offset:54272
	ds_read_b128 v[222:225], v0 offset:55296
	ds_read_b128 v[232:235], v0 offset:56320
	s_barrier
	s_waitcnt lgkmcnt(0)
	s_setprio 1
	s_waitcnt lgkmcnt(7)
	v_mfma_f32_16x16x32_bf16 v[46:49], v[10:13], v[50:53], v[46:49]
	s_waitcnt lgkmcnt(5)
	v_mfma_f32_16x16x32_bf16 v[38:41], v[10:13], v[188:191], v[38:41]
	s_waitcnt lgkmcnt(3)
	v_mfma_f32_16x16x32_bf16 v[30:33], v[10:13], v[196:199], v[30:33]
	s_waitcnt lgkmcnt(1)
	v_mfma_f32_16x16x32_bf16 v[10:13], v[10:13], v[222:225], v[22:25]
	v_mfma_f32_16x16x32_bf16 v[62:65], v[14:17], v[164:167], v[46:49]
	v_mfma_f32_16x16x32_bf16 v[42:45], v[180:183], v[50:53], v[42:45]
	v_mfma_f32_16x16x32_bf16 v[46:49], v[14:17], v[192:195], v[38:41]
	v_mfma_f32_16x16x32_bf16 v[34:37], v[180:183], v[188:191], v[34:37]
	v_mfma_f32_16x16x32_bf16 v[30:33], v[14:17], v[200:203], v[30:33]
	v_mfma_f32_16x16x32_bf16 v[26:29], v[180:183], v[196:199], v[26:29]
	s_waitcnt lgkmcnt(0)
	v_mfma_f32_16x16x32_bf16 v[14:17], v[14:17], v[232:235], v[10:13]
	v_mfma_f32_16x16x32_bf16 v[10:13], v[180:183], v[222:225], v[18:21]
	v_mfma_f32_16x16x32_bf16 v[58:61], v[184:187], v[164:167], v[42:45]
	v_mfma_f32_16x16x32_bf16 v[42:45], v[184:187], v[192:195], v[34:37]
	v_mfma_f32_16x16x32_bf16 v[26:29], v[184:187], v[200:203], v[26:29]
	v_mfma_f32_16x16x32_bf16 v[10:13], v[184:187], v[232:235], v[10:13]
	s_setprio 0
	s_setprio 1
	v_mfma_f32_16x16x32_bf16 v[2:5], v[160:163], v[188:191], v[2:5]
	v_mfma_f32_16x16x32_bf16 v[18:21], v[126:129], v[50:53], v[134:137]
	v_mfma_f32_16x16x32_bf16 v[34:37], v[148:151], v[192:195], v[2:5]
	v_mfma_f32_16x16x32_bf16 v[2:5], v[126:129], v[196:199], v[156:159]
	v_mfma_f32_16x16x32_bf16 v[54:57], v[130:133], v[164:167], v[18:21]
	v_mfma_f32_16x16x32_bf16 v[18:21], v[160:163], v[50:53], v[152:155]
	v_mfma_f32_16x16x32_bf16 v[22:25], v[130:133], v[200:203], v[2:5]
	v_mfma_f32_16x16x32_bf16 v[2:5], v[160:163], v[196:199], v[168:171]
	v_mfma_f32_16x16x32_bf16 v[50:53], v[148:151], v[164:167], v[18:21]
	v_mfma_f32_16x16x32_bf16 v[6:9], v[126:129], v[188:191], v[6:9]
	v_mfma_f32_16x16x32_bf16 v[18:21], v[148:151], v[200:203], v[2:5]
	v_mfma_f32_16x16x32_bf16 v[2:5], v[126:129], v[222:225], v[172:175]
	v_mfma_f32_16x16x32_bf16 v[38:41], v[130:133], v[192:195], v[6:9]
	v_mfma_f32_16x16x32_bf16 v[6:9], v[130:133], v[232:235], v[2:5]
	v_mfma_f32_16x16x32_bf16 v[2:5], v[160:163], v[222:225], v[176:179]
	v_mfma_f32_16x16x32_bf16 v[2:5], v[148:151], v[232:235], v[2:5]
	s_setprio 0
	s_movk_i32 s0, 0x100
	v_cmp_gt_u32_e32 vcc, s0, v142
	s_barrier
	s_and_saveexec_b64 s[0:1], vcc
	s_cbranch_execz .LBB0_37
	s_barrier

.LBB0_84:
	s_or_b64 exec, exec, s[52:53]
	v_mov_b32_e32 v3, v1
	v_lshl_add_u64 v[12:13], s[0:1], 0, v[2:3]
	v_lshl_add_u64 v[16:17], s[12:13], 0, v[2:3]
	v_lshl_add_u64 v[20:21], s[14:15], 0, v[2:3]
	v_lshl_add_u64 v[130:131], s[16:17], 0, v[2:3]
	v_and_b32_e32 v146, 15, v142
	v_bfe_u32 v145, v142, 4, 2
	v_lshlrev_b32_e32 v3, 2, v142
	v_add_u32_e32 v156, 0x18000, v147
	v_lshl_add_u64 v[10:11], s[0:1], 0, v[0:1]
	v_lshl_add_u64 v[14:15], s[12:13], 0, v[0:1]
	v_lshl_add_u64 v[18:19], s[14:15], 0, v[0:1]
	v_lshl_add_u64 v[132:133], s[16:17], 0, v[0:1]
	v_lshlrev_b32_e32 v0, 6, v146
	v_lshlrev_b32_e32 v2, 4, v145
	v_and_b32_e32 v3, 32, v3
	s_mov_b64 s[12:13], 0x80
	v_readfirstlane_b32 s0, v156
	v_add_u32_e32 v157, 0x1a000, v147
	v_bitop3_b32 v22, v2, v3, v0 bitop3:0x36
	v_lshl_add_u64 v[2:3], v[10:11], 0, s[12:13]
	s_mov_b32 m0, s0
	v_readfirstlane_b32 s0, v157
	v_add_u32_e32 v158, 0x8000, v147
	s_waitcnt vmcnt(4)
	s_barrier
	global_load_lds_dwordx4 v[2:3], off
	v_lshl_add_u64 v[2:3], v[12:13], 0, s[12:13]
	s_mov_b32 m0, s0
	v_readfirstlane_b32 s0, v158
	v_add_u32_e32 v159, 0xa000, v147
	global_load_lds_dwordx4 v[2:3], off
	v_lshl_add_u64 v[2:3], v[14:15], 0, s[12:13]
	s_mov_b32 m0, s0
	v_readfirstlane_b32 s0, v159
	v_add_u32_e32 v160, 0x1c000, v147
	global_load_lds_dwordx4 v[2:3], off
	v_lshl_add_u64 v[2:3], v[16:17], 0, s[12:13]
	s_mov_b32 m0, s0
	v_readfirstlane_b32 s0, v160
	v_add_u32_e32 v161, 0x1e000, v147
	global_load_lds_dwordx4 v[2:3], off
	v_lshl_add_u64 v[2:3], v[18:19], 0, s[12:13]
	s_mov_b32 m0, s0
	v_readfirstlane_b32 s0, v161
	global_load_lds_dwordx4 v[2:3], off
	v_lshl_add_u64 v[2:3], v[20:21], 0, s[12:13]
	s_mov_b32 m0, s0
	s_sub_i32 s1, s57, s64
	global_load_lds_dwordx4 v[2:3], off
	s_sub_i32 s1, s1, s63
	v_lshlrev_b32_e32 v0, 15, v4
	s_sext_i32_i16 s1, s1
	v_and_b32_e32 v0, 0xffff0000, v0
	s_lshl_b32 s0, s62, 10
	s_lshl_b32 s1, s1, 8
	v_lshl_add_u32 v0, v5, 12, v0
	v_and_b32_e32 v2, 1, v4
	s_add_i32 s0, s0, s1
	v_lshl_or_b32 v0, v2, 6, v0
	v_lshlrev_b32_e32 v2, 15, v6
	s_ashr_i32 s1, s0, 31
	v_and_b32_e32 v2, 0xffff0000, v2
	s_lshl_b64 s[0:1], s[0:1], 12
	v_lshl_add_u32 v2, v8, 12, v2
	v_and_b32_e32 v3, 1, v6
	s_add_u32 s0, s4, s0
	v_lshl_or_b32 v2, v3, 6, v2
	v_lshl_add_u32 v0, v7, 1, v0
	s_addc_u32 s1, s5, s1
	v_lshl_add_u32 v2, v9, 1, v2
	v_mov_b32_e32 v3, v1
	s_waitcnt vmcnt(6)
	v_lshl_add_u64 v[134:135], s[0:1], 0, v[0:1]
	v_lshl_add_u64 v[136:137], s[0:1], 0, v[2:3]
	s_add_u32 s0, s88, s10
	v_bfe_u32 v144, v142, 6, 2
	s_addc_u32 s1, s89, s11
	v_lshlrev_b32_e32 v23, 13, v143
	v_lshl_or_b32 v24, v144, 12, v212
	v_lshl_add_u64 v[140:141], s[0:1], 0, v[2:3]
	v_mov_b32_e32 v2, 0
	s_barrier
	v_lshl_add_u64 v[138:139], s[0:1], 0, v[0:1]
	s_mov_b32 s0, -2
	s_mov_b64 s[10:11], 0
	v_add_u32_e32 v151, v24, v22
	v_add_u32_e32 v0, v23, v22
	v_mov_b32_e32 v3, v2
	v_mov_b32_e32 v4, v2
	v_mov_b32_e32 v5, v2
	v_mov_b32_e32 v6, v2
	v_mov_b32_e32 v7, v2
	v_mov_b32_e32 v8, v2
	v_mov_b32_e32 v9, v2
	v_mov_b32_e32 v10, v2
	v_mov_b32_e32 v11, v2
	v_mov_b32_e32 v12, v2
	v_mov_b32_e32 v13, v2
	v_mov_b32_e32 v14, v2
	v_mov_b32_e32 v15, v2
	v_mov_b32_e32 v16, v2
	v_mov_b32_e32 v17, v2
	v_mov_b32_e32 v18, v2
	v_mov_b32_e32 v19, v2
	v_mov_b32_e32 v20, v2
	v_mov_b32_e32 v21, v2
	v_mov_b32_e32 v22, v2
	v_mov_b32_e32 v23, v2
	v_mov_b32_e32 v24, v2
	v_mov_b32_e32 v25, v2
	v_mov_b32_e32 v26, v2
	v_mov_b32_e32 v27, v2
	v_mov_b32_e32 v28, v2
	v_mov_b32_e32 v29, v2
	v_mov_b32_e32 v30, v2
	v_mov_b32_e32 v31, v2
	v_mov_b32_e32 v32, v2
	v_mov_b32_e32 v33, v2
	v_mov_b32_e32 v34, v2
	v_mov_b32_e32 v35, v2
	v_mov_b32_e32 v36, v2
	v_mov_b32_e32 v37, v2
	v_mov_b32_e32 v38, v2
	v_mov_b32_e32 v39, v2
	v_mov_b32_e32 v40, v2
	v_mov_b32_e32 v41, v2
	v_mov_b32_e32 v42, v2
	v_mov_b32_e32 v43, v2
	v_mov_b32_e32 v44, v2
	v_mov_b32_e32 v45, v2
	v_mov_b32_e32 v46, v2
	v_mov_b32_e32 v47, v2
	v_mov_b32_e32 v48, v2
	v_mov_b32_e32 v49, v2
	v_mov_b32_e32 v50, v2
	v_mov_b32_e32 v51, v2
	v_mov_b32_e32 v52, v2
	v_mov_b32_e32 v53, v2
	v_mov_b32_e32 v54, v2
	v_mov_b32_e32 v55, v2
	v_mov_b32_e32 v56, v2
	v_mov_b32_e32 v57, v2
	v_mov_b32_e32 v58, v2
	v_mov_b32_e32 v59, v2
	v_mov_b32_e32 v60, v2
	v_mov_b32_e32 v61, v2
	v_mov_b32_e32 v62, v2
	v_mov_b32_e32 v63, v2
	v_mov_b32_e32 v64, v2
	v_mov_b32_e32 v65, v2
	v_mov_b32_e32 v66, v2
	v_mov_b32_e32 v67, v2
	v_mov_b32_e32 v68, v2
	v_mov_b32_e32 v69, v2
	v_mov_b32_e32 v70, v2
	v_mov_b32_e32 v71, v2
	v_mov_b32_e32 v72, v2
	v_mov_b32_e32 v73, v2
	v_mov_b32_e32 v74, v2
	v_mov_b32_e32 v75, v2
	v_mov_b32_e32 v76, v2
	v_mov_b32_e32 v77, v2
	v_mov_b32_e32 v78, v2
	v_mov_b32_e32 v79, v2
	v_mov_b32_e32 v80, v2
	v_mov_b32_e32 v81, v2
	v_mov_b32_e32 v82, v2
	v_mov_b32_e32 v83, v2
	v_mov_b32_e32 v84, v2
	v_mov_b32_e32 v85, v2
	v_mov_b32_e32 v86, v2
	v_mov_b32_e32 v87, v2
	v_mov_b32_e32 v88, v2
	v_mov_b32_e32 v89, v2
	v_mov_b32_e32 v90, v2
	v_mov_b32_e32 v91, v2
	v_mov_b32_e32 v92, v2
	v_mov_b32_e32 v93, v2
	v_mov_b32_e32 v94, v2
	v_mov_b32_e32 v95, v2
	v_mov_b32_e32 v96, v2
	v_mov_b32_e32 v97, v2
	v_mov_b32_e32 v98, v2
	v_mov_b32_e32 v99, v2
	v_mov_b32_e32 v100, v2
	v_mov_b32_e32 v101, v2
	v_mov_b32_e32 v102, v2
	v_mov_b32_e32 v103, v2
	v_mov_b32_e32 v104, v2
	v_mov_b32_e32 v105, v2
	v_mov_b32_e32 v106, v2
	v_mov_b32_e32 v107, v2
	v_mov_b32_e32 v108, v2
	v_mov_b32_e32 v109, v2
	v_mov_b32_e32 v110, v2
	v_mov_b32_e32 v111, v2
	v_mov_b32_e32 v112, v2
	v_mov_b32_e32 v113, v2
	v_mov_b32_e32 v114, v2
	v_mov_b32_e32 v115, v2
	v_mov_b32_e32 v116, v2
	v_mov_b32_e32 v117, v2
	v_mov_b32_e32 v118, v2
	v_mov_b32_e32 v119, v2
	v_mov_b32_e32 v120, v2
	v_mov_b32_e32 v121, v2
	v_mov_b32_e32 v122, v2
	v_mov_b32_e32 v123, v2
	v_mov_b32_e32 v124, v2
	v_mov_b32_e32 v125, v2
	v_mov_b32_e32 v126, v2
	v_mov_b32_e32 v127, v2
	v_mov_b32_e32 v128, v2
	v_mov_b32_e32 v129, v2
	v_readfirstlane_b32 s1, v147
	s_nop 1
.LBB0_85:
	ds_read_b128 v[164:167], v151
	ds_read_b128 v[168:171], v151 offset:1024
	ds_read_b128 v[172:175], v151 offset:2048
	ds_read_b128 v[176:179], v151 offset:3072
	v_add_u32_e32 v162, 0xc000, v147
	v_lshl_add_u64 v[204:205], v[138:139], 0, s[10:11]
	v_lshl_add_u64 v[210:211], v[204:205], 0, s[60:61]
	s_add_i32 m0, s1, 0xc000
	v_add_u32_e32 v163, 0xe000, v147
	ds_read_b128 v[180:183], v0
	ds_read_b128 v[184:187], v0 offset:1024
	ds_read_b128 v[188:191], v0 offset:2048
	ds_read_b128 v[192:195], v0 offset:3072
	ds_read_b128 v[196:199], v0 offset:4096
	ds_read_b128 v[200:203], v0 offset:5120
	ds_read_b128 v[222:225], v0 offset:6144
	ds_read_b128 v[232:235], v0 offset:7168
	global_load_lds_dwordx4 v[210:211], off
	v_lshl_add_u64 v[210:211], v[140:141], 0, s[10:11]
	v_lshl_add_u64 v[216:217], v[210:211], 0, s[60:61]
	s_add_i32 m0, s1, 0xe000
	s_nop 0
	global_load_lds_dwordx4 v[216:217], off
	s_waitcnt lgkmcnt(8)
	s_barrier
	s_waitcnt lgkmcnt(0)
	s_setprio 1
	s_waitcnt lgkmcnt(0)
	v_mfma_f32_16x16x32_bf16 v[126:129], v[164:167], v[180:183], v[126:129]
	v_mfma_f32_16x16x32_bf16 v[122:125], v[172:175], v[180:183], v[122:125]
	v_mfma_f32_16x16x32_bf16 v[118:121], v[164:167], v[188:191], v[118:121]
	v_mfma_f32_16x16x32_bf16 v[114:117], v[172:175], v[188:191], v[114:117]
	v_mfma_f32_16x16x32_bf16 v[110:113], v[164:167], v[196:199], v[110:113]
	v_mfma_f32_16x16x32_bf16 v[106:109], v[172:175], v[196:199], v[106:109]
	v_mfma_f32_16x16x32_bf16 v[102:105], v[164:167], v[222:225], v[102:105]
	v_mfma_f32_16x16x32_bf16 v[98:101], v[172:175], v[222:225], v[98:101]
	v_mfma_f32_16x16x32_bf16 v[126:129], v[168:171], v[184:187], v[126:129]
	v_mfma_f32_16x16x32_bf16 v[122:125], v[176:179], v[184:187], v[122:125]
	v_mfma_f32_16x16x32_bf16 v[118:121], v[168:171], v[192:195], v[118:121]
	v_mfma_f32_16x16x32_bf16 v[114:117], v[176:179], v[192:195], v[114:117]
	v_mfma_f32_16x16x32_bf16 v[110:113], v[168:171], v[200:203], v[110:113]
	v_mfma_f32_16x16x32_bf16 v[106:109], v[176:179], v[200:203], v[106:109]
	v_mfma_f32_16x16x32_bf16 v[102:105], v[168:171], v[232:235], v[102:105]
	v_mfma_f32_16x16x32_bf16 v[98:101], v[176:179], v[232:235], v[98:101]
	s_setprio 0
	s_barrier
	v_lshl_add_u64 v[216:217], v[134:135], 0, s[10:11]
	v_lshl_add_u64 v[218:219], v[216:217], 0, s[74:75]
	s_add_i32 m0, s1, 0x10000
	ds_read_b128 v[236:239], v151 offset:16384
	ds_read_b128 v[240:243], v151 offset:17408
	ds_read_b128 v[244:247], v151 offset:18432
	ds_read_b128 v[248:251], v151 offset:19456
	global_load_lds_dwordx4 v[218:219], off
	v_lshl_add_u64 v[218:219], v[136:137], 0, s[10:11]
	v_lshl_add_u64 v[228:229], v[218:219], 0, s[74:75]
	s_add_i32 m0, s1, 0x12000
	s_nop 0
	global_load_lds_dwordx4 v[228:229], off
	s_barrier
	s_waitcnt lgkmcnt(0)
	s_setprio 1
	s_waitcnt lgkmcnt(0)
	v_mfma_f32_16x16x32_bf16 v[94:97], v[236:239], v[180:183], v[94:97]
	v_mfma_f32_16x16x32_bf16 v[90:93], v[244:247], v[180:183], v[90:93]
	v_mfma_f32_16x16x32_bf16 v[86:89], v[236:239], v[188:191], v[86:89]
	v_mfma_f32_16x16x32_bf16 v[82:85], v[244:247], v[188:191], v[82:85]
	v_mfma_f32_16x16x32_bf16 v[78:81], v[236:239], v[196:199], v[78:81]
	v_mfma_f32_16x16x32_bf16 v[74:77], v[244:247], v[196:199], v[74:77]
	v_mfma_f32_16x16x32_bf16 v[70:73], v[236:239], v[222:225], v[70:73]
	v_mfma_f32_16x16x32_bf16 v[66:69], v[244:247], v[222:225], v[66:69]
	v_mfma_f32_16x16x32_bf16 v[94:97], v[240:243], v[184:187], v[94:97]
	v_mfma_f32_16x16x32_bf16 v[90:93], v[248:251], v[184:187], v[90:93]
	v_mfma_f32_16x16x32_bf16 v[86:89], v[240:243], v[192:195], v[86:89]
	v_mfma_f32_16x16x32_bf16 v[82:85], v[248:251], v[192:195], v[82:85]
	v_mfma_f32_16x16x32_bf16 v[78:81], v[240:243], v[200:203], v[78:81]
	v_mfma_f32_16x16x32_bf16 v[74:77], v[248:251], v[200:203], v[74:77]
	v_mfma_f32_16x16x32_bf16 v[70:73], v[240:243], v[232:235], v[70:73]
	v_mfma_f32_16x16x32_bf16 v[66:69], v[248:251], v[232:235], v[66:69]
	s_setprio 0
	v_lshl_add_u64 v[228:229], v[204:205], 0, s[74:75]
	s_mov_b32 m0, s1
	s_barrier
	ds_read_b128 v[180:183], v0 offset:16384
	ds_read_b128 v[184:187], v0 offset:17408
	ds_read_b128 v[188:191], v0 offset:18432
	ds_read_b128 v[192:195], v0 offset:19456
	ds_read_b128 v[196:199], v0 offset:20480
	ds_read_b128 v[200:203], v0 offset:21504
	ds_read_b128 v[222:225], v0 offset:22528
	ds_read_b128 v[232:235], v0 offset:23552
	global_load_lds_dwordx4 v[228:229], off
	v_lshl_add_u64 v[228:229], v[210:211], 0, s[74:75]
	s_add_i32 m0, s1, 0x2000
	s_nop 0
	global_load_lds_dwordx4 v[228:229], off
	s_barrier
	s_waitcnt lgkmcnt(0)
	s_setprio 1
	s_waitcnt lgkmcnt(0)
	v_mfma_f32_16x16x32_bf16 v[62:65], v[164:167], v[180:183], v[62:65]
	v_mfma_f32_16x16x32_bf16 v[58:61], v[172:175], v[180:183], v[58:61]
	v_mfma_f32_16x16x32_bf16 v[54:57], v[164:167], v[188:191], v[54:57]
	v_mfma_f32_16x16x32_bf16 v[50:53], v[172:175], v[188:191], v[50:53]
	v_mfma_f32_16x16x32_bf16 v[46:49], v[164:167], v[196:199], v[46:49]
	v_mfma_f32_16x16x32_bf16 v[42:45], v[172:175], v[196:199], v[42:45]
	v_mfma_f32_16x16x32_bf16 v[38:41], v[164:167], v[222:225], v[38:41]
	v_mfma_f32_16x16x32_bf16 v[34:37], v[172:175], v[222:225], v[34:37]
	v_mfma_f32_16x16x32_bf16 v[62:65], v[168:171], v[184:187], v[62:65]
	v_mfma_f32_16x16x32_bf16 v[58:61], v[176:179], v[184:187], v[58:61]
	v_mfma_f32_16x16x32_bf16 v[54:57], v[168:171], v[192:195], v[54:57]
	v_mfma_f32_16x16x32_bf16 v[50:53], v[176:179], v[192:195], v[50:53]
	v_mfma_f32_16x16x32_bf16 v[46:49], v[168:171], v[200:203], v[46:49]
	v_mfma_f32_16x16x32_bf16 v[42:45], v[176:179], v[200:203], v[42:45]
	v_mfma_f32_16x16x32_bf16 v[38:41], v[168:171], v[232:235], v[38:41]
	v_mfma_f32_16x16x32_bf16 v[34:37], v[176:179], v[232:235], v[34:37]
	s_setprio 0
	s_barrier
	v_lshl_add_u64 v[164:165], v[216:217], 0, s[18:19]
	s_add_i32 m0, s1, 0x14000
	global_load_lds_dwordx4 v[164:165], off
	v_lshl_add_u64 v[164:165], v[218:219], 0, s[18:19]
	s_add_i32 m0, s1, 0x16000
	s_nop 0
	global_load_lds_dwordx4 v[164:165], off
	s_waitcnt vmcnt(6)
	s_barrier
	s_setprio 1
	v_mfma_f32_16x16x32_bf16 v[30:33], v[236:239], v[180:183], v[30:33]
	v_mfma_f32_16x16x32_bf16 v[26:29], v[244:247], v[180:183], v[26:29]
	v_mfma_f32_16x16x32_bf16 v[22:25], v[236:239], v[188:191], v[22:25]
	v_mfma_f32_16x16x32_bf16 v[18:21], v[244:247], v[188:191], v[18:21]
	v_mfma_f32_16x16x32_bf16 v[14:17], v[236:239], v[196:199], v[14:17]
	v_mfma_f32_16x16x32_bf16 v[10:13], v[244:247], v[196:199], v[10:13]
	v_mfma_f32_16x16x32_bf16 v[6:9], v[236:239], v[222:225], v[6:9]
	v_mfma_f32_16x16x32_bf16 v[2:5], v[244:247], v[222:225], v[2:5]
	v_mfma_f32_16x16x32_bf16 v[30:33], v[240:243], v[184:187], v[30:33]
	v_mfma_f32_16x16x32_bf16 v[26:29], v[248:251], v[184:187], v[26:29]
	v_mfma_f32_16x16x32_bf16 v[22:25], v[240:243], v[192:195], v[22:25]
	v_mfma_f32_16x16x32_bf16 v[18:21], v[248:251], v[192:195], v[18:21]
	v_mfma_f32_16x16x32_bf16 v[14:17], v[240:243], v[200:203], v[14:17]
	v_mfma_f32_16x16x32_bf16 v[10:13], v[248:251], v[200:203], v[10:13]
	v_mfma_f32_16x16x32_bf16 v[6:9], v[240:243], v[232:235], v[6:9]
	v_mfma_f32_16x16x32_bf16 v[2:5], v[248:251], v[232:235], v[2:5]
	s_setprio 0
	s_barrier
	ds_read_b128 v[164:167], v151 offset:32768
	ds_read_b128 v[168:171], v151 offset:33792
	ds_read_b128 v[172:175], v151 offset:34816
	ds_read_b128 v[176:179], v151 offset:35840
	v_lshl_add_u64 v[228:229], v[204:205], 0, s[18:19]
	s_add_i32 m0, s1, 0x4000
	ds_read_b128 v[180:183], v0 offset:32768
	ds_read_b128 v[184:187], v0 offset:33792
	ds_read_b128 v[188:191], v0 offset:34816
	ds_read_b128 v[192:195], v0 offset:35840
	ds_read_b128 v[196:199], v0 offset:36864
	ds_read_b128 v[200:203], v0 offset:37888
	ds_read_b128 v[222:225], v0 offset:38912
	ds_read_b128 v[232:235], v0 offset:39936
	global_load_lds_dwordx4 v[228:229], off
	v_lshl_add_u64 v[228:229], v[210:211], 0, s[18:19]
	s_add_i32 m0, s1, 0x6000
	s_nop 0
	global_load_lds_dwordx4 v[228:229], off
	s_waitcnt lgkmcnt(8)
	s_barrier
	s_waitcnt lgkmcnt(0)
	s_setprio 1
	s_waitcnt lgkmcnt(0)
	v_mfma_f32_16x16x32_bf16 v[126:129], v[164:167], v[180:183], v[126:129]
	v_mfma_f32_16x16x32_bf16 v[122:125], v[172:175], v[180:183], v[122:125]
	v_mfma_f32_16x16x32_bf16 v[118:121], v[164:167], v[188:191], v[118:121]
	v_mfma_f32_16x16x32_bf16 v[114:117], v[172:175], v[188:191], v[114:117]
	v_mfma_f32_16x16x32_bf16 v[110:113], v[164:167], v[196:199], v[110:113]
	v_mfma_f32_16x16x32_bf16 v[106:109], v[172:175], v[196:199], v[106:109]
	v_mfma_f32_16x16x32_bf16 v[102:105], v[164:167], v[222:225], v[102:105]
	v_mfma_f32_16x16x32_bf16 v[98:101], v[172:175], v[222:225], v[98:101]
	v_mfma_f32_16x16x32_bf16 v[126:129], v[168:171], v[184:187], v[126:129]
	v_mfma_f32_16x16x32_bf16 v[122:125], v[176:179], v[184:187], v[122:125]
	v_mfma_f32_16x16x32_bf16 v[118:121], v[168:171], v[192:195], v[118:121]
	v_mfma_f32_16x16x32_bf16 v[114:117], v[176:179], v[192:195], v[114:117]
	v_mfma_f32_16x16x32_bf16 v[110:113], v[168:171], v[200:203], v[110:113]
	v_mfma_f32_16x16x32_bf16 v[106:109], v[176:179], v[200:203], v[106:109]
	v_mfma_f32_16x16x32_bf16 v[102:105], v[168:171], v[232:235], v[102:105]
	v_mfma_f32_16x16x32_bf16 v[98:101], v[176:179], v[232:235], v[98:101]
	s_setprio 0
	s_barrier
	v_lshl_add_u64 v[228:229], v[216:217], 0, s[28:29]
	s_add_i32 m0, s1, 0x18000
	ds_read_b128 v[236:239], v151 offset:49152
	ds_read_b128 v[240:243], v151 offset:50176
	ds_read_b128 v[244:247], v151 offset:51200
	ds_read_b128 v[248:251], v151 offset:52224
	global_load_lds_dwordx4 v[228:229], off
	v_lshl_add_u64 v[228:229], v[218:219], 0, s[28:29]
	s_add_i32 m0, s1, 0x1a000
	s_nop 0
	global_load_lds_dwordx4 v[228:229], off
	s_barrier
	s_waitcnt lgkmcnt(0)
	s_setprio 1
	s_waitcnt lgkmcnt(0)
	v_mfma_f32_16x16x32_bf16 v[94:97], v[236:239], v[180:183], v[94:97]
	v_mfma_f32_16x16x32_bf16 v[90:93], v[244:247], v[180:183], v[90:93]
	v_mfma_f32_16x16x32_bf16 v[86:89], v[236:239], v[188:191], v[86:89]
	v_mfma_f32_16x16x32_bf16 v[82:85], v[244:247], v[188:191], v[82:85]
	v_mfma_f32_16x16x32_bf16 v[78:81], v[236:239], v[196:199], v[78:81]
	v_mfma_f32_16x16x32_bf16 v[74:77], v[244:247], v[196:199], v[74:77]
	v_mfma_f32_16x16x32_bf16 v[70:73], v[236:239], v[222:225], v[70:73]
	v_mfma_f32_16x16x32_bf16 v[66:69], v[244:247], v[222:225], v[66:69]
	v_mfma_f32_16x16x32_bf16 v[94:97], v[240:243], v[184:187], v[94:97]
	v_mfma_f32_16x16x32_bf16 v[90:93], v[248:251], v[184:187], v[90:93]
	v_mfma_f32_16x16x32_bf16 v[86:89], v[240:243], v[192:195], v[86:89]
	v_mfma_f32_16x16x32_bf16 v[82:85], v[248:251], v[192:195], v[82:85]
	v_mfma_f32_16x16x32_bf16 v[78:81], v[240:243], v[200:203], v[78:81]
	v_mfma_f32_16x16x32_bf16 v[74:77], v[248:251], v[200:203], v[74:77]
	v_mfma_f32_16x16x32_bf16 v[70:73], v[240:243], v[232:235], v[70:73]
	v_mfma_f32_16x16x32_bf16 v[66:69], v[248:251], v[232:235], v[66:69]
	s_setprio 0
	v_lshl_add_u64 v[204:205], v[204:205], 0, s[28:29]
	s_add_i32 m0, s1, 0x8000
	s_barrier
	ds_read_b128 v[180:183], v0 offset:49152
	ds_read_b128 v[184:187], v0 offset:50176
	ds_read_b128 v[188:191], v0 offset:51200
	ds_read_b128 v[192:195], v0 offset:52224
	ds_read_b128 v[196:199], v0 offset:53248
	ds_read_b128 v[200:203], v0 offset:54272
	ds_read_b128 v[222:225], v0 offset:55296
	ds_read_b128 v[232:235], v0 offset:56320
	global_load_lds_dwordx4 v[204:205], off
	v_lshl_add_u64 v[204:205], v[210:211], 0, s[28:29]
	s_add_i32 m0, s1, 0xa000
	s_nop 0
	global_load_lds_dwordx4 v[204:205], off
	s_barrier
	s_waitcnt lgkmcnt(0)
	s_setprio 1
	s_waitcnt lgkmcnt(0)
	v_mfma_f32_16x16x32_bf16 v[62:65], v[164:167], v[180:183], v[62:65]
	v_mfma_f32_16x16x32_bf16 v[58:61], v[172:175], v[180:183], v[58:61]
	v_mfma_f32_16x16x32_bf16 v[54:57], v[164:167], v[188:191], v[54:57]
	v_mfma_f32_16x16x32_bf16 v[50:53], v[172:175], v[188:191], v[50:53]
	v_mfma_f32_16x16x32_bf16 v[46:49], v[164:167], v[196:199], v[46:49]
	v_mfma_f32_16x16x32_bf16 v[42:45], v[172:175], v[196:199], v[42:45]
	v_mfma_f32_16x16x32_bf16 v[38:41], v[164:167], v[222:225], v[38:41]
	v_mfma_f32_16x16x32_bf16 v[34:37], v[172:175], v[222:225], v[34:37]
	v_mfma_f32_16x16x32_bf16 v[62:65], v[168:171], v[184:187], v[62:65]
	v_mfma_f32_16x16x32_bf16 v[58:61], v[176:179], v[184:187], v[58:61]
	v_mfma_f32_16x16x32_bf16 v[54:57], v[168:171], v[192:195], v[54:57]
	v_mfma_f32_16x16x32_bf16 v[50:53], v[176:179], v[192:195], v[50:53]
	v_mfma_f32_16x16x32_bf16 v[46:49], v[168:171], v[200:203], v[46:49]
	v_mfma_f32_16x16x32_bf16 v[42:45], v[176:179], v[200:203], v[42:45]
	v_mfma_f32_16x16x32_bf16 v[38:41], v[168:171], v[232:235], v[38:41]
	v_mfma_f32_16x16x32_bf16 v[34:37], v[176:179], v[232:235], v[34:37]
	s_setprio 0
	s_barrier
	v_lshl_add_u64 v[164:165], v[216:217], 0, s[30:31]
	s_add_i32 m0, s1, 0x1c000
	global_load_lds_dwordx4 v[164:165], off
	v_lshl_add_u64 v[164:165], v[218:219], 0, s[30:31]
	s_add_i32 m0, s1, 0x1e000
	s_nop 0
	global_load_lds_dwordx4 v[164:165], off
	s_waitcnt vmcnt(6)
	s_barrier
	s_setprio 1
	v_mfma_f32_16x16x32_bf16 v[30:33], v[236:239], v[180:183], v[30:33]
	v_mfma_f32_16x16x32_bf16 v[26:29], v[244:247], v[180:183], v[26:29]
	v_mfma_f32_16x16x32_bf16 v[22:25], v[236:239], v[188:191], v[22:25]
	v_mfma_f32_16x16x32_bf16 v[18:21], v[244:247], v[188:191], v[18:21]
	v_mfma_f32_16x16x32_bf16 v[14:17], v[236:239], v[196:199], v[14:17]
	v_mfma_f32_16x16x32_bf16 v[10:13], v[244:247], v[196:199], v[10:13]
	v_mfma_f32_16x16x32_bf16 v[6:9], v[236:239], v[222:225], v[6:9]
	v_mfma_f32_16x16x32_bf16 v[2:5], v[244:247], v[222:225], v[2:5]
	v_mfma_f32_16x16x32_bf16 v[30:33], v[240:243], v[184:187], v[30:33]
	v_mfma_f32_16x16x32_bf16 v[26:29], v[248:251], v[184:187], v[26:29]
	v_mfma_f32_16x16x32_bf16 v[22:25], v[240:243], v[192:195], v[22:25]
	v_mfma_f32_16x16x32_bf16 v[18:21], v[248:251], v[192:195], v[18:21]
	v_mfma_f32_16x16x32_bf16 v[14:17], v[240:243], v[200:203], v[14:17]
	v_mfma_f32_16x16x32_bf16 v[10:13], v[248:251], v[200:203], v[10:13]
	v_mfma_f32_16x16x32_bf16 v[6:9], v[240:243], v[232:235], v[6:9]
	v_mfma_f32_16x16x32_bf16 v[2:5], v[248:251], v[232:235], v[2:5]
	s_setprio 0
	s_add_i32 s0, s0, 2
	s_add_u32 s10, s10, 0x100
	s_addc_u32 s11, s11, 0
	s_cmp_lt_u32 s0, 28
	s_barrier
	s_cbranch_scc1 .LBB0_85
	s_add_i32 s1, s1, 0x1e000
	s_mov_b64 s[10:11], 0xf80
	v_readfirstlane_b32 s0, v162
	v_lshl_add_u64 v[132:133], v[132:133], 0, s[10:11]
	s_mov_b32 m0, s0
	v_readfirstlane_b32 s0, v163
	ds_read_b128 v[134:137], v151
	ds_read_b128 v[138:141], v151 offset:1024
	ds_read_b128 v[152:155], v151 offset:2048
	ds_read_b128 v[156:159], v151 offset:3072
	ds_read_b128 v[164:167], v0
	ds_read_b128 v[168:171], v0 offset:1024
	ds_read_b128 v[172:175], v0 offset:2048
	ds_read_b128 v[176:179], v0 offset:3072
	ds_read_b128 v[180:183], v0 offset:4096
	ds_read_b128 v[184:187], v0 offset:5120
	ds_read_b128 v[188:191], v0 offset:6144
	ds_read_b128 v[192:195], v0 offset:7168
	global_load_lds_dwordx4 v[132:133], off
	v_lshl_add_u64 v[130:131], v[130:131], 0, s[10:11]
	s_mov_b32 m0, s0
	s_nop 0
	global_load_lds_dwordx4 v[130:131], off
	s_barrier
	s_waitcnt lgkmcnt(0)
	s_setprio 1
	s_waitcnt lgkmcnt(0)
	v_mfma_f32_16x16x32_bf16 v[126:129], v[134:137], v[164:167], v[126:129]
	v_mfma_f32_16x16x32_bf16 v[122:125], v[152:155], v[164:167], v[122:125]
	v_mfma_f32_16x16x32_bf16 v[114:117], v[152:155], v[172:175], v[114:117]
	v_mfma_f32_16x16x32_bf16 v[106:109], v[152:155], v[180:183], v[106:109]
	v_mfma_f32_16x16x32_bf16 v[98:101], v[152:155], v[188:191], v[98:101]
	v_mfma_f32_16x16x32_bf16 v[126:129], v[138:141], v[168:171], v[126:129]
	v_mfma_f32_16x16x32_bf16 v[122:125], v[156:159], v[168:171], v[122:125]
	v_mfma_f32_16x16x32_bf16 v[118:121], v[134:137], v[172:175], v[118:121]
	v_mfma_f32_16x16x32_bf16 v[114:117], v[156:159], v[176:179], v[114:117]
	v_mfma_f32_16x16x32_bf16 v[110:113], v[134:137], v[180:183], v[110:113]
	v_mfma_f32_16x16x32_bf16 v[106:109], v[156:159], v[184:187], v[106:109]
	v_mfma_f32_16x16x32_bf16 v[102:105], v[134:137], v[188:191], v[102:105]
	v_mfma_f32_16x16x32_bf16 v[98:101], v[156:159], v[192:195], v[98:101]
	v_mfma_f32_16x16x32_bf16 v[130:133], v[138:141], v[176:179], v[118:121]
	v_mfma_f32_16x16x32_bf16 v[160:163], v[138:141], v[184:187], v[110:113]
	v_mfma_f32_16x16x32_bf16 v[196:199], v[138:141], v[192:195], v[102:105]
	s_setprio 0
	s_barrier
	s_nop 0
	ds_read_b128 v[102:105], v151 offset:16384
	ds_read_b128 v[110:113], v151 offset:17408
	ds_read_b128 v[118:121], v151 offset:18432
	ds_read_b128 v[200:203], v151 offset:19456
	s_barrier
	s_waitcnt lgkmcnt(0)
	s_setprio 1
	s_waitcnt lgkmcnt(1)
	v_mfma_f32_16x16x32_bf16 v[90:93], v[118:121], v[164:167], v[90:93]
	v_mfma_f32_16x16x32_bf16 v[86:89], v[102:105], v[172:175], v[86:89]
	v_mfma_f32_16x16x32_bf16 v[82:85], v[118:121], v[172:175], v[82:85]
	v_mfma_f32_16x16x32_bf16 v[78:81], v[102:105], v[180:183], v[78:81]
	v_mfma_f32_16x16x32_bf16 v[70:73], v[102:105], v[188:191], v[70:73]
	v_mfma_f32_16x16x32_bf16 v[94:97], v[102:105], v[164:167], v[94:97]
	s_waitcnt lgkmcnt(0)
	v_mfma_f32_16x16x32_bf16 v[90:93], v[200:203], v[168:171], v[90:93]
	v_mfma_f32_16x16x32_bf16 v[86:89], v[110:113], v[176:179], v[86:89]
	v_mfma_f32_16x16x32_bf16 v[82:85], v[200:203], v[176:179], v[82:85]
	v_mfma_f32_16x16x32_bf16 v[78:81], v[110:113], v[184:187], v[78:81]
	v_mfma_f32_16x16x32_bf16 v[74:77], v[118:121], v[180:183], v[74:77]
	v_mfma_f32_16x16x32_bf16 v[70:73], v[110:113], v[192:195], v[70:73]
	v_mfma_f32_16x16x32_bf16 v[66:69], v[118:121], v[188:191], v[66:69]
	v_mfma_f32_16x16x32_bf16 v[222:225], v[110:113], v[168:171], v[94:97]
	v_mfma_f32_16x16x32_bf16 v[164:167], v[200:203], v[184:187], v[74:77]
	v_mfma_f32_16x16x32_bf16 v[168:171], v[200:203], v[192:195], v[66:69]
	s_setprio 0
	s_barrier
	s_nop 2
	ds_read_b128 v[66:69], v0 offset:16384
	ds_read_b128 v[74:77], v0 offset:17408
	ds_read_b128 v[94:97], v0 offset:18432
	ds_read_b128 v[172:175], v0 offset:19456
	ds_read_b128 v[176:179], v0 offset:20480
	ds_read_b128 v[180:183], v0 offset:21504
	ds_read_b128 v[184:187], v0 offset:22528
	ds_read_b128 v[188:191], v0 offset:23552
	s_waitcnt vmcnt(4)
	s_barrier
	s_waitcnt lgkmcnt(0)
	s_setprio 1
	s_waitcnt lgkmcnt(5)
	v_mfma_f32_16x16x32_bf16 v[54:57], v[134:137], v[94:97], v[54:57]
	v_mfma_f32_16x16x32_bf16 v[50:53], v[152:155], v[94:97], v[50:53]
	v_mfma_f32_16x16x32_bf16 v[62:65], v[134:137], v[66:69], v[62:65]
	v_mfma_f32_16x16x32_bf16 v[58:61], v[152:155], v[66:69], v[58:61]
	s_waitcnt lgkmcnt(4)
	v_mfma_f32_16x16x32_bf16 v[54:57], v[138:141], v[172:175], v[54:57]
	v_mfma_f32_16x16x32_bf16 v[50:53], v[156:159], v[172:175], v[50:53]
	s_waitcnt lgkmcnt(3)
	v_mfma_f32_16x16x32_bf16 v[46:49], v[134:137], v[176:179], v[46:49]
	v_mfma_f32_16x16x32_bf16 v[42:45], v[152:155], v[176:179], v[42:45]
	s_waitcnt lgkmcnt(1)
	v_mfma_f32_16x16x32_bf16 v[38:41], v[134:137], v[184:187], v[38:41]
	v_mfma_f32_16x16x32_bf16 v[34:37], v[152:155], v[184:187], v[34:37]
	v_mfma_f32_16x16x32_bf16 v[192:195], v[138:141], v[74:77], v[62:65]
	v_mfma_f32_16x16x32_bf16 v[232:235], v[156:159], v[74:77], v[58:61]
	v_mfma_f32_16x16x32_bf16 v[236:239], v[138:141], v[180:183], v[46:49]
	v_mfma_f32_16x16x32_bf16 v[240:243], v[156:159], v[180:183], v[42:45]
	s_waitcnt lgkmcnt(0)
	v_mfma_f32_16x16x32_bf16 v[134:137], v[138:141], v[188:191], v[38:41]
	v_mfma_f32_16x16x32_bf16 v[138:141], v[156:159], v[188:191], v[34:37]
	s_setprio 0
	s_setprio 1
	v_mfma_f32_16x16x32_bf16 v[30:33], v[102:105], v[66:69], v[30:33]
	v_mfma_f32_16x16x32_bf16 v[26:29], v[118:121], v[66:69], v[26:29]
	v_mfma_f32_16x16x32_bf16 v[14:17], v[102:105], v[176:179], v[14:17]
	v_mfma_f32_16x16x32_bf16 v[10:13], v[118:121], v[176:179], v[10:13]
	v_mfma_f32_16x16x32_bf16 v[30:33], v[110:113], v[74:77], v[30:33]
	v_mfma_f32_16x16x32_bf16 v[26:29], v[200:203], v[74:77], v[26:29]
	v_mfma_f32_16x16x32_bf16 v[22:25], v[102:105], v[94:97], v[22:25]
	v_mfma_f32_16x16x32_bf16 v[18:21], v[118:121], v[94:97], v[18:21]
	v_mfma_f32_16x16x32_bf16 v[14:17], v[110:113], v[180:183], v[14:17]
	v_mfma_f32_16x16x32_bf16 v[10:13], v[200:203], v[180:183], v[10:13]
	v_mfma_f32_16x16x32_bf16 v[6:9], v[102:105], v[184:187], v[6:9]
	v_mfma_f32_16x16x32_bf16 v[2:5], v[118:121], v[184:187], v[2:5]
	v_mfma_f32_16x16x32_bf16 v[152:155], v[110:113], v[172:175], v[22:25]
	v_mfma_f32_16x16x32_bf16 v[156:159], v[200:203], v[172:175], v[18:21]
	v_mfma_f32_16x16x32_bf16 v[172:175], v[110:113], v[188:191], v[6:9]
	v_mfma_f32_16x16x32_bf16 v[176:179], v[200:203], v[188:191], v[2:5]
	s_setprio 0
	s_barrier
	s_nop 1
	ds_read_b128 v[2:5], v151 offset:32768
	ds_read_b128 v[6:9], v151 offset:33792
	ds_read_b128 v[180:183], v151 offset:34816
	ds_read_b128 v[184:187], v151 offset:35840
	ds_read_b128 v[18:21], v0 offset:32768
	ds_read_b128 v[22:25], v0 offset:33792
	ds_read_b128 v[38:41], v0 offset:34816
	ds_read_b128 v[46:49], v0 offset:35840
	ds_read_b128 v[58:61], v0 offset:36864
	ds_read_b128 v[66:69], v0 offset:37888
	ds_read_b128 v[188:191], v0 offset:38912
	ds_read_b128 v[200:203], v0 offset:39936
	s_waitcnt vmcnt(2)
	s_barrier
	s_waitcnt lgkmcnt(0)
	s_setprio 1
	s_waitcnt lgkmcnt(7)
	v_mfma_f32_16x16x32_bf16 v[34:37], v[2:5], v[18:21], v[126:129]
	s_waitcnt lgkmcnt(6)
	v_mfma_f32_16x16x32_bf16 v[118:121], v[6:9], v[22:25], v[34:37]
	v_mfma_f32_16x16x32_bf16 v[34:37], v[180:183], v[18:21], v[122:125]
	v_mfma_f32_16x16x32_bf16 v[110:113], v[184:187], v[22:25], v[34:37]
	s_waitcnt lgkmcnt(5)
	v_mfma_f32_16x16x32_bf16 v[34:37], v[2:5], v[38:41], v[130:133]
	s_waitcnt lgkmcnt(4)
	v_mfma_f32_16x16x32_bf16 v[102:105], v[6:9], v[46:49], v[34:37]
	v_mfma_f32_16x16x32_bf16 v[34:37], v[180:183], v[38:41], v[114:117]
	v_mfma_f32_16x16x32_bf16 v[94:97], v[184:187], v[46:49], v[34:37]
	s_waitcnt lgkmcnt(3)
	v_mfma_f32_16x16x32_bf16 v[34:37], v[2:5], v[58:61], v[160:163]
	s_waitcnt lgkmcnt(2)
	v_mfma_f32_16x16x32_bf16 v[74:77], v[6:9], v[66:69], v[34:37]
	v_mfma_f32_16x16x32_bf16 v[34:37], v[180:183], v[58:61], v[106:109]
	v_mfma_f32_16x16x32_bf16 v[62:65], v[184:187], v[66:69], v[34:37]
	s_waitcnt lgkmcnt(1)
	v_mfma_f32_16x16x32_bf16 v[34:37], v[2:5], v[188:191], v[196:199]
	s_waitcnt lgkmcnt(0)
	v_mfma_f32_16x16x32_bf16 v[42:45], v[6:9], v[200:203], v[34:37]
	v_mfma_f32_16x16x32_bf16 v[34:37], v[180:183], v[188:191], v[98:101]
	v_mfma_f32_16x16x32_bf16 v[34:37], v[184:187], v[200:203], v[34:37]
	s_setprio 0
	s_barrier
	ds_read_b128 v[130:133], v151 offset:49152
	ds_read_b128 v[160:163], v151 offset:50176
	ds_read_b128 v[196:199], v151 offset:51200
	ds_read_b128 v[148:151], v151 offset:52224
	s_waitcnt vmcnt(0)
	s_barrier
	s_waitcnt lgkmcnt(0)
	s_setprio 1
	s_waitcnt lgkmcnt(3)
	v_mfma_f32_16x16x32_bf16 v[98:101], v[130:133], v[18:21], v[222:225]
	s_waitcnt lgkmcnt(1)
	v_mfma_f32_16x16x32_bf16 v[18:21], v[196:199], v[18:21], v[90:93]
	s_waitcnt lgkmcnt(0)
	v_mfma_f32_16x16x32_bf16 v[122:125], v[148:151], v[22:25], v[18:21]
	v_mfma_f32_16x16x32_bf16 v[18:21], v[130:133], v[38:41], v[86:89]
	v_mfma_f32_16x16x32_bf16 v[114:117], v[160:163], v[46:49], v[18:21]
	v_mfma_f32_16x16x32_bf16 v[18:21], v[196:199], v[38:41], v[82:85]
	v_mfma_f32_16x16x32_bf16 v[106:109], v[148:151], v[46:49], v[18:21]
	v_mfma_f32_16x16x32_bf16 v[18:21], v[130:133], v[58:61], v[78:81]
	v_mfma_f32_16x16x32_bf16 v[126:129], v[160:163], v[22:25], v[98:101]
	v_mfma_f32_16x16x32_bf16 v[98:101], v[160:163], v[66:69], v[18:21]
	v_mfma_f32_16x16x32_bf16 v[18:21], v[196:199], v[58:61], v[164:167]
	v_mfma_f32_16x16x32_bf16 v[90:93], v[148:151], v[66:69], v[18:21]
	v_mfma_f32_16x16x32_bf16 v[18:21], v[130:133], v[188:191], v[70:73]
	v_mfma_f32_16x16x32_bf16 v[66:69], v[160:163], v[200:203], v[18:21]
	v_mfma_f32_16x16x32_bf16 v[18:21], v[196:199], v[188:191], v[168:171]
	v_mfma_f32_16x16x32_bf16 v[58:61], v[148:151], v[200:203], v[18:21]
	s_setprio 0
	s_barrier
	ds_read_b128 v[82:85], v0 offset:49152
	ds_read_b128 v[164:167], v0 offset:50176
	ds_read_b128 v[168:171], v0 offset:51200
	ds_read_b128 v[188:191], v0 offset:52224
	ds_read_b128 v[200:203], v0 offset:53248
	ds_read_b128 v[222:225], v0 offset:54272
	ds_read_b128 v[244:247], v0 offset:55296
	ds_read_b128 v[248:251], v0 offset:56320
	s_barrier
	s_waitcnt lgkmcnt(0)
	s_setprio 1
	s_waitcnt lgkmcnt(7)
	v_mfma_f32_16x16x32_bf16 v[18:21], v[2:5], v[82:85], v[192:195]
	s_waitcnt lgkmcnt(6)
	v_mfma_f32_16x16x32_bf16 v[78:81], v[6:9], v[164:167], v[18:21]
	v_mfma_f32_16x16x32_bf16 v[18:21], v[180:183], v[82:85], v[232:235]
	v_mfma_f32_16x16x32_bf16 v[70:73], v[184:187], v[164:167], v[18:21]
	s_waitcnt lgkmcnt(5)
	v_mfma_f32_16x16x32_bf16 v[18:21], v[2:5], v[168:171], v[54:57]
	s_waitcnt lgkmcnt(4)
	v_mfma_f32_16x16x32_bf16 v[46:49], v[6:9], v[188:191], v[18:21]
	v_mfma_f32_16x16x32_bf16 v[18:21], v[180:183], v[168:171], v[50:53]
	v_mfma_f32_16x16x32_bf16 v[38:41], v[184:187], v[188:191], v[18:21]
	s_waitcnt lgkmcnt(3)
	v_mfma_f32_16x16x32_bf16 v[18:21], v[2:5], v[200:203], v[236:239]
	s_waitcnt lgkmcnt(1)
	v_mfma_f32_16x16x32_bf16 v[2:5], v[2:5], v[244:247], v[134:137]
	v_mfma_f32_16x16x32_bf16 v[22:25], v[6:9], v[222:225], v[18:21]
	v_mfma_f32_16x16x32_bf16 v[18:21], v[180:183], v[200:203], v[240:243]
	s_waitcnt lgkmcnt(0)
	v_mfma_f32_16x16x32_bf16 v[6:9], v[6:9], v[248:251], v[2:5]
	v_mfma_f32_16x16x32_bf16 v[2:5], v[180:183], v[244:247], v[138:141]
	v_mfma_f32_16x16x32_bf16 v[18:21], v[184:187], v[222:225], v[18:21]
	v_mfma_f32_16x16x32_bf16 v[2:5], v[184:187], v[248:251], v[2:5]
	s_setprio 0
	s_setprio 1
	v_mfma_f32_16x16x32_bf16 v[26:29], v[196:199], v[82:85], v[26:29]
	v_mfma_f32_16x16x32_bf16 v[30:33], v[130:133], v[82:85], v[30:33]
	v_mfma_f32_16x16x32_bf16 v[82:85], v[148:151], v[164:167], v[26:29]
	v_mfma_f32_16x16x32_bf16 v[26:29], v[130:133], v[168:171], v[152:155]
	v_mfma_f32_16x16x32_bf16 v[54:57], v[160:163], v[188:191], v[26:29]
	v_mfma_f32_16x16x32_bf16 v[26:29], v[196:199], v[168:171], v[156:159]
	v_mfma_f32_16x16x32_bf16 v[10:13], v[196:199], v[200:203], v[10:13]
	v_mfma_f32_16x16x32_bf16 v[50:53], v[148:151], v[188:191], v[26:29]
	v_mfma_f32_16x16x32_bf16 v[14:17], v[130:133], v[200:203], v[14:17]
	v_mfma_f32_16x16x32_bf16 v[26:29], v[148:151], v[222:225], v[10:13]
	v_mfma_f32_16x16x32_bf16 v[10:13], v[130:133], v[244:247], v[172:175]
	v_mfma_f32_16x16x32_bf16 v[86:89], v[160:163], v[164:167], v[30:33]
	v_mfma_f32_16x16x32_bf16 v[30:33], v[160:163], v[222:225], v[14:17]
	v_mfma_f32_16x16x32_bf16 v[14:17], v[160:163], v[248:251], v[10:13]
	v_mfma_f32_16x16x32_bf16 v[10:13], v[196:199], v[244:247], v[176:179]
	v_mfma_f32_16x16x32_bf16 v[10:13], v[148:151], v[248:251], v[10:13]
	s_setprio 0
	s_movk_i32 s0, 0x100
	v_cmp_gt_u32_e32 vcc, s0, v142
	s_barrier
	s_and_saveexec_b64 s[0:1], vcc
	s_cbranch_execz .LBB0_81
	s_barrier
	s_branch .LBB0_81

.LBB0_179:
	s_or_b64 exec, exec, s[52:53]
	v_mov_b32_e32 v3, v1
	v_lshl_add_u64 v[14:15], s[0:1], 0, v[2:3]
	v_lshl_add_u64 v[18:19], s[16:17], 0, v[2:3]
	v_lshl_add_u64 v[22:23], s[72:73], 0, v[2:3]
	v_lshl_add_u64 v[130:131], s[76:77], 0, v[2:3]
	v_and_b32_e32 v146, 15, v142
	v_bfe_u32 v145, v142, 4, 2
	v_lshlrev_b32_e32 v3, 2, v142
	v_add_u32_e32 v156, 0x18000, v147
	v_lshl_add_u64 v[12:13], s[0:1], 0, v[0:1]
	v_lshl_add_u64 v[16:17], s[16:17], 0, v[0:1]
	v_lshl_add_u64 v[20:21], s[72:73], 0, v[0:1]
	v_lshl_add_u64 v[132:133], s[76:77], 0, v[0:1]
	v_lshlrev_b32_e32 v0, 6, v146
	v_lshlrev_b32_e32 v2, 4, v145
	v_and_b32_e32 v3, 32, v3
	s_mov_b64 s[16:17], 0x80
	v_readfirstlane_b32 s0, v156
	v_add_u32_e32 v157, 0x1a000, v147
	v_bitop3_b32 v24, v2, v3, v0 bitop3:0x36
	v_lshl_add_u64 v[2:3], v[12:13], 0, s[16:17]
	s_mov_b32 m0, s0
	v_readfirstlane_b32 s0, v157
	v_add_u32_e32 v158, 0x8000, v147
	s_waitcnt vmcnt(4)
	s_barrier
	global_load_lds_dwordx4 v[2:3], off
	v_lshl_add_u64 v[2:3], v[14:15], 0, s[16:17]
	s_mov_b32 m0, s0
	v_readfirstlane_b32 s0, v158
	v_add_u32_e32 v159, 0xa000, v147
	global_load_lds_dwordx4 v[2:3], off
	v_lshl_add_u64 v[2:3], v[16:17], 0, s[16:17]
	s_mov_b32 m0, s0
	v_readfirstlane_b32 s0, v159
	v_add_u32_e32 v160, 0x1c000, v147
	global_load_lds_dwordx4 v[2:3], off
	v_lshl_add_u64 v[2:3], v[18:19], 0, s[16:17]
	s_mov_b32 m0, s0
	v_readfirstlane_b32 s0, v160
	v_add_u32_e32 v161, 0x1e000, v147
	global_load_lds_dwordx4 v[2:3], off
	v_lshl_add_u64 v[2:3], v[20:21], 0, s[16:17]
	s_mov_b32 m0, s0
	v_readfirstlane_b32 s0, v161
	global_load_lds_dwordx4 v[2:3], off
	v_lshl_add_u64 v[2:3], v[22:23], 0, s[16:17]
	s_mov_b32 m0, s0
	v_lshlrev_b32_e32 v0, 14, v4
	global_load_lds_dwordx4 v[2:3], off
	v_lshlrev_b32_e32 v2, 14, v7
	v_and_b32_e32 v0, 0x7fff8000, v0
	v_and_b32_e32 v2, 0x7fff8000, v2
	v_lshl_add_u32 v0, v5, 11, v0
	v_lshl_add_u32 v2, v9, 11, v2
	v_or_b32_e32 v0, v0, v6
	s_add_u32 s0, s57, s12
	v_or_b32_e32 v2, v2, v10
	v_readlane_b32 s36, v253, 33
	v_add_lshl_u32 v0, v0, v8, 1
	s_addc_u32 s1, s63, s13
	v_add_lshl_u32 v2, v2, v11, 1
	v_mov_b32_e32 v3, v1
	v_readlane_b32 s48, v253, 45
	v_lshl_add_u64 v[134:135], s[0:1], 0, v[0:1]
	v_lshl_add_u64 v[136:137], s[0:1], 0, v[2:3]
	v_readlane_b32 s49, v253, 46
	s_add_u32 s0, s48, s14
	v_bfe_u32 v144, v142, 6, 2
	s_waitcnt vmcnt(6)
	s_addc_u32 s1, s49, s15
	v_lshlrev_b32_e32 v25, 13, v143
	v_lshl_or_b32 v26, v144, 12, v212
	v_lshl_add_u64 v[140:141], s[0:1], 0, v[2:3]
	v_mov_b32_e32 v2, 0
	v_lshl_add_u64 v[138:139], s[0:1], 0, v[0:1]
	s_mov_b32 s0, -2
	s_mov_b64 s[12:13], 0
	v_add_u32_e32 v151, v26, v24
	v_add_u32_e32 v0, v25, v24
	v_mov_b32_e32 v3, v2
	v_mov_b32_e32 v4, v2
	v_mov_b32_e32 v5, v2
	v_mov_b32_e32 v6, v2
	v_mov_b32_e32 v7, v2
	v_mov_b32_e32 v8, v2
	v_mov_b32_e32 v9, v2
	v_mov_b32_e32 v10, v2
	v_mov_b32_e32 v11, v2
	v_mov_b32_e32 v12, v2
	v_mov_b32_e32 v13, v2
	v_mov_b32_e32 v14, v2
	v_mov_b32_e32 v15, v2
	v_mov_b32_e32 v16, v2
	v_mov_b32_e32 v17, v2
	v_mov_b32_e32 v18, v2
	v_mov_b32_e32 v19, v2
	v_mov_b32_e32 v20, v2
	v_mov_b32_e32 v21, v2
	v_mov_b32_e32 v22, v2
	v_mov_b32_e32 v23, v2
	v_mov_b32_e32 v24, v2
	v_mov_b32_e32 v25, v2
	v_mov_b32_e32 v26, v2
	v_mov_b32_e32 v27, v2
	v_mov_b32_e32 v28, v2
	v_mov_b32_e32 v29, v2
	v_mov_b32_e32 v30, v2
	v_mov_b32_e32 v31, v2
	v_mov_b32_e32 v32, v2
	v_mov_b32_e32 v33, v2
	v_mov_b32_e32 v34, v2
	v_mov_b32_e32 v35, v2
	v_mov_b32_e32 v36, v2
	v_mov_b32_e32 v37, v2
	v_mov_b32_e32 v38, v2
	v_mov_b32_e32 v39, v2
	v_mov_b32_e32 v40, v2
	v_mov_b32_e32 v41, v2
	v_mov_b32_e32 v42, v2
	v_mov_b32_e32 v43, v2
	v_mov_b32_e32 v44, v2
	v_mov_b32_e32 v45, v2
	v_mov_b32_e32 v46, v2
	v_mov_b32_e32 v47, v2
	v_mov_b32_e32 v48, v2
	v_mov_b32_e32 v49, v2
	v_mov_b32_e32 v50, v2
	v_mov_b32_e32 v51, v2
	v_mov_b32_e32 v52, v2
	v_mov_b32_e32 v53, v2
	v_mov_b32_e32 v54, v2
	v_mov_b32_e32 v55, v2
	v_mov_b32_e32 v56, v2
	v_mov_b32_e32 v57, v2
	v_mov_b32_e32 v58, v2
	v_mov_b32_e32 v59, v2
	v_mov_b32_e32 v60, v2
	v_mov_b32_e32 v61, v2
	v_mov_b32_e32 v62, v2
	v_mov_b32_e32 v63, v2
	v_mov_b32_e32 v64, v2
	v_mov_b32_e32 v65, v2
	v_mov_b32_e32 v66, v2
	v_mov_b32_e32 v67, v2
	v_mov_b32_e32 v68, v2
	v_mov_b32_e32 v69, v2
	v_mov_b32_e32 v70, v2
	v_mov_b32_e32 v71, v2
	v_mov_b32_e32 v72, v2
	v_mov_b32_e32 v73, v2
	v_mov_b32_e32 v74, v2
	v_mov_b32_e32 v75, v2
	v_mov_b32_e32 v76, v2
	v_mov_b32_e32 v77, v2
	v_mov_b32_e32 v78, v2
	v_mov_b32_e32 v79, v2
	v_mov_b32_e32 v80, v2
	v_mov_b32_e32 v81, v2
	v_mov_b32_e32 v82, v2
	v_mov_b32_e32 v83, v2
	v_mov_b32_e32 v84, v2
	v_mov_b32_e32 v85, v2
	v_mov_b32_e32 v86, v2
	v_mov_b32_e32 v87, v2
	v_mov_b32_e32 v88, v2
	v_mov_b32_e32 v89, v2
	v_mov_b32_e32 v90, v2
	v_mov_b32_e32 v91, v2
	v_mov_b32_e32 v92, v2
	v_mov_b32_e32 v93, v2
	v_mov_b32_e32 v94, v2
	v_mov_b32_e32 v95, v2
	v_mov_b32_e32 v96, v2
	v_mov_b32_e32 v97, v2
	v_mov_b32_e32 v98, v2
	v_mov_b32_e32 v99, v2
	v_mov_b32_e32 v100, v2
	v_mov_b32_e32 v101, v2
	v_mov_b32_e32 v102, v2
	v_mov_b32_e32 v103, v2
	v_mov_b32_e32 v104, v2
	v_mov_b32_e32 v105, v2
	v_mov_b32_e32 v106, v2
	v_mov_b32_e32 v107, v2
	v_mov_b32_e32 v108, v2
	v_mov_b32_e32 v109, v2
	v_mov_b32_e32 v110, v2
	v_mov_b32_e32 v111, v2
	v_mov_b32_e32 v112, v2
	v_mov_b32_e32 v113, v2
	v_mov_b32_e32 v114, v2
	v_mov_b32_e32 v115, v2
	v_mov_b32_e32 v116, v2
	v_mov_b32_e32 v117, v2
	v_mov_b32_e32 v118, v2
	v_mov_b32_e32 v119, v2
	v_mov_b32_e32 v120, v2
	v_mov_b32_e32 v121, v2
	v_mov_b32_e32 v122, v2
	v_mov_b32_e32 v123, v2
	v_mov_b32_e32 v124, v2
	v_mov_b32_e32 v125, v2
	v_mov_b32_e32 v126, v2
	v_mov_b32_e32 v127, v2
	v_mov_b32_e32 v128, v2
	v_mov_b32_e32 v129, v2
	s_barrier
	v_readlane_b32 s37, v253, 34
	v_readlane_b32 s38, v253, 35
	v_readlane_b32 s39, v253, 36
	v_readlane_b32 s40, v253, 37
	v_readlane_b32 s41, v253, 38
	v_readlane_b32 s42, v253, 39
	v_readlane_b32 s43, v253, 40
	v_readlane_b32 s44, v253, 41
	v_readlane_b32 s45, v253, 42
	v_readlane_b32 s46, v253, 43
	v_readlane_b32 s47, v253, 44
	v_readlane_b32 s50, v253, 47
	v_readlane_b32 s51, v253, 48
	v_readfirstlane_b32 s1, v147
	s_nop 1
.LBB0_180:
	ds_read_b128 v[164:167], v151
	ds_read_b128 v[168:171], v151 offset:1024
	ds_read_b128 v[172:175], v151 offset:2048
	ds_read_b128 v[176:179], v151 offset:3072
	v_add_u32_e32 v162, 0xc000, v147
	v_lshl_add_u64 v[204:205], v[138:139], 0, s[12:13]
	v_lshl_add_u64 v[210:211], v[204:205], 0, s[60:61]
	s_add_i32 m0, s1, 0xc000
	v_add_u32_e32 v163, 0xe000, v147
	ds_read_b128 v[180:183], v0
	ds_read_b128 v[184:187], v0 offset:1024
	ds_read_b128 v[188:191], v0 offset:2048
	ds_read_b128 v[192:195], v0 offset:3072
	ds_read_b128 v[196:199], v0 offset:4096
	ds_read_b128 v[200:203], v0 offset:5120
	ds_read_b128 v[222:225], v0 offset:6144
	ds_read_b128 v[232:235], v0 offset:7168
	global_load_lds_dwordx4 v[210:211], off
	v_lshl_add_u64 v[210:211], v[140:141], 0, s[12:13]
	v_lshl_add_u64 v[216:217], v[210:211], 0, s[60:61]
	s_add_i32 m0, s1, 0xe000
	s_nop 0
	global_load_lds_dwordx4 v[216:217], off
	s_waitcnt lgkmcnt(8)
	s_barrier
	s_waitcnt lgkmcnt(0)
	s_setprio 1
	s_waitcnt lgkmcnt(0)
	v_mfma_f32_16x16x32_bf16 v[126:129], v[164:167], v[180:183], v[126:129]
	v_mfma_f32_16x16x32_bf16 v[122:125], v[172:175], v[180:183], v[122:125]
	v_mfma_f32_16x16x32_bf16 v[118:121], v[164:167], v[188:191], v[118:121]
	v_mfma_f32_16x16x32_bf16 v[114:117], v[172:175], v[188:191], v[114:117]
	v_mfma_f32_16x16x32_bf16 v[110:113], v[164:167], v[196:199], v[110:113]
	v_mfma_f32_16x16x32_bf16 v[106:109], v[172:175], v[196:199], v[106:109]
	v_mfma_f32_16x16x32_bf16 v[102:105], v[164:167], v[222:225], v[102:105]
	v_mfma_f32_16x16x32_bf16 v[98:101], v[172:175], v[222:225], v[98:101]
	v_mfma_f32_16x16x32_bf16 v[126:129], v[168:171], v[184:187], v[126:129]
	v_mfma_f32_16x16x32_bf16 v[122:125], v[176:179], v[184:187], v[122:125]
	v_mfma_f32_16x16x32_bf16 v[118:121], v[168:171], v[192:195], v[118:121]
	v_mfma_f32_16x16x32_bf16 v[114:117], v[176:179], v[192:195], v[114:117]
	v_mfma_f32_16x16x32_bf16 v[110:113], v[168:171], v[200:203], v[110:113]
	v_mfma_f32_16x16x32_bf16 v[106:109], v[176:179], v[200:203], v[106:109]
	v_mfma_f32_16x16x32_bf16 v[102:105], v[168:171], v[232:235], v[102:105]
	v_mfma_f32_16x16x32_bf16 v[98:101], v[176:179], v[232:235], v[98:101]
	s_setprio 0
	s_barrier
	v_lshl_add_u64 v[216:217], v[134:135], 0, s[12:13]
	v_lshl_add_u64 v[218:219], v[216:217], 0, s[74:75]
	s_add_i32 m0, s1, 0x10000
	ds_read_b128 v[236:239], v151 offset:16384
	ds_read_b128 v[240:243], v151 offset:17408
	ds_read_b128 v[244:247], v151 offset:18432
	ds_read_b128 v[248:251], v151 offset:19456
	global_load_lds_dwordx4 v[218:219], off
	v_lshl_add_u64 v[218:219], v[136:137], 0, s[12:13]
	v_lshl_add_u64 v[228:229], v[218:219], 0, s[74:75]
	s_add_i32 m0, s1, 0x12000
	s_nop 0
	global_load_lds_dwordx4 v[228:229], off
	s_barrier
	s_waitcnt lgkmcnt(0)
	s_setprio 1
	s_waitcnt lgkmcnt(0)
	v_mfma_f32_16x16x32_bf16 v[94:97], v[236:239], v[180:183], v[94:97]
	v_mfma_f32_16x16x32_bf16 v[90:93], v[244:247], v[180:183], v[90:93]
	v_mfma_f32_16x16x32_bf16 v[86:89], v[236:239], v[188:191], v[86:89]
	v_mfma_f32_16x16x32_bf16 v[82:85], v[244:247], v[188:191], v[82:85]
	v_mfma_f32_16x16x32_bf16 v[78:81], v[236:239], v[196:199], v[78:81]
	v_mfma_f32_16x16x32_bf16 v[74:77], v[244:247], v[196:199], v[74:77]
	v_mfma_f32_16x16x32_bf16 v[70:73], v[236:239], v[222:225], v[70:73]
	v_mfma_f32_16x16x32_bf16 v[66:69], v[244:247], v[222:225], v[66:69]
	v_mfma_f32_16x16x32_bf16 v[94:97], v[240:243], v[184:187], v[94:97]
	v_mfma_f32_16x16x32_bf16 v[90:93], v[248:251], v[184:187], v[90:93]
	v_mfma_f32_16x16x32_bf16 v[86:89], v[240:243], v[192:195], v[86:89]
	v_mfma_f32_16x16x32_bf16 v[82:85], v[248:251], v[192:195], v[82:85]
	v_mfma_f32_16x16x32_bf16 v[78:81], v[240:243], v[200:203], v[78:81]
	v_mfma_f32_16x16x32_bf16 v[74:77], v[248:251], v[200:203], v[74:77]
	v_mfma_f32_16x16x32_bf16 v[70:73], v[240:243], v[232:235], v[70:73]
	v_mfma_f32_16x16x32_bf16 v[66:69], v[248:251], v[232:235], v[66:69]
	s_setprio 0
	v_lshl_add_u64 v[228:229], v[204:205], 0, s[74:75]
	s_mov_b32 m0, s1
	s_barrier
	ds_read_b128 v[180:183], v0 offset:16384
	ds_read_b128 v[184:187], v0 offset:17408
	ds_read_b128 v[188:191], v0 offset:18432
	ds_read_b128 v[192:195], v0 offset:19456
	ds_read_b128 v[196:199], v0 offset:20480
	ds_read_b128 v[200:203], v0 offset:21504
	ds_read_b128 v[222:225], v0 offset:22528
	ds_read_b128 v[232:235], v0 offset:23552
	global_load_lds_dwordx4 v[228:229], off
	v_lshl_add_u64 v[228:229], v[210:211], 0, s[74:75]
	s_add_i32 m0, s1, 0x2000
	s_nop 0
	global_load_lds_dwordx4 v[228:229], off
	s_barrier
	s_waitcnt lgkmcnt(0)
	s_setprio 1
	s_waitcnt lgkmcnt(0)
	v_mfma_f32_16x16x32_bf16 v[62:65], v[164:167], v[180:183], v[62:65]
	v_mfma_f32_16x16x32_bf16 v[58:61], v[172:175], v[180:183], v[58:61]
	v_mfma_f32_16x16x32_bf16 v[54:57], v[164:167], v[188:191], v[54:57]
	v_mfma_f32_16x16x32_bf16 v[50:53], v[172:175], v[188:191], v[50:53]
	v_mfma_f32_16x16x32_bf16 v[46:49], v[164:167], v[196:199], v[46:49]
	v_mfma_f32_16x16x32_bf16 v[42:45], v[172:175], v[196:199], v[42:45]
	v_mfma_f32_16x16x32_bf16 v[38:41], v[164:167], v[222:225], v[38:41]
	v_mfma_f32_16x16x32_bf16 v[34:37], v[172:175], v[222:225], v[34:37]
	v_mfma_f32_16x16x32_bf16 v[62:65], v[168:171], v[184:187], v[62:65]
	v_mfma_f32_16x16x32_bf16 v[58:61], v[176:179], v[184:187], v[58:61]
	v_mfma_f32_16x16x32_bf16 v[54:57], v[168:171], v[192:195], v[54:57]
	v_mfma_f32_16x16x32_bf16 v[50:53], v[176:179], v[192:195], v[50:53]
	v_mfma_f32_16x16x32_bf16 v[46:49], v[168:171], v[200:203], v[46:49]
	v_mfma_f32_16x16x32_bf16 v[42:45], v[176:179], v[200:203], v[42:45]
	v_mfma_f32_16x16x32_bf16 v[38:41], v[168:171], v[232:235], v[38:41]
	v_mfma_f32_16x16x32_bf16 v[34:37], v[176:179], v[232:235], v[34:37]
	s_setprio 0
	s_barrier
	v_lshl_add_u64 v[164:165], v[216:217], 0, s[18:19]
	s_add_i32 m0, s1, 0x14000
	global_load_lds_dwordx4 v[164:165], off
	v_lshl_add_u64 v[164:165], v[218:219], 0, s[18:19]
	s_add_i32 m0, s1, 0x16000
	s_nop 0
	global_load_lds_dwordx4 v[164:165], off
	s_waitcnt vmcnt(6)
	s_barrier
	s_setprio 1
	v_mfma_f32_16x16x32_bf16 v[30:33], v[236:239], v[180:183], v[30:33]
	v_mfma_f32_16x16x32_bf16 v[26:29], v[244:247], v[180:183], v[26:29]
	v_mfma_f32_16x16x32_bf16 v[22:25], v[236:239], v[188:191], v[22:25]
	v_mfma_f32_16x16x32_bf16 v[18:21], v[244:247], v[188:191], v[18:21]
	v_mfma_f32_16x16x32_bf16 v[14:17], v[236:239], v[196:199], v[14:17]
	v_mfma_f32_16x16x32_bf16 v[10:13], v[244:247], v[196:199], v[10:13]
	v_mfma_f32_16x16x32_bf16 v[6:9], v[236:239], v[222:225], v[6:9]
	v_mfma_f32_16x16x32_bf16 v[2:5], v[244:247], v[222:225], v[2:5]
	v_mfma_f32_16x16x32_bf16 v[30:33], v[240:243], v[184:187], v[30:33]
	v_mfma_f32_16x16x32_bf16 v[26:29], v[248:251], v[184:187], v[26:29]
	v_mfma_f32_16x16x32_bf16 v[22:25], v[240:243], v[192:195], v[22:25]
	v_mfma_f32_16x16x32_bf16 v[18:21], v[248:251], v[192:195], v[18:21]
	v_mfma_f32_16x16x32_bf16 v[14:17], v[240:243], v[200:203], v[14:17]
	v_mfma_f32_16x16x32_bf16 v[10:13], v[248:251], v[200:203], v[10:13]
	v_mfma_f32_16x16x32_bf16 v[6:9], v[240:243], v[232:235], v[6:9]
	v_mfma_f32_16x16x32_bf16 v[2:5], v[248:251], v[232:235], v[2:5]
	s_setprio 0
	s_barrier
	ds_read_b128 v[164:167], v151 offset:32768
	ds_read_b128 v[168:171], v151 offset:33792
	ds_read_b128 v[172:175], v151 offset:34816
	ds_read_b128 v[176:179], v151 offset:35840
	v_lshl_add_u64 v[228:229], v[204:205], 0, s[18:19]
	s_add_i32 m0, s1, 0x4000
	ds_read_b128 v[180:183], v0 offset:32768
	ds_read_b128 v[184:187], v0 offset:33792
	ds_read_b128 v[188:191], v0 offset:34816
	ds_read_b128 v[192:195], v0 offset:35840
	ds_read_b128 v[196:199], v0 offset:36864
	ds_read_b128 v[200:203], v0 offset:37888
	ds_read_b128 v[222:225], v0 offset:38912
	ds_read_b128 v[232:235], v0 offset:39936
	global_load_lds_dwordx4 v[228:229], off
	v_lshl_add_u64 v[228:229], v[210:211], 0, s[18:19]
	s_add_i32 m0, s1, 0x6000
	s_nop 0
	global_load_lds_dwordx4 v[228:229], off
	s_waitcnt lgkmcnt(8)
	s_barrier
	s_waitcnt lgkmcnt(0)
	s_setprio 1
	s_waitcnt lgkmcnt(0)
	v_mfma_f32_16x16x32_bf16 v[126:129], v[164:167], v[180:183], v[126:129]
	v_mfma_f32_16x16x32_bf16 v[122:125], v[172:175], v[180:183], v[122:125]
	v_mfma_f32_16x16x32_bf16 v[118:121], v[164:167], v[188:191], v[118:121]
	v_mfma_f32_16x16x32_bf16 v[114:117], v[172:175], v[188:191], v[114:117]
	v_mfma_f32_16x16x32_bf16 v[110:113], v[164:167], v[196:199], v[110:113]
	v_mfma_f32_16x16x32_bf16 v[106:109], v[172:175], v[196:199], v[106:109]
	v_mfma_f32_16x16x32_bf16 v[102:105], v[164:167], v[222:225], v[102:105]
	v_mfma_f32_16x16x32_bf16 v[98:101], v[172:175], v[222:225], v[98:101]
	v_mfma_f32_16x16x32_bf16 v[126:129], v[168:171], v[184:187], v[126:129]
	v_mfma_f32_16x16x32_bf16 v[122:125], v[176:179], v[184:187], v[122:125]
	v_mfma_f32_16x16x32_bf16 v[118:121], v[168:171], v[192:195], v[118:121]
	v_mfma_f32_16x16x32_bf16 v[114:117], v[176:179], v[192:195], v[114:117]
	v_mfma_f32_16x16x32_bf16 v[110:113], v[168:171], v[200:203], v[110:113]
	v_mfma_f32_16x16x32_bf16 v[106:109], v[176:179], v[200:203], v[106:109]
	v_mfma_f32_16x16x32_bf16 v[102:105], v[168:171], v[232:235], v[102:105]
	v_mfma_f32_16x16x32_bf16 v[98:101], v[176:179], v[232:235], v[98:101]
	s_setprio 0
	s_barrier
	v_lshl_add_u64 v[228:229], v[216:217], 0, s[28:29]
	s_add_i32 m0, s1, 0x18000
	ds_read_b128 v[236:239], v151 offset:49152
	ds_read_b128 v[240:243], v151 offset:50176
	ds_read_b128 v[244:247], v151 offset:51200
	ds_read_b128 v[248:251], v151 offset:52224
	global_load_lds_dwordx4 v[228:229], off
	v_lshl_add_u64 v[228:229], v[218:219], 0, s[28:29]
	s_add_i32 m0, s1, 0x1a000
	s_nop 0
	global_load_lds_dwordx4 v[228:229], off
	s_barrier
	s_waitcnt lgkmcnt(0)
	s_setprio 1
	s_waitcnt lgkmcnt(0)
	v_mfma_f32_16x16x32_bf16 v[94:97], v[236:239], v[180:183], v[94:97]
	v_mfma_f32_16x16x32_bf16 v[90:93], v[244:247], v[180:183], v[90:93]
	v_mfma_f32_16x16x32_bf16 v[86:89], v[236:239], v[188:191], v[86:89]
	v_mfma_f32_16x16x32_bf16 v[82:85], v[244:247], v[188:191], v[82:85]
	v_mfma_f32_16x16x32_bf16 v[78:81], v[236:239], v[196:199], v[78:81]
	v_mfma_f32_16x16x32_bf16 v[74:77], v[244:247], v[196:199], v[74:77]
	v_mfma_f32_16x16x32_bf16 v[70:73], v[236:239], v[222:225], v[70:73]
	v_mfma_f32_16x16x32_bf16 v[66:69], v[244:247], v[222:225], v[66:69]
	v_mfma_f32_16x16x32_bf16 v[94:97], v[240:243], v[184:187], v[94:97]
	v_mfma_f32_16x16x32_bf16 v[90:93], v[248:251], v[184:187], v[90:93]
	v_mfma_f32_16x16x32_bf16 v[86:89], v[240:243], v[192:195], v[86:89]
	v_mfma_f32_16x16x32_bf16 v[82:85], v[248:251], v[192:195], v[82:85]
	v_mfma_f32_16x16x32_bf16 v[78:81], v[240:243], v[200:203], v[78:81]
	v_mfma_f32_16x16x32_bf16 v[74:77], v[248:251], v[200:203], v[74:77]
	v_mfma_f32_16x16x32_bf16 v[70:73], v[240:243], v[232:235], v[70:73]
	v_mfma_f32_16x16x32_bf16 v[66:69], v[248:251], v[232:235], v[66:69]
	s_setprio 0
	v_lshl_add_u64 v[204:205], v[204:205], 0, s[28:29]
	s_add_i32 m0, s1, 0x8000
	s_barrier
	ds_read_b128 v[180:183], v0 offset:49152
	ds_read_b128 v[184:187], v0 offset:50176
	ds_read_b128 v[188:191], v0 offset:51200
	ds_read_b128 v[192:195], v0 offset:52224
	ds_read_b128 v[196:199], v0 offset:53248
	ds_read_b128 v[200:203], v0 offset:54272
	ds_read_b128 v[222:225], v0 offset:55296
	ds_read_b128 v[232:235], v0 offset:56320
	global_load_lds_dwordx4 v[204:205], off
	v_lshl_add_u64 v[204:205], v[210:211], 0, s[28:29]
	s_add_i32 m0, s1, 0xa000
	s_nop 0
	global_load_lds_dwordx4 v[204:205], off
	s_barrier
	s_waitcnt lgkmcnt(0)
	s_setprio 1
	s_waitcnt lgkmcnt(0)
	v_mfma_f32_16x16x32_bf16 v[62:65], v[164:167], v[180:183], v[62:65]
	v_mfma_f32_16x16x32_bf16 v[58:61], v[172:175], v[180:183], v[58:61]
	v_mfma_f32_16x16x32_bf16 v[54:57], v[164:167], v[188:191], v[54:57]
	v_mfma_f32_16x16x32_bf16 v[50:53], v[172:175], v[188:191], v[50:53]
	v_mfma_f32_16x16x32_bf16 v[46:49], v[164:167], v[196:199], v[46:49]
	v_mfma_f32_16x16x32_bf16 v[42:45], v[172:175], v[196:199], v[42:45]
	v_mfma_f32_16x16x32_bf16 v[38:41], v[164:167], v[222:225], v[38:41]
	v_mfma_f32_16x16x32_bf16 v[34:37], v[172:175], v[222:225], v[34:37]
	v_mfma_f32_16x16x32_bf16 v[62:65], v[168:171], v[184:187], v[62:65]
	v_mfma_f32_16x16x32_bf16 v[58:61], v[176:179], v[184:187], v[58:61]
	v_mfma_f32_16x16x32_bf16 v[54:57], v[168:171], v[192:195], v[54:57]
	v_mfma_f32_16x16x32_bf16 v[50:53], v[176:179], v[192:195], v[50:53]
	v_mfma_f32_16x16x32_bf16 v[46:49], v[168:171], v[200:203], v[46:49]
	v_mfma_f32_16x16x32_bf16 v[42:45], v[176:179], v[200:203], v[42:45]
	v_mfma_f32_16x16x32_bf16 v[38:41], v[168:171], v[232:235], v[38:41]
	v_mfma_f32_16x16x32_bf16 v[34:37], v[176:179], v[232:235], v[34:37]
	s_setprio 0
	s_barrier
	v_lshl_add_u64 v[164:165], v[216:217], 0, s[30:31]
	s_add_i32 m0, s1, 0x1c000
	global_load_lds_dwordx4 v[164:165], off
	v_lshl_add_u64 v[164:165], v[218:219], 0, s[30:31]
	s_add_i32 m0, s1, 0x1e000
	s_nop 0
	global_load_lds_dwordx4 v[164:165], off
	s_waitcnt vmcnt(6)
	s_barrier
	s_setprio 1
	v_mfma_f32_16x16x32_bf16 v[30:33], v[236:239], v[180:183], v[30:33]
	v_mfma_f32_16x16x32_bf16 v[26:29], v[244:247], v[180:183], v[26:29]
	v_mfma_f32_16x16x32_bf16 v[22:25], v[236:239], v[188:191], v[22:25]
	v_mfma_f32_16x16x32_bf16 v[18:21], v[244:247], v[188:191], v[18:21]
	v_mfma_f32_16x16x32_bf16 v[14:17], v[236:239], v[196:199], v[14:17]
	v_mfma_f32_16x16x32_bf16 v[10:13], v[244:247], v[196:199], v[10:13]
	v_mfma_f32_16x16x32_bf16 v[6:9], v[236:239], v[222:225], v[6:9]
	v_mfma_f32_16x16x32_bf16 v[2:5], v[244:247], v[222:225], v[2:5]
	v_mfma_f32_16x16x32_bf16 v[30:33], v[240:243], v[184:187], v[30:33]
	v_mfma_f32_16x16x32_bf16 v[26:29], v[248:251], v[184:187], v[26:29]
	v_mfma_f32_16x16x32_bf16 v[22:25], v[240:243], v[192:195], v[22:25]
	v_mfma_f32_16x16x32_bf16 v[18:21], v[248:251], v[192:195], v[18:21]
	v_mfma_f32_16x16x32_bf16 v[14:17], v[240:243], v[200:203], v[14:17]
	v_mfma_f32_16x16x32_bf16 v[10:13], v[248:251], v[200:203], v[10:13]
	v_mfma_f32_16x16x32_bf16 v[6:9], v[240:243], v[232:235], v[6:9]
	v_mfma_f32_16x16x32_bf16 v[2:5], v[248:251], v[232:235], v[2:5]
	s_setprio 0
	s_add_i32 s0, s0, 2
	s_add_u32 s12, s12, 0x100
	s_addc_u32 s13, s13, 0
	s_cmp_lt_u32 s0, 28
	s_barrier
	s_cbranch_scc1 .LBB0_180
	s_add_i32 s1, s1, 0x1e000
	s_mov_b64 s[12:13], 0xf80
	v_readfirstlane_b32 s0, v162
	v_lshl_add_u64 v[132:133], v[132:133], 0, s[12:13]
	s_mov_b32 m0, s0
	v_readfirstlane_b32 s0, v163
	ds_read_b128 v[134:137], v151
	ds_read_b128 v[138:141], v151 offset:1024
	ds_read_b128 v[152:155], v151 offset:2048
	ds_read_b128 v[156:159], v151 offset:3072
	ds_read_b128 v[164:167], v0
	ds_read_b128 v[168:171], v0 offset:1024
	ds_read_b128 v[172:175], v0 offset:2048
	ds_read_b128 v[176:179], v0 offset:3072
	ds_read_b128 v[180:183], v0 offset:4096
	ds_read_b128 v[184:187], v0 offset:5120
	ds_read_b128 v[188:191], v0 offset:6144
	ds_read_b128 v[192:195], v0 offset:7168
	global_load_lds_dwordx4 v[132:133], off
	v_lshl_add_u64 v[130:131], v[130:131], 0, s[12:13]
	s_mov_b32 m0, s0
	s_nop 0
	global_load_lds_dwordx4 v[130:131], off
	s_barrier
	s_waitcnt lgkmcnt(0)
	s_setprio 1
	s_waitcnt lgkmcnt(0)
	v_mfma_f32_16x16x32_bf16 v[126:129], v[134:137], v[164:167], v[126:129]
	v_mfma_f32_16x16x32_bf16 v[122:125], v[152:155], v[164:167], v[122:125]
	v_mfma_f32_16x16x32_bf16 v[114:117], v[152:155], v[172:175], v[114:117]
	v_mfma_f32_16x16x32_bf16 v[106:109], v[152:155], v[180:183], v[106:109]
	v_mfma_f32_16x16x32_bf16 v[98:101], v[152:155], v[188:191], v[98:101]
	v_mfma_f32_16x16x32_bf16 v[126:129], v[138:141], v[168:171], v[126:129]
	v_mfma_f32_16x16x32_bf16 v[122:125], v[156:159], v[168:171], v[122:125]
	v_mfma_f32_16x16x32_bf16 v[118:121], v[134:137], v[172:175], v[118:121]
	v_mfma_f32_16x16x32_bf16 v[114:117], v[156:159], v[176:179], v[114:117]
	v_mfma_f32_16x16x32_bf16 v[110:113], v[134:137], v[180:183], v[110:113]
	v_mfma_f32_16x16x32_bf16 v[106:109], v[156:159], v[184:187], v[106:109]
	v_mfma_f32_16x16x32_bf16 v[102:105], v[134:137], v[188:191], v[102:105]
	v_mfma_f32_16x16x32_bf16 v[98:101], v[156:159], v[192:195], v[98:101]
	v_mfma_f32_16x16x32_bf16 v[130:133], v[138:141], v[176:179], v[118:121]
	v_mfma_f32_16x16x32_bf16 v[160:163], v[138:141], v[184:187], v[110:113]
	v_mfma_f32_16x16x32_bf16 v[196:199], v[138:141], v[192:195], v[102:105]
	s_setprio 0
	s_barrier
	s_nop 0
	ds_read_b128 v[102:105], v151 offset:16384
	ds_read_b128 v[110:113], v151 offset:17408
	ds_read_b128 v[118:121], v151 offset:18432
	ds_read_b128 v[200:203], v151 offset:19456
	s_barrier
	s_waitcnt lgkmcnt(0)
	s_setprio 1
	s_waitcnt lgkmcnt(1)
	v_mfma_f32_16x16x32_bf16 v[90:93], v[118:121], v[164:167], v[90:93]
	v_mfma_f32_16x16x32_bf16 v[82:85], v[118:121], v[172:175], v[82:85]
	v_mfma_f32_16x16x32_bf16 v[74:77], v[118:121], v[180:183], v[74:77]
	v_mfma_f32_16x16x32_bf16 v[66:69], v[118:121], v[188:191], v[66:69]
	v_mfma_f32_16x16x32_bf16 v[94:97], v[102:105], v[164:167], v[94:97]
	s_waitcnt lgkmcnt(0)
	v_mfma_f32_16x16x32_bf16 v[90:93], v[200:203], v[168:171], v[90:93]
	v_mfma_f32_16x16x32_bf16 v[86:89], v[102:105], v[172:175], v[86:89]
	v_mfma_f32_16x16x32_bf16 v[82:85], v[200:203], v[176:179], v[82:85]
	v_mfma_f32_16x16x32_bf16 v[78:81], v[102:105], v[180:183], v[78:81]
	v_mfma_f32_16x16x32_bf16 v[74:77], v[200:203], v[184:187], v[74:77]
	v_mfma_f32_16x16x32_bf16 v[70:73], v[102:105], v[188:191], v[70:73]
	v_mfma_f32_16x16x32_bf16 v[66:69], v[200:203], v[192:195], v[66:69]
	v_mfma_f32_16x16x32_bf16 v[222:225], v[110:113], v[168:171], v[94:97]
	v_mfma_f32_16x16x32_bf16 v[164:167], v[110:113], v[176:179], v[86:89]
	v_mfma_f32_16x16x32_bf16 v[168:171], v[110:113], v[184:187], v[78:81]
	v_mfma_f32_16x16x32_bf16 v[172:175], v[110:113], v[192:195], v[70:73]
	s_setprio 0
	s_barrier
	s_nop 0
	ds_read_b128 v[70:73], v0 offset:16384
	ds_read_b128 v[78:81], v0 offset:17408
	ds_read_b128 v[86:89], v0 offset:18432
	ds_read_b128 v[94:97], v0 offset:19456
	ds_read_b128 v[176:179], v0 offset:20480
	ds_read_b128 v[180:183], v0 offset:21504
	ds_read_b128 v[184:187], v0 offset:22528
	ds_read_b128 v[188:191], v0 offset:23552
	s_waitcnt vmcnt(4)
	s_barrier
	s_waitcnt lgkmcnt(0)
	s_setprio 1
	s_waitcnt lgkmcnt(7)
	v_mfma_f32_16x16x32_bf16 v[62:65], v[134:137], v[70:73], v[62:65]
	v_mfma_f32_16x16x32_bf16 v[58:61], v[152:155], v[70:73], v[58:61]
	s_waitcnt lgkmcnt(5)
	v_mfma_f32_16x16x32_bf16 v[50:53], v[152:155], v[86:89], v[50:53]
	s_waitcnt lgkmcnt(3)
	v_mfma_f32_16x16x32_bf16 v[42:45], v[152:155], v[176:179], v[42:45]
	s_waitcnt lgkmcnt(1)
	v_mfma_f32_16x16x32_bf16 v[34:37], v[152:155], v[184:187], v[34:37]
	v_mfma_f32_16x16x32_bf16 v[62:65], v[138:141], v[78:81], v[62:65]
	v_mfma_f32_16x16x32_bf16 v[58:61], v[156:159], v[78:81], v[58:61]
	v_mfma_f32_16x16x32_bf16 v[54:57], v[134:137], v[86:89], v[54:57]
	v_mfma_f32_16x16x32_bf16 v[50:53], v[156:159], v[94:97], v[50:53]
	v_mfma_f32_16x16x32_bf16 v[46:49], v[134:137], v[176:179], v[46:49]
	v_mfma_f32_16x16x32_bf16 v[42:45], v[156:159], v[180:183], v[42:45]
	v_mfma_f32_16x16x32_bf16 v[38:41], v[134:137], v[184:187], v[38:41]
	s_waitcnt lgkmcnt(0)
	v_mfma_f32_16x16x32_bf16 v[34:37], v[156:159], v[188:191], v[34:37]
	v_mfma_f32_16x16x32_bf16 v[192:195], v[138:141], v[94:97], v[54:57]
	v_mfma_f32_16x16x32_bf16 v[232:235], v[138:141], v[180:183], v[46:49]
	v_mfma_f32_16x16x32_bf16 v[134:137], v[138:141], v[188:191], v[38:41]
	s_setprio 0
	s_setprio 1
	v_mfma_f32_16x16x32_bf16 v[26:29], v[118:121], v[70:73], v[26:29]
	v_mfma_f32_16x16x32_bf16 v[18:21], v[118:121], v[86:89], v[18:21]
	v_mfma_f32_16x16x32_bf16 v[10:13], v[118:121], v[176:179], v[10:13]
	v_mfma_f32_16x16x32_bf16 v[2:5], v[118:121], v[184:187], v[2:5]
	v_mfma_f32_16x16x32_bf16 v[30:33], v[102:105], v[70:73], v[30:33]
	v_mfma_f32_16x16x32_bf16 v[26:29], v[200:203], v[78:81], v[26:29]
	v_mfma_f32_16x16x32_bf16 v[22:25], v[102:105], v[86:89], v[22:25]
	v_mfma_f32_16x16x32_bf16 v[18:21], v[200:203], v[94:97], v[18:21]
	v_mfma_f32_16x16x32_bf16 v[14:17], v[102:105], v[176:179], v[14:17]
	v_mfma_f32_16x16x32_bf16 v[10:13], v[200:203], v[180:183], v[10:13]
	v_mfma_f32_16x16x32_bf16 v[6:9], v[102:105], v[184:187], v[6:9]
	v_mfma_f32_16x16x32_bf16 v[2:5], v[200:203], v[188:191], v[2:5]
	v_mfma_f32_16x16x32_bf16 v[138:141], v[110:113], v[78:81], v[30:33]
	v_mfma_f32_16x16x32_bf16 v[152:155], v[110:113], v[94:97], v[22:25]
	v_mfma_f32_16x16x32_bf16 v[156:159], v[110:113], v[180:183], v[14:17]
	v_mfma_f32_16x16x32_bf16 v[176:179], v[110:113], v[188:191], v[6:9]
	s_setprio 0
	s_barrier
	s_nop 0
	ds_read_b128 v[6:9], v151 offset:32768
	ds_read_b128 v[14:17], v151 offset:33792
	ds_read_b128 v[180:183], v151 offset:34816
	ds_read_b128 v[184:187], v151 offset:35840
	ds_read_b128 v[22:25], v0 offset:32768
	ds_read_b128 v[30:33], v0 offset:33792
	ds_read_b128 v[38:41], v0 offset:34816
	ds_read_b128 v[46:49], v0 offset:35840
	ds_read_b128 v[54:57], v0 offset:36864
	ds_read_b128 v[188:191], v0 offset:37888
	ds_read_b128 v[200:203], v0 offset:38912
	ds_read_b128 v[236:239], v0 offset:39936
	s_waitcnt vmcnt(2)
	s_barrier
	s_waitcnt lgkmcnt(0)
	s_setprio 1
	s_waitcnt lgkmcnt(7)
	v_mfma_f32_16x16x32_bf16 v[70:73], v[6:9], v[22:25], v[126:129]
	s_waitcnt lgkmcnt(6)
	v_mfma_f32_16x16x32_bf16 v[126:129], v[14:17], v[30:33], v[70:73]
	v_mfma_f32_16x16x32_bf16 v[70:73], v[180:183], v[22:25], v[122:125]
	v_mfma_f32_16x16x32_bf16 v[118:121], v[184:187], v[30:33], v[70:73]
	s_waitcnt lgkmcnt(5)
	v_mfma_f32_16x16x32_bf16 v[70:73], v[6:9], v[38:41], v[130:133]
	s_waitcnt lgkmcnt(4)
	v_mfma_f32_16x16x32_bf16 v[110:113], v[14:17], v[46:49], v[70:73]
	v_mfma_f32_16x16x32_bf16 v[70:73], v[180:183], v[38:41], v[114:117]
	v_mfma_f32_16x16x32_bf16 v[102:105], v[184:187], v[46:49], v[70:73]
	s_waitcnt lgkmcnt(3)
	v_mfma_f32_16x16x32_bf16 v[70:73], v[6:9], v[54:57], v[160:163]
	s_waitcnt lgkmcnt(2)
	v_mfma_f32_16x16x32_bf16 v[94:97], v[14:17], v[188:191], v[70:73]
	v_mfma_f32_16x16x32_bf16 v[70:73], v[180:183], v[54:57], v[106:109]
	v_mfma_f32_16x16x32_bf16 v[86:89], v[184:187], v[188:191], v[70:73]
	s_waitcnt lgkmcnt(1)
	v_mfma_f32_16x16x32_bf16 v[70:73], v[6:9], v[200:203], v[196:199]
	s_waitcnt lgkmcnt(0)
	v_mfma_f32_16x16x32_bf16 v[78:81], v[14:17], v[236:239], v[70:73]
	v_mfma_f32_16x16x32_bf16 v[70:73], v[180:183], v[200:203], v[98:101]
	v_mfma_f32_16x16x32_bf16 v[70:73], v[184:187], v[236:239], v[70:73]
	s_setprio 0
	s_barrier
	ds_read_b128 v[130:133], v151 offset:49152
	ds_read_b128 v[160:163], v151 offset:50176
	ds_read_b128 v[196:199], v151 offset:51200
	ds_read_b128 v[148:151], v151 offset:52224
	s_waitcnt vmcnt(0)
	s_barrier
	s_waitcnt lgkmcnt(0)
	s_setprio 1
	s_waitcnt lgkmcnt(3)
	v_mfma_f32_16x16x32_bf16 v[98:101], v[130:133], v[22:25], v[222:225]
	s_waitcnt lgkmcnt(1)
	v_mfma_f32_16x16x32_bf16 v[22:25], v[196:199], v[22:25], v[90:93]
	s_waitcnt lgkmcnt(0)
	v_mfma_f32_16x16x32_bf16 v[114:117], v[148:151], v[30:33], v[22:25]
	v_mfma_f32_16x16x32_bf16 v[22:25], v[130:133], v[38:41], v[164:167]
	v_mfma_f32_16x16x32_bf16 v[106:109], v[160:163], v[46:49], v[22:25]
	v_mfma_f32_16x16x32_bf16 v[22:25], v[196:199], v[38:41], v[82:85]
	v_mfma_f32_16x16x32_bf16 v[122:125], v[160:163], v[30:33], v[98:101]
	v_mfma_f32_16x16x32_bf16 v[98:101], v[148:151], v[46:49], v[22:25]
	v_mfma_f32_16x16x32_bf16 v[22:25], v[130:133], v[54:57], v[168:171]
	v_mfma_f32_16x16x32_bf16 v[90:93], v[160:163], v[188:191], v[22:25]
	v_mfma_f32_16x16x32_bf16 v[22:25], v[196:199], v[54:57], v[74:77]
	v_mfma_f32_16x16x32_bf16 v[82:85], v[148:151], v[188:191], v[22:25]
	v_mfma_f32_16x16x32_bf16 v[22:25], v[130:133], v[200:203], v[172:175]
	v_mfma_f32_16x16x32_bf16 v[74:77], v[160:163], v[236:239], v[22:25]
	v_mfma_f32_16x16x32_bf16 v[22:25], v[196:199], v[200:203], v[66:69]
	v_mfma_f32_16x16x32_bf16 v[66:69], v[148:151], v[236:239], v[22:25]
	s_setprio 0
	s_barrier
	ds_read_b128 v[164:167], v0 offset:49152
	ds_read_b128 v[168:171], v0 offset:50176
	ds_read_b128 v[172:175], v0 offset:51200
	ds_read_b128 v[188:191], v0 offset:52224
	ds_read_b128 v[200:203], v0 offset:53248
	ds_read_b128 v[222:225], v0 offset:54272
	ds_read_b128 v[236:239], v0 offset:55296
	ds_read_b128 v[240:243], v0 offset:56320
	s_barrier
	s_waitcnt lgkmcnt(0)
	s_setprio 1
	s_waitcnt lgkmcnt(7)
	v_mfma_f32_16x16x32_bf16 v[22:25], v[6:9], v[164:167], v[62:65]
	s_waitcnt lgkmcnt(6)
	v_mfma_f32_16x16x32_bf16 v[62:65], v[14:17], v[168:171], v[22:25]
	v_mfma_f32_16x16x32_bf16 v[22:25], v[180:183], v[164:167], v[58:61]
	v_mfma_f32_16x16x32_bf16 v[54:57], v[184:187], v[168:171], v[22:25]
	s_waitcnt lgkmcnt(5)
	v_mfma_f32_16x16x32_bf16 v[22:25], v[6:9], v[172:175], v[192:195]
	s_waitcnt lgkmcnt(4)
	v_mfma_f32_16x16x32_bf16 v[46:49], v[14:17], v[188:191], v[22:25]
	v_mfma_f32_16x16x32_bf16 v[22:25], v[180:183], v[172:175], v[50:53]
	v_mfma_f32_16x16x32_bf16 v[38:41], v[184:187], v[188:191], v[22:25]
	s_waitcnt lgkmcnt(3)
	v_mfma_f32_16x16x32_bf16 v[22:25], v[6:9], v[200:203], v[232:235]
	s_waitcnt lgkmcnt(1)
	v_mfma_f32_16x16x32_bf16 v[6:9], v[6:9], v[236:239], v[134:137]
	v_mfma_f32_16x16x32_bf16 v[30:33], v[14:17], v[222:225], v[22:25]
	v_mfma_f32_16x16x32_bf16 v[22:25], v[180:183], v[200:203], v[42:45]
	s_waitcnt lgkmcnt(0)
	v_mfma_f32_16x16x32_bf16 v[14:17], v[14:17], v[240:243], v[6:9]
	v_mfma_f32_16x16x32_bf16 v[6:9], v[180:183], v[236:239], v[34:37]
	v_mfma_f32_16x16x32_bf16 v[22:25], v[184:187], v[222:225], v[22:25]
	v_mfma_f32_16x16x32_bf16 v[6:9], v[184:187], v[240:243], v[6:9]
	s_setprio 0
	s_setprio 1
	v_mfma_f32_16x16x32_bf16 v[34:37], v[130:133], v[164:167], v[138:141]
	v_mfma_f32_16x16x32_bf16 v[26:29], v[196:199], v[164:167], v[26:29]
	v_mfma_f32_16x16x32_bf16 v[18:21], v[196:199], v[172:175], v[18:21]
	v_mfma_f32_16x16x32_bf16 v[58:61], v[160:163], v[168:171], v[34:37]
	v_mfma_f32_16x16x32_bf16 v[50:53], v[148:151], v[168:171], v[26:29]
	v_mfma_f32_16x16x32_bf16 v[26:29], v[130:133], v[172:175], v[152:155]
	v_mfma_f32_16x16x32_bf16 v[34:37], v[148:151], v[188:191], v[18:21]
	v_mfma_f32_16x16x32_bf16 v[18:21], v[130:133], v[200:203], v[156:159]
	v_mfma_f32_16x16x32_bf16 v[10:13], v[196:199], v[200:203], v[10:13]
	v_mfma_f32_16x16x32_bf16 v[42:45], v[160:163], v[188:191], v[26:29]
	v_mfma_f32_16x16x32_bf16 v[26:29], v[160:163], v[222:225], v[18:21]
	v_mfma_f32_16x16x32_bf16 v[18:21], v[148:151], v[222:225], v[10:13]
	v_mfma_f32_16x16x32_bf16 v[10:13], v[130:133], v[236:239], v[176:179]
	v_mfma_f32_16x16x32_bf16 v[2:5], v[196:199], v[236:239], v[2:5]
	v_mfma_f32_16x16x32_bf16 v[10:13], v[160:163], v[240:243], v[10:13]
	v_mfma_f32_16x16x32_bf16 v[2:5], v[148:151], v[240:243], v[2:5]
	s_setprio 0
	s_movk_i32 s0, 0x100
	v_cmp_gt_u32_e32 vcc, s0, v142
	s_barrier
	s_and_saveexec_b64 s[0:1], vcc
	s_cbranch_execz .LBB0_183
	s_barrier

.LBB0_677:
	s_or_b64 exec, exec, s[16:17]
	v_mov_b32_e32 v3, v1
	v_lshl_add_u64 v[12:13], s[0:1], 0, v[2:3]
	v_lshl_add_u64 v[16:17], s[10:11], 0, v[2:3]
	v_lshl_add_u64 v[20:21], s[12:13], 0, v[2:3]
	v_lshl_add_u64 v[130:131], s[14:15], 0, v[2:3]
	v_and_b32_e32 v146, 15, v142
	v_bfe_u32 v145, v142, 4, 2
	v_lshlrev_b32_e32 v3, 2, v142
	v_add_u32_e32 v156, 0x18000, v147
	v_lshl_add_u64 v[10:11], s[0:1], 0, v[0:1]
	v_lshl_add_u64 v[14:15], s[10:11], 0, v[0:1]
	v_lshl_add_u64 v[18:19], s[12:13], 0, v[0:1]
	v_lshl_add_u64 v[132:133], s[14:15], 0, v[0:1]
	v_lshlrev_b32_e32 v0, 6, v146
	v_lshlrev_b32_e32 v2, 4, v145
	v_and_b32_e32 v3, 32, v3
	s_mov_b64 s[10:11], 0x80
	v_readfirstlane_b32 s0, v156
	v_add_u32_e32 v157, 0x1a000, v147
	v_bitop3_b32 v22, v2, v3, v0 bitop3:0x36
	v_lshl_add_u64 v[2:3], v[10:11], 0, s[10:11]
	s_mov_b32 m0, s0
	v_readfirstlane_b32 s0, v157
	v_add_u32_e32 v158, 0x8000, v147
	s_waitcnt vmcnt(4)
	s_barrier
	global_load_lds_dwordx4 v[2:3], off
	v_lshl_add_u64 v[2:3], v[12:13], 0, s[10:11]
	s_mov_b32 m0, s0
	v_readfirstlane_b32 s0, v158
	v_add_u32_e32 v159, 0xa000, v147
	global_load_lds_dwordx4 v[2:3], off
	v_lshl_add_u64 v[2:3], v[14:15], 0, s[10:11]
	s_mov_b32 m0, s0
	v_readfirstlane_b32 s0, v159
	v_add_u32_e32 v160, 0x1c000, v147
	global_load_lds_dwordx4 v[2:3], off
	v_lshl_add_u64 v[2:3], v[16:17], 0, s[10:11]
	s_mov_b32 m0, s0
	v_readfirstlane_b32 s0, v160
	v_add_u32_e32 v161, 0x1e000, v147
	global_load_lds_dwordx4 v[2:3], off
	v_lshl_add_u64 v[2:3], v[18:19], 0, s[10:11]
	s_mov_b32 m0, s0
	v_readfirstlane_b32 s0, v161
	global_load_lds_dwordx4 v[2:3], off
	v_lshl_add_u64 v[2:3], v[20:21], 0, s[10:11]
	s_mov_b32 m0, s0
	s_sub_i32 s1, s57, s64
	global_load_lds_dwordx4 v[2:3], off
	s_sub_i32 s1, s1, s63
	v_lshlrev_b32_e32 v0, 15, v4
	s_sext_i32_i16 s1, s1
	v_and_b32_e32 v0, 0xffff0000, v0
	s_lshl_b32 s0, s62, 10
	s_lshl_b32 s1, s1, 8
	v_lshl_add_u32 v0, v5, 12, v0
	v_and_b32_e32 v2, 1, v4
	s_add_i32 s0, s0, s1
	v_lshl_or_b32 v0, v2, 6, v0
	v_lshlrev_b32_e32 v2, 15, v6
	s_ashr_i32 s1, s0, 31
	v_and_b32_e32 v2, 0xffff0000, v2
	s_lshl_b64 s[0:1], s[0:1], 12
	v_lshl_add_u32 v2, v8, 12, v2
	v_and_b32_e32 v3, 1, v6
	s_add_u32 s0, s52, s0
	v_lshl_or_b32 v2, v3, 6, v2
	v_lshl_add_u32 v0, v7, 1, v0
	s_addc_u32 s1, s53, s1
	v_lshl_add_u32 v2, v9, 1, v2
	v_mov_b32_e32 v3, v1
	v_lshl_add_u64 v[134:135], s[0:1], 0, v[0:1]
	v_lshl_add_u64 v[136:137], s[0:1], 0, v[2:3]
	s_add_u32 s0, s88, s8
	v_bfe_u32 v144, v142, 6, 2
	s_waitcnt vmcnt(6)
	s_addc_u32 s1, s89, s9
	v_lshlrev_b32_e32 v23, 13, v143
	v_lshl_or_b32 v24, v144, 12, v212
	v_lshl_add_u64 v[140:141], s[0:1], 0, v[2:3]
	v_mov_b32_e32 v2, 0
	v_lshl_add_u64 v[138:139], s[0:1], 0, v[0:1]
	s_mov_b32 s0, -2
	s_mov_b64 s[8:9], 0
	v_add_u32_e32 v151, v24, v22
	v_add_u32_e32 v0, v23, v22
	v_mov_b32_e32 v3, v2
	v_mov_b32_e32 v4, v2
	v_mov_b32_e32 v5, v2
	v_mov_b32_e32 v6, v2
	v_mov_b32_e32 v7, v2
	v_mov_b32_e32 v8, v2
	v_mov_b32_e32 v9, v2
	v_mov_b32_e32 v10, v2
	v_mov_b32_e32 v11, v2
	v_mov_b32_e32 v12, v2
	v_mov_b32_e32 v13, v2
	v_mov_b32_e32 v14, v2
	v_mov_b32_e32 v15, v2
	v_mov_b32_e32 v16, v2
	v_mov_b32_e32 v17, v2
	v_mov_b32_e32 v18, v2
	v_mov_b32_e32 v19, v2
	v_mov_b32_e32 v20, v2
	v_mov_b32_e32 v21, v2
	v_mov_b32_e32 v22, v2
	v_mov_b32_e32 v23, v2
	v_mov_b32_e32 v24, v2
	v_mov_b32_e32 v25, v2
	v_mov_b32_e32 v26, v2
	v_mov_b32_e32 v27, v2
	v_mov_b32_e32 v28, v2
	v_mov_b32_e32 v29, v2
	v_mov_b32_e32 v30, v2
	v_mov_b32_e32 v31, v2
	v_mov_b32_e32 v32, v2
	v_mov_b32_e32 v33, v2
	v_mov_b32_e32 v34, v2
	v_mov_b32_e32 v35, v2
	v_mov_b32_e32 v36, v2
	v_mov_b32_e32 v37, v2
	v_mov_b32_e32 v38, v2
	v_mov_b32_e32 v39, v2
	v_mov_b32_e32 v40, v2
	v_mov_b32_e32 v41, v2
	v_mov_b32_e32 v42, v2
	v_mov_b32_e32 v43, v2
	v_mov_b32_e32 v44, v2
	v_mov_b32_e32 v45, v2
	v_mov_b32_e32 v46, v2
	v_mov_b32_e32 v47, v2
	v_mov_b32_e32 v48, v2
	v_mov_b32_e32 v49, v2
	v_mov_b32_e32 v50, v2
	v_mov_b32_e32 v51, v2
	v_mov_b32_e32 v52, v2
	v_mov_b32_e32 v53, v2
	v_mov_b32_e32 v54, v2
	v_mov_b32_e32 v55, v2
	v_mov_b32_e32 v56, v2
	v_mov_b32_e32 v57, v2
	v_mov_b32_e32 v58, v2
	v_mov_b32_e32 v59, v2
	v_mov_b32_e32 v60, v2
	v_mov_b32_e32 v61, v2
	v_mov_b32_e32 v62, v2
	v_mov_b32_e32 v63, v2
	v_mov_b32_e32 v64, v2
	v_mov_b32_e32 v65, v2
	v_mov_b32_e32 v66, v2
	v_mov_b32_e32 v67, v2
	v_mov_b32_e32 v68, v2
	v_mov_b32_e32 v69, v2
	v_mov_b32_e32 v70, v2
	v_mov_b32_e32 v71, v2
	v_mov_b32_e32 v72, v2
	v_mov_b32_e32 v73, v2
	v_mov_b32_e32 v74, v2
	v_mov_b32_e32 v75, v2
	v_mov_b32_e32 v76, v2
	v_mov_b32_e32 v77, v2
	v_mov_b32_e32 v78, v2
	v_mov_b32_e32 v79, v2
	v_mov_b32_e32 v80, v2
	v_mov_b32_e32 v81, v2
	v_mov_b32_e32 v82, v2
	v_mov_b32_e32 v83, v2
	v_mov_b32_e32 v84, v2
	v_mov_b32_e32 v85, v2
	v_mov_b32_e32 v86, v2
	v_mov_b32_e32 v87, v2
	v_mov_b32_e32 v88, v2
	v_mov_b32_e32 v89, v2
	v_mov_b32_e32 v90, v2
	v_mov_b32_e32 v91, v2
	v_mov_b32_e32 v92, v2
	v_mov_b32_e32 v93, v2
	v_mov_b32_e32 v94, v2
	v_mov_b32_e32 v95, v2
	v_mov_b32_e32 v96, v2
	v_mov_b32_e32 v97, v2
	v_mov_b32_e32 v98, v2
	v_mov_b32_e32 v99, v2
	v_mov_b32_e32 v100, v2
	v_mov_b32_e32 v101, v2
	v_mov_b32_e32 v102, v2
	v_mov_b32_e32 v103, v2
	v_mov_b32_e32 v104, v2
	v_mov_b32_e32 v105, v2
	v_mov_b32_e32 v106, v2
	v_mov_b32_e32 v107, v2
	v_mov_b32_e32 v108, v2
	v_mov_b32_e32 v109, v2
	v_mov_b32_e32 v110, v2
	v_mov_b32_e32 v111, v2
	v_mov_b32_e32 v112, v2
	v_mov_b32_e32 v113, v2
	v_mov_b32_e32 v114, v2
	v_mov_b32_e32 v115, v2
	v_mov_b32_e32 v116, v2
	v_mov_b32_e32 v117, v2
	v_mov_b32_e32 v118, v2
	v_mov_b32_e32 v119, v2
	v_mov_b32_e32 v120, v2
	v_mov_b32_e32 v121, v2
	v_mov_b32_e32 v122, v2
	v_mov_b32_e32 v123, v2
	v_mov_b32_e32 v124, v2
	v_mov_b32_e32 v125, v2
	v_mov_b32_e32 v126, v2
	v_mov_b32_e32 v127, v2
	v_mov_b32_e32 v128, v2
	v_mov_b32_e32 v129, v2
	s_barrier
	v_readfirstlane_b32 s1, v147
	s_nop 1
.LBB0_678:
	ds_read_b128 v[164:167], v151
	ds_read_b128 v[168:171], v151 offset:1024
	ds_read_b128 v[172:175], v151 offset:2048
	ds_read_b128 v[176:179], v151 offset:3072
	v_add_u32_e32 v162, 0xc000, v147
	v_lshl_add_u64 v[204:205], v[138:139], 0, s[8:9]
	v_add_u32_e32 v163, 0xe000, v147
	v_lshl_add_u64 v[222:223], v[204:205], 0, s[60:61]
	s_add_i32 m0, s1, 0xc000
	v_lshl_add_u64 v[216:217], v[140:141], 0, s[8:9]
	ds_read_b128 v[180:183], v0
	ds_read_b128 v[184:187], v0 offset:1024
	ds_read_b128 v[188:191], v0 offset:2048
	ds_read_b128 v[192:195], v0 offset:3072
	ds_read_b128 v[196:199], v0 offset:4096
	ds_read_b128 v[200:203], v0 offset:5120
	ds_read_b128 v[232:235], v0 offset:6144
	ds_read_b128 v[236:239], v0 offset:7168
	global_load_lds_dwordx4 v[222:223], off
	v_lshl_add_u64 v[222:223], v[216:217], 0, s[60:61]
	s_add_i32 m0, s1, 0xe000
	s_nop 0
	global_load_lds_dwordx4 v[222:223], off
	s_waitcnt lgkmcnt(8)
	s_barrier
	s_waitcnt lgkmcnt(0)
	s_setprio 1
	s_waitcnt lgkmcnt(0)
	v_mfma_f32_16x16x32_bf16 v[126:129], v[164:167], v[180:183], v[126:129]
	v_mfma_f32_16x16x32_bf16 v[122:125], v[172:175], v[180:183], v[122:125]
	v_mfma_f32_16x16x32_bf16 v[118:121], v[164:167], v[188:191], v[118:121]
	v_mfma_f32_16x16x32_bf16 v[114:117], v[172:175], v[188:191], v[114:117]
	v_mfma_f32_16x16x32_bf16 v[110:113], v[164:167], v[196:199], v[110:113]
	v_mfma_f32_16x16x32_bf16 v[106:109], v[172:175], v[196:199], v[106:109]
	v_mfma_f32_16x16x32_bf16 v[102:105], v[164:167], v[232:235], v[102:105]
	v_mfma_f32_16x16x32_bf16 v[98:101], v[172:175], v[232:235], v[98:101]
	v_mfma_f32_16x16x32_bf16 v[126:129], v[168:171], v[184:187], v[126:129]
	v_mfma_f32_16x16x32_bf16 v[122:125], v[176:179], v[184:187], v[122:125]
	v_mfma_f32_16x16x32_bf16 v[118:121], v[168:171], v[192:195], v[118:121]
	v_mfma_f32_16x16x32_bf16 v[114:117], v[176:179], v[192:195], v[114:117]
	v_mfma_f32_16x16x32_bf16 v[110:113], v[168:171], v[200:203], v[110:113]
	v_mfma_f32_16x16x32_bf16 v[106:109], v[176:179], v[200:203], v[106:109]
	v_mfma_f32_16x16x32_bf16 v[102:105], v[168:171], v[236:239], v[102:105]
	v_mfma_f32_16x16x32_bf16 v[98:101], v[176:179], v[236:239], v[98:101]
	s_setprio 0
	s_barrier
	v_lshl_add_u64 v[210:211], v[134:135], 0, s[8:9]
	v_lshl_add_u64 v[228:229], v[210:211], 0, s[74:75]
	s_add_i32 m0, s1, 0x10000
	ds_read_b128 v[240:243], v151 offset:16384
	ds_read_b128 v[244:247], v151 offset:17408
	ds_read_b128 v[248:251], v151 offset:18432
	ds_read_b128 v[222:225], v151 offset:19456
	global_load_lds_dwordx4 v[228:229], off
	v_lshl_add_u64 v[228:229], v[136:137], 0, s[8:9]
	v_lshl_add_u64 v[218:219], v[228:229], 0, s[74:75]
	s_add_i32 m0, s1, 0x12000
	s_nop 0
	global_load_lds_dwordx4 v[218:219], off
	s_barrier
	s_waitcnt lgkmcnt(0)
	s_setprio 1
	s_waitcnt lgkmcnt(0)
	v_mfma_f32_16x16x32_bf16 v[94:97], v[240:243], v[180:183], v[94:97]
	v_mfma_f32_16x16x32_bf16 v[90:93], v[248:251], v[180:183], v[90:93]
	v_mfma_f32_16x16x32_bf16 v[86:89], v[240:243], v[188:191], v[86:89]
	v_mfma_f32_16x16x32_bf16 v[82:85], v[248:251], v[188:191], v[82:85]
	v_mfma_f32_16x16x32_bf16 v[78:81], v[240:243], v[196:199], v[78:81]
	v_mfma_f32_16x16x32_bf16 v[74:77], v[248:251], v[196:199], v[74:77]
	v_mfma_f32_16x16x32_bf16 v[70:73], v[240:243], v[232:235], v[70:73]
	v_mfma_f32_16x16x32_bf16 v[66:69], v[248:251], v[232:235], v[66:69]
	v_mfma_f32_16x16x32_bf16 v[94:97], v[244:247], v[184:187], v[94:97]
	v_mfma_f32_16x16x32_bf16 v[90:93], v[222:225], v[184:187], v[90:93]
	v_mfma_f32_16x16x32_bf16 v[86:89], v[244:247], v[192:195], v[86:89]
	v_mfma_f32_16x16x32_bf16 v[82:85], v[222:225], v[192:195], v[82:85]
	v_mfma_f32_16x16x32_bf16 v[78:81], v[244:247], v[200:203], v[78:81]
	v_mfma_f32_16x16x32_bf16 v[74:77], v[222:225], v[200:203], v[74:77]
	v_mfma_f32_16x16x32_bf16 v[70:73], v[244:247], v[236:239], v[70:73]
	v_mfma_f32_16x16x32_bf16 v[66:69], v[222:225], v[236:239], v[66:69]
	s_setprio 0
	v_lshl_add_u64 v[218:219], v[204:205], 0, s[74:75]
	s_mov_b32 m0, s1
	s_barrier
	ds_read_b128 v[180:183], v0 offset:16384
	ds_read_b128 v[184:187], v0 offset:17408
	ds_read_b128 v[188:191], v0 offset:18432
	ds_read_b128 v[192:195], v0 offset:19456
	ds_read_b128 v[196:199], v0 offset:20480
	ds_read_b128 v[200:203], v0 offset:21504
	ds_read_b128 v[232:235], v0 offset:22528
	ds_read_b128 v[236:239], v0 offset:23552
	global_load_lds_dwordx4 v[218:219], off
	v_lshl_add_u64 v[218:219], v[216:217], 0, s[74:75]
	s_add_i32 m0, s1, 0x2000
	s_nop 0
	global_load_lds_dwordx4 v[218:219], off
	s_barrier
	s_waitcnt lgkmcnt(0)
	s_setprio 1
	s_waitcnt lgkmcnt(0)
	v_mfma_f32_16x16x32_bf16 v[62:65], v[164:167], v[180:183], v[62:65]
	v_mfma_f32_16x16x32_bf16 v[58:61], v[172:175], v[180:183], v[58:61]
	v_mfma_f32_16x16x32_bf16 v[54:57], v[164:167], v[188:191], v[54:57]
	v_mfma_f32_16x16x32_bf16 v[50:53], v[172:175], v[188:191], v[50:53]
	v_mfma_f32_16x16x32_bf16 v[46:49], v[164:167], v[196:199], v[46:49]
	v_mfma_f32_16x16x32_bf16 v[42:45], v[172:175], v[196:199], v[42:45]
	v_mfma_f32_16x16x32_bf16 v[38:41], v[164:167], v[232:235], v[38:41]
	v_mfma_f32_16x16x32_bf16 v[34:37], v[172:175], v[232:235], v[34:37]
	v_mfma_f32_16x16x32_bf16 v[62:65], v[168:171], v[184:187], v[62:65]
	v_mfma_f32_16x16x32_bf16 v[58:61], v[176:179], v[184:187], v[58:61]
	v_mfma_f32_16x16x32_bf16 v[54:57], v[168:171], v[192:195], v[54:57]
	v_mfma_f32_16x16x32_bf16 v[50:53], v[176:179], v[192:195], v[50:53]
	v_mfma_f32_16x16x32_bf16 v[46:49], v[168:171], v[200:203], v[46:49]
	v_mfma_f32_16x16x32_bf16 v[42:45], v[176:179], v[200:203], v[42:45]
	v_mfma_f32_16x16x32_bf16 v[38:41], v[168:171], v[236:239], v[38:41]
	v_mfma_f32_16x16x32_bf16 v[34:37], v[176:179], v[236:239], v[34:37]
	s_setprio 0
	s_barrier
	v_lshl_add_u64 v[164:165], v[210:211], 0, s[18:19]
	s_add_i32 m0, s1, 0x14000
	global_load_lds_dwordx4 v[164:165], off
	v_lshl_add_u64 v[164:165], v[228:229], 0, s[18:19]
	s_add_i32 m0, s1, 0x16000
	s_nop 0
	global_load_lds_dwordx4 v[164:165], off
	s_waitcnt vmcnt(6)
	s_barrier
	s_setprio 1
	v_mfma_f32_16x16x32_bf16 v[30:33], v[240:243], v[180:183], v[30:33]
	v_mfma_f32_16x16x32_bf16 v[26:29], v[248:251], v[180:183], v[26:29]
	v_mfma_f32_16x16x32_bf16 v[22:25], v[240:243], v[188:191], v[22:25]
	v_mfma_f32_16x16x32_bf16 v[18:21], v[248:251], v[188:191], v[18:21]
	v_mfma_f32_16x16x32_bf16 v[14:17], v[240:243], v[196:199], v[14:17]
	v_mfma_f32_16x16x32_bf16 v[10:13], v[248:251], v[196:199], v[10:13]
	v_mfma_f32_16x16x32_bf16 v[6:9], v[240:243], v[232:235], v[6:9]
	v_mfma_f32_16x16x32_bf16 v[2:5], v[248:251], v[232:235], v[2:5]
	v_mfma_f32_16x16x32_bf16 v[30:33], v[244:247], v[184:187], v[30:33]
	v_mfma_f32_16x16x32_bf16 v[26:29], v[222:225], v[184:187], v[26:29]
	v_mfma_f32_16x16x32_bf16 v[22:25], v[244:247], v[192:195], v[22:25]
	v_mfma_f32_16x16x32_bf16 v[18:21], v[222:225], v[192:195], v[18:21]
	v_mfma_f32_16x16x32_bf16 v[14:17], v[244:247], v[200:203], v[14:17]
	v_mfma_f32_16x16x32_bf16 v[10:13], v[222:225], v[200:203], v[10:13]
	v_mfma_f32_16x16x32_bf16 v[6:9], v[244:247], v[236:239], v[6:9]
	v_mfma_f32_16x16x32_bf16 v[2:5], v[222:225], v[236:239], v[2:5]
	s_setprio 0
	s_barrier
	ds_read_b128 v[164:167], v151 offset:32768
	ds_read_b128 v[168:171], v151 offset:33792
	ds_read_b128 v[172:175], v151 offset:34816
	ds_read_b128 v[176:179], v151 offset:35840
	v_lshl_add_u64 v[218:219], v[204:205], 0, s[18:19]
	s_add_i32 m0, s1, 0x4000
	ds_read_b128 v[180:183], v0 offset:32768
	ds_read_b128 v[184:187], v0 offset:33792
	ds_read_b128 v[188:191], v0 offset:34816
	ds_read_b128 v[192:195], v0 offset:35840
	ds_read_b128 v[196:199], v0 offset:36864
	ds_read_b128 v[200:203], v0 offset:37888
	ds_read_b128 v[222:225], v0 offset:38912
	ds_read_b128 v[232:235], v0 offset:39936
	global_load_lds_dwordx4 v[218:219], off
	v_lshl_add_u64 v[218:219], v[216:217], 0, s[18:19]
	s_add_i32 m0, s1, 0x6000
	s_nop 0
	global_load_lds_dwordx4 v[218:219], off
	s_waitcnt lgkmcnt(8)
	s_barrier
	s_waitcnt lgkmcnt(0)
	s_setprio 1
	s_waitcnt lgkmcnt(0)
	v_mfma_f32_16x16x32_bf16 v[126:129], v[164:167], v[180:183], v[126:129]
	v_mfma_f32_16x16x32_bf16 v[122:125], v[172:175], v[180:183], v[122:125]
	v_mfma_f32_16x16x32_bf16 v[118:121], v[164:167], v[188:191], v[118:121]
	v_mfma_f32_16x16x32_bf16 v[114:117], v[172:175], v[188:191], v[114:117]
	v_mfma_f32_16x16x32_bf16 v[110:113], v[164:167], v[196:199], v[110:113]
	v_mfma_f32_16x16x32_bf16 v[106:109], v[172:175], v[196:199], v[106:109]
	v_mfma_f32_16x16x32_bf16 v[102:105], v[164:167], v[222:225], v[102:105]
	v_mfma_f32_16x16x32_bf16 v[98:101], v[172:175], v[222:225], v[98:101]
	v_mfma_f32_16x16x32_bf16 v[126:129], v[168:171], v[184:187], v[126:129]
	v_mfma_f32_16x16x32_bf16 v[122:125], v[176:179], v[184:187], v[122:125]
	v_mfma_f32_16x16x32_bf16 v[118:121], v[168:171], v[192:195], v[118:121]
	v_mfma_f32_16x16x32_bf16 v[114:117], v[176:179], v[192:195], v[114:117]
	v_mfma_f32_16x16x32_bf16 v[110:113], v[168:171], v[200:203], v[110:113]
	v_mfma_f32_16x16x32_bf16 v[106:109], v[176:179], v[200:203], v[106:109]
	v_mfma_f32_16x16x32_bf16 v[102:105], v[168:171], v[232:235], v[102:105]
	v_mfma_f32_16x16x32_bf16 v[98:101], v[176:179], v[232:235], v[98:101]
	s_setprio 0
	s_barrier
	v_lshl_add_u64 v[218:219], v[210:211], 0, s[28:29]
	s_add_i32 m0, s1, 0x18000
	ds_read_b128 v[236:239], v151 offset:49152
	ds_read_b128 v[240:243], v151 offset:50176
	ds_read_b128 v[244:247], v151 offset:51200
	ds_read_b128 v[248:251], v151 offset:52224
	global_load_lds_dwordx4 v[218:219], off
	v_lshl_add_u64 v[218:219], v[228:229], 0, s[28:29]
	s_add_i32 m0, s1, 0x1a000
	s_nop 0
	global_load_lds_dwordx4 v[218:219], off
	s_barrier
	s_waitcnt lgkmcnt(0)
	s_setprio 1
	s_waitcnt lgkmcnt(0)
	v_mfma_f32_16x16x32_bf16 v[94:97], v[236:239], v[180:183], v[94:97]
	v_mfma_f32_16x16x32_bf16 v[90:93], v[244:247], v[180:183], v[90:93]
	v_mfma_f32_16x16x32_bf16 v[86:89], v[236:239], v[188:191], v[86:89]
	v_mfma_f32_16x16x32_bf16 v[82:85], v[244:247], v[188:191], v[82:85]
	v_mfma_f32_16x16x32_bf16 v[78:81], v[236:239], v[196:199], v[78:81]
	v_mfma_f32_16x16x32_bf16 v[74:77], v[244:247], v[196:199], v[74:77]
	v_mfma_f32_16x16x32_bf16 v[70:73], v[236:239], v[222:225], v[70:73]
	v_mfma_f32_16x16x32_bf16 v[66:69], v[244:247], v[222:225], v[66:69]
	v_mfma_f32_16x16x32_bf16 v[94:97], v[240:243], v[184:187], v[94:97]
	v_mfma_f32_16x16x32_bf16 v[90:93], v[248:251], v[184:187], v[90:93]
	v_mfma_f32_16x16x32_bf16 v[86:89], v[240:243], v[192:195], v[86:89]
	v_mfma_f32_16x16x32_bf16 v[82:85], v[248:251], v[192:195], v[82:85]
	v_mfma_f32_16x16x32_bf16 v[78:81], v[240:243], v[200:203], v[78:81]
	v_mfma_f32_16x16x32_bf16 v[74:77], v[248:251], v[200:203], v[74:77]
	v_mfma_f32_16x16x32_bf16 v[70:73], v[240:243], v[232:235], v[70:73]
	v_mfma_f32_16x16x32_bf16 v[66:69], v[248:251], v[232:235], v[66:69]
	s_setprio 0
	v_lshl_add_u64 v[204:205], v[204:205], 0, s[28:29]
	s_add_i32 m0, s1, 0x8000
	s_barrier
	ds_read_b128 v[180:183], v0 offset:49152
	ds_read_b128 v[184:187], v0 offset:50176
	ds_read_b128 v[188:191], v0 offset:51200
	ds_read_b128 v[192:195], v0 offset:52224
	ds_read_b128 v[196:199], v0 offset:53248
	ds_read_b128 v[200:203], v0 offset:54272
	ds_read_b128 v[222:225], v0 offset:55296
	ds_read_b128 v[232:235], v0 offset:56320
	global_load_lds_dwordx4 v[204:205], off
	v_lshl_add_u64 v[204:205], v[216:217], 0, s[28:29]
	s_add_i32 m0, s1, 0xa000
	s_nop 0
	global_load_lds_dwordx4 v[204:205], off
	s_barrier
	s_waitcnt lgkmcnt(0)
	s_setprio 1
	s_waitcnt lgkmcnt(0)
	v_mfma_f32_16x16x32_bf16 v[62:65], v[164:167], v[180:183], v[62:65]
	v_mfma_f32_16x16x32_bf16 v[58:61], v[172:175], v[180:183], v[58:61]
	v_mfma_f32_16x16x32_bf16 v[54:57], v[164:167], v[188:191], v[54:57]
	v_mfma_f32_16x16x32_bf16 v[50:53], v[172:175], v[188:191], v[50:53]
	v_mfma_f32_16x16x32_bf16 v[46:49], v[164:167], v[196:199], v[46:49]
	v_mfma_f32_16x16x32_bf16 v[42:45], v[172:175], v[196:199], v[42:45]
	v_mfma_f32_16x16x32_bf16 v[38:41], v[164:167], v[222:225], v[38:41]
	v_mfma_f32_16x16x32_bf16 v[34:37], v[172:175], v[222:225], v[34:37]
	v_mfma_f32_16x16x32_bf16 v[62:65], v[168:171], v[184:187], v[62:65]
	v_mfma_f32_16x16x32_bf16 v[58:61], v[176:179], v[184:187], v[58:61]
	v_mfma_f32_16x16x32_bf16 v[54:57], v[168:171], v[192:195], v[54:57]
	v_mfma_f32_16x16x32_bf16 v[50:53], v[176:179], v[192:195], v[50:53]
	v_mfma_f32_16x16x32_bf16 v[46:49], v[168:171], v[200:203], v[46:49]
	v_mfma_f32_16x16x32_bf16 v[42:45], v[176:179], v[200:203], v[42:45]
	v_mfma_f32_16x16x32_bf16 v[38:41], v[168:171], v[232:235], v[38:41]
	v_mfma_f32_16x16x32_bf16 v[34:37], v[176:179], v[232:235], v[34:37]
	s_setprio 0
	s_barrier
	v_lshl_add_u64 v[164:165], v[210:211], 0, s[30:31]
	s_add_i32 m0, s1, 0x1c000
	global_load_lds_dwordx4 v[164:165], off
	v_lshl_add_u64 v[164:165], v[228:229], 0, s[30:31]
	s_add_i32 m0, s1, 0x1e000
	s_nop 0
	global_load_lds_dwordx4 v[164:165], off
	s_waitcnt vmcnt(6)
	s_barrier
	s_setprio 1
	v_mfma_f32_16x16x32_bf16 v[30:33], v[236:239], v[180:183], v[30:33]
	v_mfma_f32_16x16x32_bf16 v[26:29], v[244:247], v[180:183], v[26:29]
	v_mfma_f32_16x16x32_bf16 v[22:25], v[236:239], v[188:191], v[22:25]
	v_mfma_f32_16x16x32_bf16 v[18:21], v[244:247], v[188:191], v[18:21]
	v_mfma_f32_16x16x32_bf16 v[14:17], v[236:239], v[196:199], v[14:17]
	v_mfma_f32_16x16x32_bf16 v[10:13], v[244:247], v[196:199], v[10:13]
	v_mfma_f32_16x16x32_bf16 v[6:9], v[236:239], v[222:225], v[6:9]
	v_mfma_f32_16x16x32_bf16 v[2:5], v[244:247], v[222:225], v[2:5]
	v_mfma_f32_16x16x32_bf16 v[30:33], v[240:243], v[184:187], v[30:33]
	v_mfma_f32_16x16x32_bf16 v[26:29], v[248:251], v[184:187], v[26:29]
	v_mfma_f32_16x16x32_bf16 v[22:25], v[240:243], v[192:195], v[22:25]
	v_mfma_f32_16x16x32_bf16 v[18:21], v[248:251], v[192:195], v[18:21]
	v_mfma_f32_16x16x32_bf16 v[14:17], v[240:243], v[200:203], v[14:17]
	v_mfma_f32_16x16x32_bf16 v[10:13], v[248:251], v[200:203], v[10:13]
	v_mfma_f32_16x16x32_bf16 v[6:9], v[240:243], v[232:235], v[6:9]
	v_mfma_f32_16x16x32_bf16 v[2:5], v[248:251], v[232:235], v[2:5]
	s_setprio 0
	s_add_i32 s0, s0, 2
	s_add_u32 s8, s8, 0x100
	s_addc_u32 s9, s9, 0
	s_cmp_lt_u32 s0, 28
	s_barrier
	s_cbranch_scc1 .LBB0_678
	s_add_i32 s1, s1, 0x1e000
	s_mov_b64 s[8:9], 0xf80
	v_readfirstlane_b32 s0, v162
	v_lshl_add_u64 v[132:133], v[132:133], 0, s[8:9]
	s_mov_b32 m0, s0
	v_readfirstlane_b32 s0, v163
	ds_read_b128 v[134:137], v151
	ds_read_b128 v[138:141], v151 offset:1024
	ds_read_b128 v[152:155], v151 offset:2048
	ds_read_b128 v[156:159], v151 offset:3072
	ds_read_b128 v[164:167], v0
	ds_read_b128 v[168:171], v0 offset:1024
	ds_read_b128 v[172:175], v0 offset:2048
	ds_read_b128 v[176:179], v0 offset:3072
	ds_read_b128 v[180:183], v0 offset:4096
	ds_read_b128 v[184:187], v0 offset:5120
	ds_read_b128 v[188:191], v0 offset:6144
	ds_read_b128 v[192:195], v0 offset:7168
	global_load_lds_dwordx4 v[132:133], off
	v_lshl_add_u64 v[130:131], v[130:131], 0, s[8:9]
	s_mov_b32 m0, s0
	s_nop 0
	global_load_lds_dwordx4 v[130:131], off
	s_barrier
	s_waitcnt lgkmcnt(0)
	s_setprio 1
	s_waitcnt lgkmcnt(0)
	v_mfma_f32_16x16x32_bf16 v[126:129], v[134:137], v[164:167], v[126:129]
	v_mfma_f32_16x16x32_bf16 v[122:125], v[152:155], v[164:167], v[122:125]
	v_mfma_f32_16x16x32_bf16 v[114:117], v[152:155], v[172:175], v[114:117]
	v_mfma_f32_16x16x32_bf16 v[106:109], v[152:155], v[180:183], v[106:109]
	v_mfma_f32_16x16x32_bf16 v[98:101], v[152:155], v[188:191], v[98:101]
	v_mfma_f32_16x16x32_bf16 v[126:129], v[138:141], v[168:171], v[126:129]
	v_mfma_f32_16x16x32_bf16 v[122:125], v[156:159], v[168:171], v[122:125]
	v_mfma_f32_16x16x32_bf16 v[118:121], v[134:137], v[172:175], v[118:121]
	v_mfma_f32_16x16x32_bf16 v[114:117], v[156:159], v[176:179], v[114:117]
	v_mfma_f32_16x16x32_bf16 v[110:113], v[134:137], v[180:183], v[110:113]
	v_mfma_f32_16x16x32_bf16 v[106:109], v[156:159], v[184:187], v[106:109]
	v_mfma_f32_16x16x32_bf16 v[102:105], v[134:137], v[188:191], v[102:105]
	v_mfma_f32_16x16x32_bf16 v[98:101], v[156:159], v[192:195], v[98:101]
	v_mfma_f32_16x16x32_bf16 v[130:133], v[138:141], v[176:179], v[118:121]
	v_mfma_f32_16x16x32_bf16 v[160:163], v[138:141], v[184:187], v[110:113]
	v_mfma_f32_16x16x32_bf16 v[196:199], v[138:141], v[192:195], v[102:105]
	s_setprio 0
	s_barrier
	s_nop 0
	ds_read_b128 v[102:105], v151 offset:16384
	ds_read_b128 v[110:113], v151 offset:17408
	ds_read_b128 v[118:121], v151 offset:18432
	ds_read_b128 v[200:203], v151 offset:19456
	s_barrier
	s_waitcnt lgkmcnt(0)
	s_setprio 1
	s_waitcnt lgkmcnt(1)
	v_mfma_f32_16x16x32_bf16 v[90:93], v[118:121], v[164:167], v[90:93]
	v_mfma_f32_16x16x32_bf16 v[86:89], v[102:105], v[172:175], v[86:89]
	v_mfma_f32_16x16x32_bf16 v[82:85], v[118:121], v[172:175], v[82:85]
	v_mfma_f32_16x16x32_bf16 v[78:81], v[102:105], v[180:183], v[78:81]
	v_mfma_f32_16x16x32_bf16 v[70:73], v[102:105], v[188:191], v[70:73]
	v_mfma_f32_16x16x32_bf16 v[94:97], v[102:105], v[164:167], v[94:97]
	s_waitcnt lgkmcnt(0)
	v_mfma_f32_16x16x32_bf16 v[90:93], v[200:203], v[168:171], v[90:93]
	v_mfma_f32_16x16x32_bf16 v[86:89], v[110:113], v[176:179], v[86:89]
	v_mfma_f32_16x16x32_bf16 v[82:85], v[200:203], v[176:179], v[82:85]
	v_mfma_f32_16x16x32_bf16 v[78:81], v[110:113], v[184:187], v[78:81]
	v_mfma_f32_16x16x32_bf16 v[74:77], v[118:121], v[180:183], v[74:77]
	v_mfma_f32_16x16x32_bf16 v[70:73], v[110:113], v[192:195], v[70:73]
	v_mfma_f32_16x16x32_bf16 v[66:69], v[118:121], v[188:191], v[66:69]
	v_mfma_f32_16x16x32_bf16 v[222:225], v[110:113], v[168:171], v[94:97]
	v_mfma_f32_16x16x32_bf16 v[164:167], v[200:203], v[184:187], v[74:77]
	v_mfma_f32_16x16x32_bf16 v[168:171], v[200:203], v[192:195], v[66:69]
	s_setprio 0
	s_barrier
	s_nop 2
	ds_read_b128 v[66:69], v0 offset:16384
	ds_read_b128 v[74:77], v0 offset:17408
	ds_read_b128 v[94:97], v0 offset:18432
	ds_read_b128 v[172:175], v0 offset:19456
	ds_read_b128 v[176:179], v0 offset:20480
	ds_read_b128 v[180:183], v0 offset:21504
	ds_read_b128 v[184:187], v0 offset:22528
	ds_read_b128 v[188:191], v0 offset:23552
	s_waitcnt vmcnt(4)
	s_barrier
	s_waitcnt lgkmcnt(0)
	s_setprio 1
	s_waitcnt lgkmcnt(5)
	v_mfma_f32_16x16x32_bf16 v[54:57], v[134:137], v[94:97], v[54:57]
	v_mfma_f32_16x16x32_bf16 v[50:53], v[152:155], v[94:97], v[50:53]
	v_mfma_f32_16x16x32_bf16 v[62:65], v[134:137], v[66:69], v[62:65]
	v_mfma_f32_16x16x32_bf16 v[58:61], v[152:155], v[66:69], v[58:61]
	s_waitcnt lgkmcnt(4)
	v_mfma_f32_16x16x32_bf16 v[54:57], v[138:141], v[172:175], v[54:57]
	v_mfma_f32_16x16x32_bf16 v[50:53], v[156:159], v[172:175], v[50:53]
	s_waitcnt lgkmcnt(3)
	v_mfma_f32_16x16x32_bf16 v[46:49], v[134:137], v[176:179], v[46:49]
	v_mfma_f32_16x16x32_bf16 v[42:45], v[152:155], v[176:179], v[42:45]
	s_waitcnt lgkmcnt(1)
	v_mfma_f32_16x16x32_bf16 v[38:41], v[134:137], v[184:187], v[38:41]
	v_mfma_f32_16x16x32_bf16 v[34:37], v[152:155], v[184:187], v[34:37]
	v_mfma_f32_16x16x32_bf16 v[192:195], v[138:141], v[74:77], v[62:65]
	v_mfma_f32_16x16x32_bf16 v[232:235], v[156:159], v[74:77], v[58:61]
	v_mfma_f32_16x16x32_bf16 v[236:239], v[138:141], v[180:183], v[46:49]
	v_mfma_f32_16x16x32_bf16 v[240:243], v[156:159], v[180:183], v[42:45]
	s_waitcnt lgkmcnt(0)
	v_mfma_f32_16x16x32_bf16 v[134:137], v[138:141], v[188:191], v[38:41]
	v_mfma_f32_16x16x32_bf16 v[138:141], v[156:159], v[188:191], v[34:37]
	s_setprio 0
	s_setprio 1
	v_mfma_f32_16x16x32_bf16 v[30:33], v[102:105], v[66:69], v[30:33]
	v_mfma_f32_16x16x32_bf16 v[26:29], v[118:121], v[66:69], v[26:29]
	v_mfma_f32_16x16x32_bf16 v[14:17], v[102:105], v[176:179], v[14:17]
	v_mfma_f32_16x16x32_bf16 v[10:13], v[118:121], v[176:179], v[10:13]
	v_mfma_f32_16x16x32_bf16 v[30:33], v[110:113], v[74:77], v[30:33]
	v_mfma_f32_16x16x32_bf16 v[26:29], v[200:203], v[74:77], v[26:29]
	v_mfma_f32_16x16x32_bf16 v[22:25], v[102:105], v[94:97], v[22:25]
	v_mfma_f32_16x16x32_bf16 v[18:21], v[118:121], v[94:97], v[18:21]
	v_mfma_f32_16x16x32_bf16 v[14:17], v[110:113], v[180:183], v[14:17]
	v_mfma_f32_16x16x32_bf16 v[10:13], v[200:203], v[180:183], v[10:13]
	v_mfma_f32_16x16x32_bf16 v[6:9], v[102:105], v[184:187], v[6:9]
	v_mfma_f32_16x16x32_bf16 v[2:5], v[118:121], v[184:187], v[2:5]
	v_mfma_f32_16x16x32_bf16 v[152:155], v[110:113], v[172:175], v[22:25]
	v_mfma_f32_16x16x32_bf16 v[156:159], v[200:203], v[172:175], v[18:21]
	v_mfma_f32_16x16x32_bf16 v[172:175], v[110:113], v[188:191], v[6:9]
	v_mfma_f32_16x16x32_bf16 v[176:179], v[200:203], v[188:191], v[2:5]
	s_setprio 0
	s_barrier
	s_nop 1
	ds_read_b128 v[2:5], v151 offset:32768
	ds_read_b128 v[6:9], v151 offset:33792
	ds_read_b128 v[180:183], v151 offset:34816
	ds_read_b128 v[184:187], v151 offset:35840
	ds_read_b128 v[18:21], v0 offset:32768
	ds_read_b128 v[22:25], v0 offset:33792
	ds_read_b128 v[38:41], v0 offset:34816
	ds_read_b128 v[46:49], v0 offset:35840
	ds_read_b128 v[58:61], v0 offset:36864
	ds_read_b128 v[66:69], v0 offset:37888
	ds_read_b128 v[188:191], v0 offset:38912
	ds_read_b128 v[200:203], v0 offset:39936
	s_waitcnt vmcnt(2)
	s_barrier
	s_waitcnt lgkmcnt(0)
	s_setprio 1
	s_waitcnt lgkmcnt(7)
	v_mfma_f32_16x16x32_bf16 v[34:37], v[2:5], v[18:21], v[126:129]
	s_waitcnt lgkmcnt(6)
	v_mfma_f32_16x16x32_bf16 v[118:121], v[6:9], v[22:25], v[34:37]
	v_mfma_f32_16x16x32_bf16 v[34:37], v[180:183], v[18:21], v[122:125]
	v_mfma_f32_16x16x32_bf16 v[110:113], v[184:187], v[22:25], v[34:37]
	s_waitcnt lgkmcnt(5)
	v_mfma_f32_16x16x32_bf16 v[34:37], v[2:5], v[38:41], v[130:133]
	s_waitcnt lgkmcnt(4)
	v_mfma_f32_16x16x32_bf16 v[102:105], v[6:9], v[46:49], v[34:37]
	v_mfma_f32_16x16x32_bf16 v[34:37], v[180:183], v[38:41], v[114:117]
	v_mfma_f32_16x16x32_bf16 v[94:97], v[184:187], v[46:49], v[34:37]
	s_waitcnt lgkmcnt(3)
	v_mfma_f32_16x16x32_bf16 v[34:37], v[2:5], v[58:61], v[160:163]
	s_waitcnt lgkmcnt(2)
	v_mfma_f32_16x16x32_bf16 v[74:77], v[6:9], v[66:69], v[34:37]
	v_mfma_f32_16x16x32_bf16 v[34:37], v[180:183], v[58:61], v[106:109]
	v_mfma_f32_16x16x32_bf16 v[62:65], v[184:187], v[66:69], v[34:37]
	s_waitcnt lgkmcnt(1)
	v_mfma_f32_16x16x32_bf16 v[34:37], v[2:5], v[188:191], v[196:199]
	s_waitcnt lgkmcnt(0)
	v_mfma_f32_16x16x32_bf16 v[42:45], v[6:9], v[200:203], v[34:37]
	v_mfma_f32_16x16x32_bf16 v[34:37], v[180:183], v[188:191], v[98:101]
	v_mfma_f32_16x16x32_bf16 v[34:37], v[184:187], v[200:203], v[34:37]
	s_setprio 0
	s_barrier
	ds_read_b128 v[130:133], v151 offset:49152
	ds_read_b128 v[160:163], v151 offset:50176
	ds_read_b128 v[196:199], v151 offset:51200
	ds_read_b128 v[148:151], v151 offset:52224
	s_waitcnt vmcnt(0)
	s_barrier
	s_waitcnt lgkmcnt(0)
	s_setprio 1
	s_waitcnt lgkmcnt(3)
	v_mfma_f32_16x16x32_bf16 v[98:101], v[130:133], v[18:21], v[222:225]
	s_waitcnt lgkmcnt(1)
	v_mfma_f32_16x16x32_bf16 v[18:21], v[196:199], v[18:21], v[90:93]
	s_waitcnt lgkmcnt(0)
	v_mfma_f32_16x16x32_bf16 v[122:125], v[148:151], v[22:25], v[18:21]
	v_mfma_f32_16x16x32_bf16 v[18:21], v[130:133], v[38:41], v[86:89]
	v_mfma_f32_16x16x32_bf16 v[114:117], v[160:163], v[46:49], v[18:21]
	v_mfma_f32_16x16x32_bf16 v[18:21], v[196:199], v[38:41], v[82:85]
	v_mfma_f32_16x16x32_bf16 v[106:109], v[148:151], v[46:49], v[18:21]
	v_mfma_f32_16x16x32_bf16 v[18:21], v[130:133], v[58:61], v[78:81]
	v_mfma_f32_16x16x32_bf16 v[126:129], v[160:163], v[22:25], v[98:101]
	v_mfma_f32_16x16x32_bf16 v[98:101], v[160:163], v[66:69], v[18:21]
	v_mfma_f32_16x16x32_bf16 v[18:21], v[196:199], v[58:61], v[164:167]
	v_mfma_f32_16x16x32_bf16 v[90:93], v[148:151], v[66:69], v[18:21]
	v_mfma_f32_16x16x32_bf16 v[18:21], v[130:133], v[188:191], v[70:73]
	v_mfma_f32_16x16x32_bf16 v[66:69], v[160:163], v[200:203], v[18:21]
	v_mfma_f32_16x16x32_bf16 v[18:21], v[196:199], v[188:191], v[168:171]
	v_mfma_f32_16x16x32_bf16 v[58:61], v[148:151], v[200:203], v[18:21]
	s_setprio 0
	s_barrier
	ds_read_b128 v[82:85], v0 offset:49152
	ds_read_b128 v[164:167], v0 offset:50176
	ds_read_b128 v[168:171], v0 offset:51200
	ds_read_b128 v[188:191], v0 offset:52224
	ds_read_b128 v[200:203], v0 offset:53248
	ds_read_b128 v[222:225], v0 offset:54272
	ds_read_b128 v[244:247], v0 offset:55296
	ds_read_b128 v[248:251], v0 offset:56320
	s_barrier
	s_waitcnt lgkmcnt(0)
	s_setprio 1
	s_waitcnt lgkmcnt(7)
	v_mfma_f32_16x16x32_bf16 v[18:21], v[2:5], v[82:85], v[192:195]
	s_waitcnt lgkmcnt(6)
	v_mfma_f32_16x16x32_bf16 v[78:81], v[6:9], v[164:167], v[18:21]
	v_mfma_f32_16x16x32_bf16 v[18:21], v[180:183], v[82:85], v[232:235]
	v_mfma_f32_16x16x32_bf16 v[70:73], v[184:187], v[164:167], v[18:21]
	s_waitcnt lgkmcnt(5)
	v_mfma_f32_16x16x32_bf16 v[18:21], v[2:5], v[168:171], v[54:57]
	s_waitcnt lgkmcnt(4)
	v_mfma_f32_16x16x32_bf16 v[46:49], v[6:9], v[188:191], v[18:21]
	v_mfma_f32_16x16x32_bf16 v[18:21], v[180:183], v[168:171], v[50:53]
	v_mfma_f32_16x16x32_bf16 v[38:41], v[184:187], v[188:191], v[18:21]
	s_waitcnt lgkmcnt(3)
	v_mfma_f32_16x16x32_bf16 v[18:21], v[2:5], v[200:203], v[236:239]
	s_waitcnt lgkmcnt(1)
	v_mfma_f32_16x16x32_bf16 v[2:5], v[2:5], v[244:247], v[134:137]
	v_mfma_f32_16x16x32_bf16 v[22:25], v[6:9], v[222:225], v[18:21]
	v_mfma_f32_16x16x32_bf16 v[18:21], v[180:183], v[200:203], v[240:243]
	s_waitcnt lgkmcnt(0)
	v_mfma_f32_16x16x32_bf16 v[6:9], v[6:9], v[248:251], v[2:5]
	v_mfma_f32_16x16x32_bf16 v[2:5], v[180:183], v[244:247], v[138:141]
	v_mfma_f32_16x16x32_bf16 v[18:21], v[184:187], v[222:225], v[18:21]
	v_mfma_f32_16x16x32_bf16 v[2:5], v[184:187], v[248:251], v[2:5]
	s_setprio 0
	s_setprio 1
	v_mfma_f32_16x16x32_bf16 v[26:29], v[196:199], v[82:85], v[26:29]
	v_mfma_f32_16x16x32_bf16 v[30:33], v[130:133], v[82:85], v[30:33]
	v_mfma_f32_16x16x32_bf16 v[82:85], v[148:151], v[164:167], v[26:29]
	v_mfma_f32_16x16x32_bf16 v[26:29], v[130:133], v[168:171], v[152:155]
	v_mfma_f32_16x16x32_bf16 v[54:57], v[160:163], v[188:191], v[26:29]
	v_mfma_f32_16x16x32_bf16 v[26:29], v[196:199], v[168:171], v[156:159]
	v_mfma_f32_16x16x32_bf16 v[10:13], v[196:199], v[200:203], v[10:13]
	v_mfma_f32_16x16x32_bf16 v[50:53], v[148:151], v[188:191], v[26:29]
	v_mfma_f32_16x16x32_bf16 v[14:17], v[130:133], v[200:203], v[14:17]
	v_mfma_f32_16x16x32_bf16 v[26:29], v[148:151], v[222:225], v[10:13]
	v_mfma_f32_16x16x32_bf16 v[10:13], v[130:133], v[244:247], v[172:175]
	v_mfma_f32_16x16x32_bf16 v[86:89], v[160:163], v[164:167], v[30:33]
	v_mfma_f32_16x16x32_bf16 v[30:33], v[160:163], v[222:225], v[14:17]
	v_mfma_f32_16x16x32_bf16 v[14:17], v[160:163], v[248:251], v[10:13]
	v_mfma_f32_16x16x32_bf16 v[10:13], v[196:199], v[244:247], v[176:179]
	v_mfma_f32_16x16x32_bf16 v[10:13], v[148:151], v[248:251], v[10:13]
	s_setprio 0
	s_movk_i32 s0, 0x100
	v_cmp_gt_u32_e32 vcc, s0, v142
	s_barrier
	s_and_saveexec_b64 s[0:1], vcc
	s_cbranch_execz .LBB0_674
	s_barrier
	s_branch .LBB0_674

.LBB0_760:
	s_or_b64 exec, exec, s[14:15]
	v_mov_b32_e32 v131, v1
	v_add_u32_e32 v155, 0x18000, v145
	v_lshl_add_u64 v[10:11], s[0:1], 0, v[0:1]
	v_lshl_add_u64 v[12:13], s[0:1], 0, v[130:131]
	v_lshl_add_u64 v[18:19], s[12:13], 0, v[0:1]
	v_lshl_add_u64 v[20:21], s[12:13], 0, v[130:131]
	s_mov_b64 s[12:13], 0x80
	v_readfirstlane_b32 s0, v155
	v_add_u32_e32 v156, 0x1a000, v145
	v_lshl_add_u64 v[10:11], v[10:11], 0, s[12:13]
	s_mov_b32 m0, s0
	v_readfirstlane_b32 s0, v156
	v_add_u32_e32 v157, 0x8000, v145
	v_lshl_add_u64 v[14:15], s[8:9], 0, v[0:1]
	s_waitcnt vmcnt(4)
	s_barrier
	global_load_lds_dwordx4 v[10:11], off
	v_lshl_add_u64 v[10:11], v[12:13], 0, s[12:13]
	s_mov_b32 m0, s0
	v_readfirstlane_b32 s0, v157
	v_add_u32_e32 v158, 0xa000, v145
	v_lshl_add_u64 v[16:17], s[8:9], 0, v[130:131]
	global_load_lds_dwordx4 v[10:11], off
	v_lshl_add_u64 v[10:11], v[14:15], 0, s[12:13]
	s_mov_b32 m0, s0
	v_readfirstlane_b32 s0, v158
	v_add_u32_e32 v159, 0x1c000, v145
	global_load_lds_dwordx4 v[10:11], off
	v_lshl_add_u64 v[10:11], v[16:17], 0, s[12:13]
	s_mov_b32 m0, s0
	v_readfirstlane_b32 s0, v159
	v_add_u32_e32 v160, 0x1e000, v145
	global_load_lds_dwordx4 v[10:11], off
	v_lshl_add_u64 v[10:11], v[18:19], 0, s[12:13]
	s_mov_b32 m0, s0
	v_readfirstlane_b32 s0, v160
	global_load_lds_dwordx4 v[10:11], off
	v_lshl_add_u64 v[10:11], v[20:21], 0, s[12:13]
	s_mov_b32 m0, s0
	s_movk_i32 s13, 0x1600
	global_load_lds_dwordx4 v[10:11], off
	v_lshrrev_b32_e32 v10, 1, v2
	v_mul_lo_u32 v2, v4, s13
	s_mov_b32 s12, 0x16000
	v_mad_u64_u32 v[10:11], s[0:1], v10, s12, v[2:3]
	v_or_b32_e32 v2, v10, v3
	v_add_lshl_u32 v2, v2, v5, 1
	v_lshrrev_b32_e32 v5, 1, v6
	v_mul_lo_u32 v4, v8, s13
	v_mad_u64_u32 v[4:5], s[12:13], v5, s12, v[4:5]
	s_add_u32 s0, s16, s57
	v_or_b32_e32 v4, v4, v7
	v_mov_b32_e32 v3, v1
	s_addc_u32 s1, s17, s54
	v_add_lshl_u32 v4, v4, v9, 1
	v_mov_b32_e32 v5, v1
	v_and_b32_e32 v144, 15, v140
	v_bfe_u32 v143, v140, 4, 2
	v_lshlrev_b32_e32 v24, 2, v140
	v_lshl_add_u64 v[132:133], s[0:1], 0, v[2:3]
	v_lshl_add_u64 v[134:135], s[0:1], 0, v[4:5]
	s_add_u32 s0, s20, s10
	v_bfe_u32 v142, v140, 6, 2
	v_lshlrev_b32_e32 v22, 6, v144
	v_lshlrev_b32_e32 v23, 4, v143
	v_and_b32_e32 v24, 32, v24
	s_waitcnt vmcnt(6)
	s_addc_u32 s1, s21, s11
	v_bitop3_b32 v22, v23, v24, v22 bitop3:0x36
	v_lshlrev_b32_e32 v23, 13, v141
	v_lshl_or_b32 v24, v142, 12, v212
	v_lshl_add_u64 v[136:137], s[0:1], 0, v[2:3]
	v_mov_b32_e32 v2, 0
	v_lshl_add_u64 v[138:139], s[0:1], 0, v[4:5]
	s_mov_b32 s0, -2
	s_mov_b64 s[10:11], 0
	v_add_u32_e32 v148, v24, v22
	v_add_u32_e32 v147, v23, v22
	v_mov_b32_e32 v3, v2
	v_mov_b32_e32 v4, v2
	v_mov_b32_e32 v5, v2
	v_mov_b32_e32 v6, v2
	v_mov_b32_e32 v7, v2
	v_mov_b32_e32 v8, v2
	v_mov_b32_e32 v9, v2
	v_mov_b32_e32 v10, v2
	v_mov_b32_e32 v11, v2
	v_mov_b32_e32 v12, v2
	v_mov_b32_e32 v13, v2
	v_mov_b32_e32 v14, v2
	v_mov_b32_e32 v15, v2
	v_mov_b32_e32 v16, v2
	v_mov_b32_e32 v17, v2
	v_mov_b32_e32 v18, v2
	v_mov_b32_e32 v19, v2
	v_mov_b32_e32 v20, v2
	v_mov_b32_e32 v21, v2
	v_mov_b32_e32 v22, v2
	v_mov_b32_e32 v23, v2
	v_mov_b32_e32 v24, v2
	v_mov_b32_e32 v25, v2
	v_mov_b32_e32 v26, v2
	v_mov_b32_e32 v27, v2
	v_mov_b32_e32 v28, v2
	v_mov_b32_e32 v29, v2
	v_mov_b32_e32 v30, v2
	v_mov_b32_e32 v31, v2
	v_mov_b32_e32 v32, v2
	v_mov_b32_e32 v33, v2
	v_mov_b32_e32 v34, v2
	v_mov_b32_e32 v35, v2
	v_mov_b32_e32 v36, v2
	v_mov_b32_e32 v37, v2
	v_mov_b32_e32 v38, v2
	v_mov_b32_e32 v39, v2
	v_mov_b32_e32 v40, v2
	v_mov_b32_e32 v41, v2
	v_mov_b32_e32 v42, v2
	v_mov_b32_e32 v43, v2
	v_mov_b32_e32 v44, v2
	v_mov_b32_e32 v45, v2
	v_mov_b32_e32 v46, v2
	v_mov_b32_e32 v47, v2
	v_mov_b32_e32 v48, v2
	v_mov_b32_e32 v49, v2
	v_mov_b32_e32 v50, v2
	v_mov_b32_e32 v51, v2
	v_mov_b32_e32 v52, v2
	v_mov_b32_e32 v53, v2
	v_mov_b32_e32 v54, v2
	v_mov_b32_e32 v55, v2
	v_mov_b32_e32 v56, v2
	v_mov_b32_e32 v57, v2
	v_mov_b32_e32 v58, v2
	v_mov_b32_e32 v59, v2
	v_mov_b32_e32 v60, v2
	v_mov_b32_e32 v61, v2
	v_mov_b32_e32 v62, v2
	v_mov_b32_e32 v63, v2
	v_mov_b32_e32 v64, v2
	v_mov_b32_e32 v65, v2
	v_mov_b32_e32 v66, v2
	v_mov_b32_e32 v67, v2
	v_mov_b32_e32 v68, v2
	v_mov_b32_e32 v69, v2
	v_mov_b32_e32 v70, v2
	v_mov_b32_e32 v71, v2
	v_mov_b32_e32 v72, v2
	v_mov_b32_e32 v73, v2
	v_mov_b32_e32 v74, v2
	v_mov_b32_e32 v75, v2
	v_mov_b32_e32 v76, v2
	v_mov_b32_e32 v77, v2
	v_mov_b32_e32 v78, v2
	v_mov_b32_e32 v79, v2
	v_mov_b32_e32 v80, v2
	v_mov_b32_e32 v81, v2
	v_mov_b32_e32 v82, v2
	v_mov_b32_e32 v83, v2
	v_mov_b32_e32 v84, v2
	v_mov_b32_e32 v85, v2
	v_mov_b32_e32 v86, v2
	v_mov_b32_e32 v87, v2
	v_mov_b32_e32 v88, v2
	v_mov_b32_e32 v89, v2
	v_mov_b32_e32 v90, v2
	v_mov_b32_e32 v91, v2
	v_mov_b32_e32 v92, v2
	v_mov_b32_e32 v93, v2
	v_mov_b32_e32 v94, v2
	v_mov_b32_e32 v95, v2
	v_mov_b32_e32 v96, v2
	v_mov_b32_e32 v97, v2
	v_mov_b32_e32 v98, v2
	v_mov_b32_e32 v99, v2
	v_mov_b32_e32 v100, v2
	v_mov_b32_e32 v101, v2
	v_mov_b32_e32 v102, v2
	v_mov_b32_e32 v103, v2
	v_mov_b32_e32 v104, v2
	v_mov_b32_e32 v105, v2
	v_mov_b32_e32 v106, v2
	v_mov_b32_e32 v107, v2
	v_mov_b32_e32 v108, v2
	v_mov_b32_e32 v109, v2
	v_mov_b32_e32 v110, v2
	v_mov_b32_e32 v111, v2
	v_mov_b32_e32 v112, v2
	v_mov_b32_e32 v113, v2
	v_mov_b32_e32 v114, v2
	v_mov_b32_e32 v115, v2
	v_mov_b32_e32 v116, v2
	v_mov_b32_e32 v117, v2
	v_mov_b32_e32 v118, v2
	v_mov_b32_e32 v119, v2
	v_mov_b32_e32 v120, v2
	v_mov_b32_e32 v121, v2
	v_mov_b32_e32 v122, v2
	v_mov_b32_e32 v123, v2
	v_mov_b32_e32 v124, v2
	v_mov_b32_e32 v125, v2
	v_mov_b32_e32 v126, v2
	v_mov_b32_e32 v127, v2
	v_mov_b32_e32 v128, v2
	v_mov_b32_e32 v129, v2
	s_barrier
	v_readfirstlane_b32 s1, v145
	s_nop 1
.LBB0_761:
	ds_read_b128 v[164:167], v148
	ds_read_b128 v[168:171], v148 offset:1024
	ds_read_b128 v[172:175], v148 offset:2048
	ds_read_b128 v[176:179], v148 offset:3072
	v_add_u32_e32 v161, 0xc000, v145
	v_lshl_add_u64 v[204:205], v[136:137], 0, s[10:11]
	v_lshl_add_u64 v[162:163], v[204:205], 0, s[34:35]
	s_add_i32 m0, s1, 0xc000
	ds_read_b128 v[180:183], v147
	ds_read_b128 v[184:187], v147 offset:1024
	ds_read_b128 v[188:191], v147 offset:2048
	ds_read_b128 v[192:195], v147 offset:3072
	ds_read_b128 v[196:199], v147 offset:4096
	ds_read_b128 v[200:203], v147 offset:5120
	ds_read_b128 v[222:225], v147 offset:6144
	ds_read_b128 v[232:235], v147 offset:7168
	global_load_lds_dwordx4 v[162:163], off
	v_add_u32_e32 v162, 0xe000, v145
	v_lshl_add_u64 v[210:211], v[138:139], 0, s[10:11]
	v_lshl_add_u64 v[216:217], v[210:211], 0, s[34:35]
	s_add_i32 m0, s1, 0xe000
	s_nop 0
	global_load_lds_dwordx4 v[216:217], off
	s_waitcnt lgkmcnt(8)
	s_barrier
	s_waitcnt lgkmcnt(0)
	s_setprio 1
	s_waitcnt lgkmcnt(0)
	v_mfma_f32_16x16x32_bf16 v[126:129], v[164:167], v[180:183], v[126:129]
	v_mfma_f32_16x16x32_bf16 v[122:125], v[172:175], v[180:183], v[122:125]
	v_mfma_f32_16x16x32_bf16 v[118:121], v[164:167], v[188:191], v[118:121]
	v_mfma_f32_16x16x32_bf16 v[114:117], v[172:175], v[188:191], v[114:117]
	v_mfma_f32_16x16x32_bf16 v[110:113], v[164:167], v[196:199], v[110:113]
	v_mfma_f32_16x16x32_bf16 v[106:109], v[172:175], v[196:199], v[106:109]
	v_mfma_f32_16x16x32_bf16 v[102:105], v[164:167], v[222:225], v[102:105]
	v_mfma_f32_16x16x32_bf16 v[98:101], v[172:175], v[222:225], v[98:101]
	v_mfma_f32_16x16x32_bf16 v[126:129], v[168:171], v[184:187], v[126:129]
	v_mfma_f32_16x16x32_bf16 v[122:125], v[176:179], v[184:187], v[122:125]
	v_mfma_f32_16x16x32_bf16 v[118:121], v[168:171], v[192:195], v[118:121]
	v_mfma_f32_16x16x32_bf16 v[114:117], v[176:179], v[192:195], v[114:117]
	v_mfma_f32_16x16x32_bf16 v[110:113], v[168:171], v[200:203], v[110:113]
	v_mfma_f32_16x16x32_bf16 v[106:109], v[176:179], v[200:203], v[106:109]
	v_mfma_f32_16x16x32_bf16 v[102:105], v[168:171], v[232:235], v[102:105]
	v_mfma_f32_16x16x32_bf16 v[98:101], v[176:179], v[232:235], v[98:101]
	s_setprio 0
	s_barrier
	v_lshl_add_u64 v[216:217], v[132:133], 0, s[10:11]
	v_lshl_add_u64 v[218:219], v[216:217], 0, s[74:75]
	s_add_i32 m0, s1, 0x10000
	ds_read_b128 v[236:239], v148 offset:16384
	ds_read_b128 v[240:243], v148 offset:17408
	ds_read_b128 v[244:247], v148 offset:18432
	ds_read_b128 v[248:251], v148 offset:19456
	global_load_lds_dwordx4 v[218:219], off
	v_lshl_add_u64 v[218:219], v[134:135], 0, s[10:11]
	v_lshl_add_u64 v[228:229], v[218:219], 0, s[74:75]
	s_add_i32 m0, s1, 0x12000
	s_nop 0
	global_load_lds_dwordx4 v[228:229], off
	s_barrier
	s_waitcnt lgkmcnt(0)
	s_setprio 1
	s_waitcnt lgkmcnt(0)
	v_mfma_f32_16x16x32_bf16 v[94:97], v[236:239], v[180:183], v[94:97]
	v_mfma_f32_16x16x32_bf16 v[90:93], v[244:247], v[180:183], v[90:93]
	v_mfma_f32_16x16x32_bf16 v[86:89], v[236:239], v[188:191], v[86:89]
	v_mfma_f32_16x16x32_bf16 v[82:85], v[244:247], v[188:191], v[82:85]
	v_mfma_f32_16x16x32_bf16 v[78:81], v[236:239], v[196:199], v[78:81]
	v_mfma_f32_16x16x32_bf16 v[74:77], v[244:247], v[196:199], v[74:77]
	v_mfma_f32_16x16x32_bf16 v[70:73], v[236:239], v[222:225], v[70:73]
	v_mfma_f32_16x16x32_bf16 v[66:69], v[244:247], v[222:225], v[66:69]
	v_mfma_f32_16x16x32_bf16 v[94:97], v[240:243], v[184:187], v[94:97]
	v_mfma_f32_16x16x32_bf16 v[90:93], v[248:251], v[184:187], v[90:93]
	v_mfma_f32_16x16x32_bf16 v[86:89], v[240:243], v[192:195], v[86:89]
	v_mfma_f32_16x16x32_bf16 v[82:85], v[248:251], v[192:195], v[82:85]
	v_mfma_f32_16x16x32_bf16 v[78:81], v[240:243], v[200:203], v[78:81]
	v_mfma_f32_16x16x32_bf16 v[74:77], v[248:251], v[200:203], v[74:77]
	v_mfma_f32_16x16x32_bf16 v[70:73], v[240:243], v[232:235], v[70:73]
	v_mfma_f32_16x16x32_bf16 v[66:69], v[248:251], v[232:235], v[66:69]
	s_setprio 0
	v_lshl_add_u64 v[228:229], v[204:205], 0, s[74:75]
	s_mov_b32 m0, s1
	s_barrier
	ds_read_b128 v[180:183], v147 offset:16384
	ds_read_b128 v[184:187], v147 offset:17408
	ds_read_b128 v[188:191], v147 offset:18432
	ds_read_b128 v[192:195], v147 offset:19456
	ds_read_b128 v[196:199], v147 offset:20480
	ds_read_b128 v[200:203], v147 offset:21504
	ds_read_b128 v[222:225], v147 offset:22528
	ds_read_b128 v[232:235], v147 offset:23552
	global_load_lds_dwordx4 v[228:229], off
	v_lshl_add_u64 v[228:229], v[210:211], 0, s[74:75]
	s_add_i32 m0, s1, 0x2000
	s_nop 0
	global_load_lds_dwordx4 v[228:229], off
	s_barrier
	s_waitcnt lgkmcnt(0)
	s_setprio 1
	s_waitcnt lgkmcnt(0)
	v_mfma_f32_16x16x32_bf16 v[62:65], v[164:167], v[180:183], v[62:65]
	v_mfma_f32_16x16x32_bf16 v[58:61], v[172:175], v[180:183], v[58:61]
	v_mfma_f32_16x16x32_bf16 v[54:57], v[164:167], v[188:191], v[54:57]
	v_mfma_f32_16x16x32_bf16 v[50:53], v[172:175], v[188:191], v[50:53]
	v_mfma_f32_16x16x32_bf16 v[46:49], v[164:167], v[196:199], v[46:49]
	v_mfma_f32_16x16x32_bf16 v[42:45], v[172:175], v[196:199], v[42:45]
	v_mfma_f32_16x16x32_bf16 v[38:41], v[164:167], v[222:225], v[38:41]
	v_mfma_f32_16x16x32_bf16 v[34:37], v[172:175], v[222:225], v[34:37]
	v_mfma_f32_16x16x32_bf16 v[62:65], v[168:171], v[184:187], v[62:65]
	v_mfma_f32_16x16x32_bf16 v[58:61], v[176:179], v[184:187], v[58:61]
	v_mfma_f32_16x16x32_bf16 v[54:57], v[168:171], v[192:195], v[54:57]
	v_mfma_f32_16x16x32_bf16 v[50:53], v[176:179], v[192:195], v[50:53]
	v_mfma_f32_16x16x32_bf16 v[46:49], v[168:171], v[200:203], v[46:49]
	v_mfma_f32_16x16x32_bf16 v[42:45], v[176:179], v[200:203], v[42:45]
	v_mfma_f32_16x16x32_bf16 v[38:41], v[168:171], v[232:235], v[38:41]
	v_mfma_f32_16x16x32_bf16 v[34:37], v[176:179], v[232:235], v[34:37]
	s_setprio 0
	s_barrier
	v_lshl_add_u64 v[164:165], v[216:217], 0, s[78:79]
	s_add_i32 m0, s1, 0x14000
	global_load_lds_dwordx4 v[164:165], off
	v_lshl_add_u64 v[164:165], v[218:219], 0, s[78:79]
	s_add_i32 m0, s1, 0x16000
	s_nop 0
	global_load_lds_dwordx4 v[164:165], off
	s_waitcnt vmcnt(6)
	s_barrier
	s_setprio 1
	v_mfma_f32_16x16x32_bf16 v[30:33], v[236:239], v[180:183], v[30:33]
	v_mfma_f32_16x16x32_bf16 v[26:29], v[244:247], v[180:183], v[26:29]
	v_mfma_f32_16x16x32_bf16 v[22:25], v[236:239], v[188:191], v[22:25]
	v_mfma_f32_16x16x32_bf16 v[18:21], v[244:247], v[188:191], v[18:21]
	v_mfma_f32_16x16x32_bf16 v[14:17], v[236:239], v[196:199], v[14:17]
	v_mfma_f32_16x16x32_bf16 v[10:13], v[244:247], v[196:199], v[10:13]
	v_mfma_f32_16x16x32_bf16 v[6:9], v[236:239], v[222:225], v[6:9]
	v_mfma_f32_16x16x32_bf16 v[2:5], v[244:247], v[222:225], v[2:5]
	v_mfma_f32_16x16x32_bf16 v[30:33], v[240:243], v[184:187], v[30:33]
	v_mfma_f32_16x16x32_bf16 v[26:29], v[248:251], v[184:187], v[26:29]
	v_mfma_f32_16x16x32_bf16 v[22:25], v[240:243], v[192:195], v[22:25]
	v_mfma_f32_16x16x32_bf16 v[18:21], v[248:251], v[192:195], v[18:21]
	v_mfma_f32_16x16x32_bf16 v[14:17], v[240:243], v[200:203], v[14:17]
	v_mfma_f32_16x16x32_bf16 v[10:13], v[248:251], v[200:203], v[10:13]
	v_mfma_f32_16x16x32_bf16 v[6:9], v[240:243], v[232:235], v[6:9]
	v_mfma_f32_16x16x32_bf16 v[2:5], v[248:251], v[232:235], v[2:5]
	s_setprio 0
	s_barrier
	ds_read_b128 v[164:167], v148 offset:32768
	ds_read_b128 v[168:171], v148 offset:33792
	ds_read_b128 v[172:175], v148 offset:34816
	ds_read_b128 v[176:179], v148 offset:35840
	v_lshl_add_u64 v[228:229], v[204:205], 0, s[78:79]
	s_add_i32 m0, s1, 0x4000
	ds_read_b128 v[180:183], v147 offset:32768
	ds_read_b128 v[184:187], v147 offset:33792
	ds_read_b128 v[188:191], v147 offset:34816
	ds_read_b128 v[192:195], v147 offset:35840
	ds_read_b128 v[196:199], v147 offset:36864
	ds_read_b128 v[200:203], v147 offset:37888
	ds_read_b128 v[222:225], v147 offset:38912
	ds_read_b128 v[232:235], v147 offset:39936
	global_load_lds_dwordx4 v[228:229], off
	v_lshl_add_u64 v[228:229], v[210:211], 0, s[78:79]
	s_add_i32 m0, s1, 0x6000
	s_nop 0
	global_load_lds_dwordx4 v[228:229], off
	s_waitcnt lgkmcnt(8)
	s_barrier
	s_waitcnt lgkmcnt(0)
	s_setprio 1
	s_waitcnt lgkmcnt(0)
	v_mfma_f32_16x16x32_bf16 v[126:129], v[164:167], v[180:183], v[126:129]
	v_mfma_f32_16x16x32_bf16 v[122:125], v[172:175], v[180:183], v[122:125]
	v_mfma_f32_16x16x32_bf16 v[118:121], v[164:167], v[188:191], v[118:121]
	v_mfma_f32_16x16x32_bf16 v[114:117], v[172:175], v[188:191], v[114:117]
	v_mfma_f32_16x16x32_bf16 v[110:113], v[164:167], v[196:199], v[110:113]
	v_mfma_f32_16x16x32_bf16 v[106:109], v[172:175], v[196:199], v[106:109]
	v_mfma_f32_16x16x32_bf16 v[102:105], v[164:167], v[222:225], v[102:105]
	v_mfma_f32_16x16x32_bf16 v[98:101], v[172:175], v[222:225], v[98:101]
	v_mfma_f32_16x16x32_bf16 v[126:129], v[168:171], v[184:187], v[126:129]
	v_mfma_f32_16x16x32_bf16 v[122:125], v[176:179], v[184:187], v[122:125]
	v_mfma_f32_16x16x32_bf16 v[118:121], v[168:171], v[192:195], v[118:121]
	v_mfma_f32_16x16x32_bf16 v[114:117], v[176:179], v[192:195], v[114:117]
	v_mfma_f32_16x16x32_bf16 v[110:113], v[168:171], v[200:203], v[110:113]
	v_mfma_f32_16x16x32_bf16 v[106:109], v[176:179], v[200:203], v[106:109]
	v_mfma_f32_16x16x32_bf16 v[102:105], v[168:171], v[232:235], v[102:105]
	v_mfma_f32_16x16x32_bf16 v[98:101], v[176:179], v[232:235], v[98:101]
	s_setprio 0
	s_barrier
	v_lshl_add_u64 v[228:229], v[216:217], 0, s[28:29]
	s_add_i32 m0, s1, 0x18000
	ds_read_b128 v[236:239], v148 offset:49152
	ds_read_b128 v[240:243], v148 offset:50176
	ds_read_b128 v[244:247], v148 offset:51200
	ds_read_b128 v[248:251], v148 offset:52224
	global_load_lds_dwordx4 v[228:229], off
	v_lshl_add_u64 v[228:229], v[218:219], 0, s[28:29]
	s_add_i32 m0, s1, 0x1a000
	s_nop 0
	global_load_lds_dwordx4 v[228:229], off
	s_barrier
	s_waitcnt lgkmcnt(0)
	s_setprio 1
	s_waitcnt lgkmcnt(0)
	v_mfma_f32_16x16x32_bf16 v[94:97], v[236:239], v[180:183], v[94:97]
	v_mfma_f32_16x16x32_bf16 v[90:93], v[244:247], v[180:183], v[90:93]
	v_mfma_f32_16x16x32_bf16 v[86:89], v[236:239], v[188:191], v[86:89]
	v_mfma_f32_16x16x32_bf16 v[82:85], v[244:247], v[188:191], v[82:85]
	v_mfma_f32_16x16x32_bf16 v[78:81], v[236:239], v[196:199], v[78:81]
	v_mfma_f32_16x16x32_bf16 v[74:77], v[244:247], v[196:199], v[74:77]
	v_mfma_f32_16x16x32_bf16 v[70:73], v[236:239], v[222:225], v[70:73]
	v_mfma_f32_16x16x32_bf16 v[66:69], v[244:247], v[222:225], v[66:69]
	v_mfma_f32_16x16x32_bf16 v[94:97], v[240:243], v[184:187], v[94:97]
	v_mfma_f32_16x16x32_bf16 v[90:93], v[248:251], v[184:187], v[90:93]
	v_mfma_f32_16x16x32_bf16 v[86:89], v[240:243], v[192:195], v[86:89]
	v_mfma_f32_16x16x32_bf16 v[82:85], v[248:251], v[192:195], v[82:85]
	v_mfma_f32_16x16x32_bf16 v[78:81], v[240:243], v[200:203], v[78:81]
	v_mfma_f32_16x16x32_bf16 v[74:77], v[248:251], v[200:203], v[74:77]
	v_mfma_f32_16x16x32_bf16 v[70:73], v[240:243], v[232:235], v[70:73]
	v_mfma_f32_16x16x32_bf16 v[66:69], v[248:251], v[232:235], v[66:69]
	s_setprio 0
	v_lshl_add_u64 v[204:205], v[204:205], 0, s[28:29]
	s_add_i32 m0, s1, 0x8000
	s_barrier
	ds_read_b128 v[180:183], v147 offset:49152
	ds_read_b128 v[184:187], v147 offset:50176
	ds_read_b128 v[188:191], v147 offset:51200
	ds_read_b128 v[192:195], v147 offset:52224
	ds_read_b128 v[196:199], v147 offset:53248
	ds_read_b128 v[200:203], v147 offset:54272
	ds_read_b128 v[222:225], v147 offset:55296
	ds_read_b128 v[232:235], v147 offset:56320
	global_load_lds_dwordx4 v[204:205], off
	v_lshl_add_u64 v[204:205], v[210:211], 0, s[28:29]
	s_add_i32 m0, s1, 0xa000
	s_nop 0
	global_load_lds_dwordx4 v[204:205], off
	s_barrier
	s_waitcnt lgkmcnt(0)
	s_setprio 1
	s_waitcnt lgkmcnt(0)
	v_mfma_f32_16x16x32_bf16 v[62:65], v[164:167], v[180:183], v[62:65]
	v_mfma_f32_16x16x32_bf16 v[58:61], v[172:175], v[180:183], v[58:61]
	v_mfma_f32_16x16x32_bf16 v[54:57], v[164:167], v[188:191], v[54:57]
	v_mfma_f32_16x16x32_bf16 v[50:53], v[172:175], v[188:191], v[50:53]
	v_mfma_f32_16x16x32_bf16 v[46:49], v[164:167], v[196:199], v[46:49]
	v_mfma_f32_16x16x32_bf16 v[42:45], v[172:175], v[196:199], v[42:45]
	v_mfma_f32_16x16x32_bf16 v[38:41], v[164:167], v[222:225], v[38:41]
	v_mfma_f32_16x16x32_bf16 v[34:37], v[172:175], v[222:225], v[34:37]
	v_mfma_f32_16x16x32_bf16 v[62:65], v[168:171], v[184:187], v[62:65]
	v_mfma_f32_16x16x32_bf16 v[58:61], v[176:179], v[184:187], v[58:61]
	v_mfma_f32_16x16x32_bf16 v[54:57], v[168:171], v[192:195], v[54:57]
	v_mfma_f32_16x16x32_bf16 v[50:53], v[176:179], v[192:195], v[50:53]
	v_mfma_f32_16x16x32_bf16 v[46:49], v[168:171], v[200:203], v[46:49]
	v_mfma_f32_16x16x32_bf16 v[42:45], v[176:179], v[200:203], v[42:45]
	v_mfma_f32_16x16x32_bf16 v[38:41], v[168:171], v[232:235], v[38:41]
	v_mfma_f32_16x16x32_bf16 v[34:37], v[176:179], v[232:235], v[34:37]
	s_setprio 0
	s_barrier
	v_lshl_add_u64 v[164:165], v[216:217], 0, s[68:69]
	s_add_i32 m0, s1, 0x1c000
	global_load_lds_dwordx4 v[164:165], off
	v_lshl_add_u64 v[164:165], v[218:219], 0, s[68:69]
	s_add_i32 m0, s1, 0x1e000
	s_nop 0
	global_load_lds_dwordx4 v[164:165], off
	s_waitcnt vmcnt(6)
	s_barrier
	s_setprio 1
	v_mfma_f32_16x16x32_bf16 v[30:33], v[236:239], v[180:183], v[30:33]
	v_mfma_f32_16x16x32_bf16 v[26:29], v[244:247], v[180:183], v[26:29]
	v_mfma_f32_16x16x32_bf16 v[22:25], v[236:239], v[188:191], v[22:25]
	v_mfma_f32_16x16x32_bf16 v[18:21], v[244:247], v[188:191], v[18:21]
	v_mfma_f32_16x16x32_bf16 v[14:17], v[236:239], v[196:199], v[14:17]
	v_mfma_f32_16x16x32_bf16 v[10:13], v[244:247], v[196:199], v[10:13]
	v_mfma_f32_16x16x32_bf16 v[6:9], v[236:239], v[222:225], v[6:9]
	v_mfma_f32_16x16x32_bf16 v[2:5], v[244:247], v[222:225], v[2:5]
	v_mfma_f32_16x16x32_bf16 v[30:33], v[240:243], v[184:187], v[30:33]
	v_mfma_f32_16x16x32_bf16 v[26:29], v[248:251], v[184:187], v[26:29]
	v_mfma_f32_16x16x32_bf16 v[22:25], v[240:243], v[192:195], v[22:25]
	v_mfma_f32_16x16x32_bf16 v[18:21], v[248:251], v[192:195], v[18:21]
	v_mfma_f32_16x16x32_bf16 v[14:17], v[240:243], v[200:203], v[14:17]
	v_mfma_f32_16x16x32_bf16 v[10:13], v[248:251], v[200:203], v[10:13]
	v_mfma_f32_16x16x32_bf16 v[6:9], v[240:243], v[232:235], v[6:9]
	v_mfma_f32_16x16x32_bf16 v[2:5], v[248:251], v[232:235], v[2:5]
	s_setprio 0
	s_add_i32 s0, s0, 2
	s_add_u32 s10, s10, 0x100
	s_addc_u32 s11, s11, 0
	s_cmpk_lt_u32 s0, 0x54
	s_barrier
	s_cbranch_scc1 .LBB0_761
	s_add_i32 s1, s1, 0x1e000
	s_add_u32 s0, s8, 0x162b80
	s_addc_u32 s1, s9, 0
	v_readfirstlane_b32 s8, v161
	v_lshl_add_u64 v[158:159], s[0:1], 0, v[0:1]
	s_mov_b32 m0, s8
	v_lshl_add_u64 v[130:131], s[0:1], 0, v[130:131]
	v_readfirstlane_b32 s0, v162
	ds_read_b128 v[132:135], v148
	ds_read_b128 v[136:139], v148 offset:1024
	ds_read_b128 v[150:153], v148 offset:2048
	ds_read_b128 v[154:157], v148 offset:3072
	ds_read_b128 v[164:167], v147
	ds_read_b128 v[168:171], v147 offset:1024
	ds_read_b128 v[172:175], v147 offset:2048
	ds_read_b128 v[176:179], v147 offset:3072
	ds_read_b128 v[180:183], v147 offset:4096
	ds_read_b128 v[184:187], v147 offset:5120
	ds_read_b128 v[188:191], v147 offset:6144
	ds_read_b128 v[192:195], v147 offset:7168
	global_load_lds_dwordx4 v[158:159], off
	s_mov_b32 m0, s0
	s_nop 0
	global_load_lds_dwordx4 v[130:131], off
	s_barrier
	s_waitcnt lgkmcnt(0)
	s_setprio 1
	s_waitcnt lgkmcnt(0)
	v_mfma_f32_16x16x32_bf16 v[122:125], v[150:153], v[164:167], v[122:125]
	v_mfma_f32_16x16x32_bf16 v[118:121], v[132:135], v[172:175], v[118:121]
	v_mfma_f32_16x16x32_bf16 v[114:117], v[150:153], v[172:175], v[114:117]
	v_mfma_f32_16x16x32_bf16 v[102:105], v[132:135], v[188:191], v[102:105]
	v_mfma_f32_16x16x32_bf16 v[98:101], v[150:153], v[188:191], v[98:101]
	v_mfma_f32_16x16x32_bf16 v[126:129], v[132:135], v[164:167], v[126:129]
	v_mfma_f32_16x16x32_bf16 v[122:125], v[154:157], v[168:171], v[122:125]
	v_mfma_f32_16x16x32_bf16 v[118:121], v[136:139], v[176:179], v[118:121]
	v_mfma_f32_16x16x32_bf16 v[114:117], v[154:157], v[176:179], v[114:117]
	v_mfma_f32_16x16x32_bf16 v[110:113], v[132:135], v[180:183], v[110:113]
	v_mfma_f32_16x16x32_bf16 v[106:109], v[150:153], v[180:183], v[106:109]
	v_mfma_f32_16x16x32_bf16 v[102:105], v[136:139], v[192:195], v[102:105]
	v_mfma_f32_16x16x32_bf16 v[98:101], v[154:157], v[192:195], v[98:101]
	v_mfma_f32_16x16x32_bf16 v[126:129], v[136:139], v[168:171], v[126:129]
	v_mfma_f32_16x16x32_bf16 v[158:161], v[136:139], v[184:187], v[110:113]
	v_mfma_f32_16x16x32_bf16 v[196:199], v[154:157], v[184:187], v[106:109]
	s_setprio 0
	s_barrier
	ds_read_b128 v[106:109], v148 offset:16384
	ds_read_b128 v[110:113], v148 offset:17408
	ds_read_b128 v[200:203], v148 offset:18432
	ds_read_b128 v[222:225], v148 offset:19456
	s_barrier
	s_waitcnt lgkmcnt(0)
	s_setprio 1
	s_waitcnt lgkmcnt(3)
	v_mfma_f32_16x16x32_bf16 v[86:89], v[106:109], v[172:175], v[86:89]
	s_waitcnt lgkmcnt(1)
	v_mfma_f32_16x16x32_bf16 v[82:85], v[200:203], v[172:175], v[82:85]
	v_mfma_f32_16x16x32_bf16 v[70:73], v[106:109], v[188:191], v[70:73]
	v_mfma_f32_16x16x32_bf16 v[66:69], v[200:203], v[188:191], v[66:69]
	v_mfma_f32_16x16x32_bf16 v[94:97], v[106:109], v[164:167], v[94:97]
	v_mfma_f32_16x16x32_bf16 v[90:93], v[200:203], v[164:167], v[90:93]
	v_mfma_f32_16x16x32_bf16 v[86:89], v[110:113], v[176:179], v[86:89]
	s_waitcnt lgkmcnt(0)
	v_mfma_f32_16x16x32_bf16 v[82:85], v[222:225], v[176:179], v[82:85]
	v_mfma_f32_16x16x32_bf16 v[78:81], v[106:109], v[180:183], v[78:81]
	v_mfma_f32_16x16x32_bf16 v[74:77], v[200:203], v[180:183], v[74:77]
	v_mfma_f32_16x16x32_bf16 v[70:73], v[110:113], v[192:195], v[70:73]
	v_mfma_f32_16x16x32_bf16 v[66:69], v[222:225], v[192:195], v[66:69]
	v_mfma_f32_16x16x32_bf16 v[232:235], v[110:113], v[168:171], v[94:97]
	v_mfma_f32_16x16x32_bf16 v[162:165], v[222:225], v[168:171], v[90:93]
	v_mfma_f32_16x16x32_bf16 v[166:169], v[110:113], v[184:187], v[78:81]
	v_mfma_f32_16x16x32_bf16 v[170:173], v[222:225], v[184:187], v[74:77]
	s_setprio 0
	s_barrier
	s_nop 0
	ds_read_b128 v[74:77], v147 offset:16384
	ds_read_b128 v[78:81], v147 offset:17408
	ds_read_b128 v[90:93], v147 offset:18432
	ds_read_b128 v[94:97], v147 offset:19456
	ds_read_b128 v[174:177], v147 offset:20480
	ds_read_b128 v[178:181], v147 offset:21504
	ds_read_b128 v[182:185], v147 offset:22528
	ds_read_b128 v[186:189], v147 offset:23552
	s_waitcnt vmcnt(4)
	s_barrier
	s_waitcnt lgkmcnt(0)
	s_setprio 1
	s_waitcnt lgkmcnt(7)
	v_mfma_f32_16x16x32_bf16 v[62:65], v[132:135], v[74:77], v[62:65]
	v_mfma_f32_16x16x32_bf16 v[58:61], v[150:153], v[74:77], v[58:61]
	s_waitcnt lgkmcnt(5)
	v_mfma_f32_16x16x32_bf16 v[54:57], v[132:135], v[90:93], v[54:57]
	v_mfma_f32_16x16x32_bf16 v[50:53], v[150:153], v[90:93], v[50:53]
	s_waitcnt lgkmcnt(1)
	v_mfma_f32_16x16x32_bf16 v[38:41], v[132:135], v[182:185], v[38:41]
	v_mfma_f32_16x16x32_bf16 v[34:37], v[150:153], v[182:185], v[34:37]
	v_mfma_f32_16x16x32_bf16 v[62:65], v[136:139], v[78:81], v[62:65]
	v_mfma_f32_16x16x32_bf16 v[58:61], v[154:157], v[78:81], v[58:61]
	v_mfma_f32_16x16x32_bf16 v[54:57], v[136:139], v[94:97], v[54:57]
	v_mfma_f32_16x16x32_bf16 v[50:53], v[154:157], v[94:97], v[50:53]
	v_mfma_f32_16x16x32_bf16 v[46:49], v[132:135], v[174:177], v[46:49]
	v_mfma_f32_16x16x32_bf16 v[42:45], v[150:153], v[174:177], v[42:45]
	s_waitcnt lgkmcnt(0)
	v_mfma_f32_16x16x32_bf16 v[38:41], v[136:139], v[186:189], v[38:41]
	v_mfma_f32_16x16x32_bf16 v[34:37], v[154:157], v[186:189], v[34:37]
	v_mfma_f32_16x16x32_bf16 v[190:193], v[136:139], v[178:181], v[46:49]
	v_mfma_f32_16x16x32_bf16 v[236:239], v[154:157], v[178:181], v[42:45]
	s_setprio 0
	s_setprio 1
	v_mfma_f32_16x16x32_bf16 v[22:25], v[106:109], v[90:93], v[22:25]
	v_mfma_f32_16x16x32_bf16 v[18:21], v[200:203], v[90:93], v[18:21]
	v_mfma_f32_16x16x32_bf16 v[6:9], v[106:109], v[182:185], v[6:9]
	v_mfma_f32_16x16x32_bf16 v[2:5], v[200:203], v[182:185], v[2:5]
	v_mfma_f32_16x16x32_bf16 v[30:33], v[106:109], v[74:77], v[30:33]
	v_mfma_f32_16x16x32_bf16 v[26:29], v[200:203], v[74:77], v[26:29]
	v_mfma_f32_16x16x32_bf16 v[22:25], v[110:113], v[94:97], v[22:25]
	v_mfma_f32_16x16x32_bf16 v[18:21], v[222:225], v[94:97], v[18:21]
	v_mfma_f32_16x16x32_bf16 v[14:17], v[106:109], v[174:177], v[14:17]
	v_mfma_f32_16x16x32_bf16 v[10:13], v[200:203], v[174:177], v[10:13]
	v_mfma_f32_16x16x32_bf16 v[6:9], v[110:113], v[186:189], v[6:9]
	v_mfma_f32_16x16x32_bf16 v[2:5], v[222:225], v[186:189], v[2:5]
	v_mfma_f32_16x16x32_bf16 v[134:137], v[110:113], v[78:81], v[30:33]
	v_mfma_f32_16x16x32_bf16 v[150:153], v[222:225], v[78:81], v[26:29]
	v_mfma_f32_16x16x32_bf16 v[154:157], v[110:113], v[178:181], v[14:17]
	v_mfma_f32_16x16x32_bf16 v[174:177], v[222:225], v[178:181], v[10:13]
	s_setprio 0
	s_barrier
	s_nop 0
	ds_read_b128 v[10:13], v148 offset:32768
	ds_read_b128 v[14:17], v148 offset:33792
	ds_read_b128 v[178:181], v148 offset:34816
	ds_read_b128 v[182:185], v148 offset:35840
	ds_read_b128 v[26:29], v147 offset:32768
	ds_read_b128 v[30:33], v147 offset:33792
	ds_read_b128 v[42:45], v147 offset:34816
	ds_read_b128 v[46:49], v147 offset:35840
	ds_read_b128 v[186:189], v147 offset:36864
	ds_read_b128 v[200:203], v147 offset:37888
	ds_read_b128 v[222:225], v147 offset:38912
	ds_read_b128 v[240:243], v147 offset:39936
	s_waitcnt vmcnt(2)
	s_barrier
	s_waitcnt lgkmcnt(0)
	s_setprio 1
	s_waitcnt lgkmcnt(7)
	v_mfma_f32_16x16x32_bf16 v[74:77], v[10:13], v[26:29], v[126:129]
	s_waitcnt lgkmcnt(6)
	v_mfma_f32_16x16x32_bf16 v[130:133], v[14:17], v[30:33], v[74:77]
	v_mfma_f32_16x16x32_bf16 v[74:77], v[178:181], v[26:29], v[122:125]
	v_mfma_f32_16x16x32_bf16 v[122:125], v[182:185], v[30:33], v[74:77]
	s_waitcnt lgkmcnt(5)
	v_mfma_f32_16x16x32_bf16 v[74:77], v[10:13], v[42:45], v[118:121]
	s_waitcnt lgkmcnt(4)
	v_mfma_f32_16x16x32_bf16 v[110:113], v[14:17], v[46:49], v[74:77]
	v_mfma_f32_16x16x32_bf16 v[74:77], v[178:181], v[42:45], v[114:117]
	v_mfma_f32_16x16x32_bf16 v[106:109], v[182:185], v[46:49], v[74:77]
	s_waitcnt lgkmcnt(3)
	v_mfma_f32_16x16x32_bf16 v[74:77], v[10:13], v[186:189], v[158:161]
	s_waitcnt lgkmcnt(2)
	v_mfma_f32_16x16x32_bf16 v[94:97], v[14:17], v[200:203], v[74:77]
	v_mfma_f32_16x16x32_bf16 v[74:77], v[178:181], v[186:189], v[196:199]
	v_mfma_f32_16x16x32_bf16 v[90:93], v[182:185], v[200:203], v[74:77]
	s_waitcnt lgkmcnt(1)
	v_mfma_f32_16x16x32_bf16 v[74:77], v[10:13], v[222:225], v[102:105]
	s_waitcnt lgkmcnt(0)
	v_mfma_f32_16x16x32_bf16 v[78:81], v[14:17], v[240:243], v[74:77]
	v_mfma_f32_16x16x32_bf16 v[74:77], v[178:181], v[222:225], v[98:101]
	v_mfma_f32_16x16x32_bf16 v[74:77], v[182:185], v[240:243], v[74:77]
	s_setprio 0
	s_barrier
	ds_read_b128 v[126:129], v148 offset:49152
	ds_read_b128 v[158:161], v148 offset:50176
	ds_read_b128 v[194:197], v148 offset:51200
	ds_read_b128 v[244:247], v148 offset:52224
	s_waitcnt vmcnt(0)
	s_barrier
	s_waitcnt lgkmcnt(0)
	s_setprio 1
	s_waitcnt lgkmcnt(3)
	v_mfma_f32_16x16x32_bf16 v[98:101], v[126:129], v[26:29], v[232:235]
	s_waitcnt lgkmcnt(1)
	v_mfma_f32_16x16x32_bf16 v[26:29], v[194:197], v[26:29], v[162:165]
	s_waitcnt lgkmcnt(0)
	v_mfma_f32_16x16x32_bf16 v[114:117], v[244:247], v[30:33], v[26:29]
	v_mfma_f32_16x16x32_bf16 v[26:29], v[126:129], v[42:45], v[86:89]
	v_mfma_f32_16x16x32_bf16 v[102:105], v[158:161], v[46:49], v[26:29]
	v_mfma_f32_16x16x32_bf16 v[26:29], v[194:197], v[42:45], v[82:85]
	v_mfma_f32_16x16x32_bf16 v[118:121], v[158:161], v[30:33], v[98:101]
	v_mfma_f32_16x16x32_bf16 v[98:101], v[244:247], v[46:49], v[26:29]
	v_mfma_f32_16x16x32_bf16 v[26:29], v[126:129], v[186:189], v[166:169]
	v_mfma_f32_16x16x32_bf16 v[86:89], v[158:161], v[200:203], v[26:29]
	v_mfma_f32_16x16x32_bf16 v[26:29], v[194:197], v[186:189], v[170:173]
	v_mfma_f32_16x16x32_bf16 v[82:85], v[244:247], v[200:203], v[26:29]
	v_mfma_f32_16x16x32_bf16 v[26:29], v[126:129], v[222:225], v[70:73]
	v_mfma_f32_16x16x32_bf16 v[70:73], v[158:161], v[240:243], v[26:29]
	v_mfma_f32_16x16x32_bf16 v[26:29], v[194:197], v[222:225], v[66:69]
	v_mfma_f32_16x16x32_bf16 v[66:69], v[244:247], v[240:243], v[26:29]
	s_setprio 0
	s_barrier
	ds_read_b128 v[162:165], v147 offset:49152
	ds_read_b128 v[166:169], v147 offset:50176
	ds_read_b128 v[170:173], v147 offset:51200
	ds_read_b128 v[186:189], v147 offset:52224
	ds_read_b128 v[198:201], v147 offset:53248
	ds_read_b128 v[202:205], v147 offset:54272
	ds_read_b128 v[222:225], v147 offset:55296
	ds_read_b128 v[146:149], v147 offset:56320
	s_barrier
	s_waitcnt lgkmcnt(0)
	s_setprio 1
	s_waitcnt lgkmcnt(7)
	v_mfma_f32_16x16x32_bf16 v[26:29], v[10:13], v[162:165], v[62:65]
	s_waitcnt lgkmcnt(6)
	v_mfma_f32_16x16x32_bf16 v[62:65], v[14:17], v[166:169], v[26:29]
	v_mfma_f32_16x16x32_bf16 v[26:29], v[178:181], v[162:165], v[58:61]
	v_mfma_f32_16x16x32_bf16 v[58:61], v[182:185], v[166:169], v[26:29]
	s_waitcnt lgkmcnt(5)
	v_mfma_f32_16x16x32_bf16 v[26:29], v[10:13], v[170:173], v[54:57]
	s_waitcnt lgkmcnt(4)
	v_mfma_f32_16x16x32_bf16 v[46:49], v[14:17], v[186:189], v[26:29]
	v_mfma_f32_16x16x32_bf16 v[26:29], v[178:181], v[170:173], v[50:53]
	v_mfma_f32_16x16x32_bf16 v[42:45], v[182:185], v[186:189], v[26:29]
	s_waitcnt lgkmcnt(3)
	v_mfma_f32_16x16x32_bf16 v[26:29], v[10:13], v[198:201], v[190:193]
	s_waitcnt lgkmcnt(1)
	v_mfma_f32_16x16x32_bf16 v[10:13], v[10:13], v[222:225], v[38:41]
	v_mfma_f32_16x16x32_bf16 v[30:33], v[14:17], v[202:205], v[26:29]
	v_mfma_f32_16x16x32_bf16 v[26:29], v[178:181], v[198:201], v[236:239]
	s_waitcnt lgkmcnt(0)
	v_mfma_f32_16x16x32_bf16 v[14:17], v[14:17], v[146:149], v[10:13]
	v_mfma_f32_16x16x32_bf16 v[10:13], v[178:181], v[222:225], v[34:37]
	v_mfma_f32_16x16x32_bf16 v[26:29], v[182:185], v[202:205], v[26:29]
	v_mfma_f32_16x16x32_bf16 v[10:13], v[182:185], v[146:149], v[10:13]
	s_setprio 0
	s_setprio 1
	v_mfma_f32_16x16x32_bf16 v[34:37], v[126:129], v[162:165], v[134:137]
	v_mfma_f32_16x16x32_bf16 v[54:57], v[158:161], v[166:169], v[34:37]
	v_mfma_f32_16x16x32_bf16 v[34:37], v[194:197], v[162:165], v[150:153]
	v_mfma_f32_16x16x32_bf16 v[18:21], v[194:197], v[170:173], v[18:21]
	v_mfma_f32_16x16x32_bf16 v[50:53], v[244:247], v[166:169], v[34:37]
	v_mfma_f32_16x16x32_bf16 v[22:25], v[126:129], v[170:173], v[22:25]
	v_mfma_f32_16x16x32_bf16 v[34:37], v[244:247], v[186:189], v[18:21]
	v_mfma_f32_16x16x32_bf16 v[18:21], v[126:129], v[198:201], v[154:157]
	v_mfma_f32_16x16x32_bf16 v[38:41], v[158:161], v[186:189], v[22:25]
	v_mfma_f32_16x16x32_bf16 v[22:25], v[158:161], v[202:205], v[18:21]
	v_mfma_f32_16x16x32_bf16 v[18:21], v[194:197], v[198:201], v[174:177]
	v_mfma_f32_16x16x32_bf16 v[6:9], v[126:129], v[222:225], v[6:9]
	v_mfma_f32_16x16x32_bf16 v[2:5], v[194:197], v[222:225], v[2:5]
	v_mfma_f32_16x16x32_bf16 v[18:21], v[244:247], v[202:205], v[18:21]
	v_mfma_f32_16x16x32_bf16 v[6:9], v[158:161], v[146:149], v[6:9]
	v_mfma_f32_16x16x32_bf16 v[2:5], v[244:247], v[146:149], v[2:5]
	s_setprio 0
	s_movk_i32 s0, 0x100
	v_cmp_gt_u32_e32 vcc, s0, v140
	s_barrier
	s_and_saveexec_b64 s[0:1], vcc
	s_cbranch_execz .LBB0_764
	s_barrier
